# nt (streaming) hint on the read-once f32 weight loads of the conversion items and adaLN rows
# baseline (speedup 1.0000x reference)
; #define LAS __attribute__((address_space(3)))
; __device__ __forceinline__ void transpose_item(const float* W, int N, bf16_t* WT, int ldw, int drow0, int dk0, LAS float* scr, int k0, int n0, int lane) {
; #pragma unroll 8
;     for (int i = 0; i < 32; ++i) { const int kk = 2 * i + (lane >> 5); scr[kk * 33 + (lane & 31)] = W[(size_t)(k0 + kk) * N + n0 + (lane & 31)]; }
.LBB0_41:
	s_lshl_b32 s15, s12, 1
	s_lshl_b32 s16, s9, 1
	v_or_b32_e32 v30, s15, v1
	v_or_b32_e32 v41, s16, v32
	s_add_i32 s17, s15, 4
	s_add_i32 s18, s16, 4
	s_add_i32 s19, s15, 8
	s_add_i32 s20, s16, 8
	s_add_i32 s21, s15, 12
	s_add_i32 s22, s16, 12
	s_add_i32 s23, s15, 16
	s_add_i32 s26, s16, 16
	s_add_i32 s27, s15, 20
	s_add_i32 s34, s16, 20
	s_add_i32 s35, s15, 24
	s_add_i32 s40, s16, 24
	s_add_i32 s15, s15, 28
	s_add_i32 s16, s16, 28
	v_add_u32_e32 v6, s8, v41
	v_or_b32_e32 v48, s17, v1
	v_or_b32_e32 v49, s18, v32
	v_or_b32_e32 v50, s19, v1
	v_or_b32_e32 v51, s20, v32
	v_or_b32_e32 v52, s21, v1
	v_or_b32_e32 v53, s22, v32
	v_or_b32_e32 v54, s23, v1
	v_or_b32_e32 v55, s26, v32
	v_or_b32_e32 v56, s27, v1
	v_or_b32_e32 v57, s34, v32
	v_or_b32_e32 v71, s35, v1
	v_or_b32_e32 v76, s40, v32
	v_or_b32_e32 v77, s15, v1
	v_or_b32_e32 v78, s16, v32
	v_add_u32_e32 v4, s13, v30
	v_ashrrev_i32_e32 v7, 31, v6
	v_add_u32_e32 v8, s13, v48
	v_add_u32_e32 v10, s8, v49
	v_add_u32_e32 v12, s13, v50
	v_add_u32_e32 v14, s8, v51
	v_add_u32_e32 v16, s13, v52
	v_add_u32_e32 v18, s8, v53
	v_add_u32_e32 v20, s13, v54
	v_add_u32_e32 v22, s8, v55
	v_add_u32_e32 v24, s13, v56
	v_add_u32_e32 v26, s8, v57
	v_add_u32_e32 v28, s13, v71
	v_add_u32_e32 v42, s8, v76
	v_add_u32_e32 v44, s13, v77
	v_add_u32_e32 v46, s8, v78
	v_ashrrev_i32_e32 v5, 31, v4
	v_lshlrev_b64 v[6:7], 12, v[6:7]
	v_ashrrev_i32_e32 v11, 31, v10
	v_ashrrev_i32_e32 v9, 31, v8
	v_ashrrev_i32_e32 v15, 31, v14
	v_ashrrev_i32_e32 v13, 31, v12
	v_ashrrev_i32_e32 v19, 31, v18
	v_ashrrev_i32_e32 v17, 31, v16
	v_ashrrev_i32_e32 v23, 31, v22
	v_ashrrev_i32_e32 v21, 31, v20
	v_ashrrev_i32_e32 v27, 31, v26
	v_ashrrev_i32_e32 v25, 31, v24
	v_ashrrev_i32_e32 v43, 31, v42
	v_ashrrev_i32_e32 v29, 31, v28
	v_ashrrev_i32_e32 v47, 31, v46
	v_ashrrev_i32_e32 v45, 31, v44
	v_lshlrev_b64 v[4:5], 12, v[4:5]
	v_lshl_add_u64 v[6:7], v[2:3], 0, v[6:7]
	v_lshlrev_b64 v[8:9], 12, v[8:9]
	v_lshlrev_b64 v[10:11], 12, v[10:11]
	v_lshlrev_b64 v[12:13], 12, v[12:13]
	v_lshlrev_b64 v[14:15], 12, v[14:15]
	v_lshlrev_b64 v[16:17], 12, v[16:17]
	v_lshlrev_b64 v[18:19], 12, v[18:19]
	v_lshlrev_b64 v[20:21], 12, v[20:21]
	v_lshlrev_b64 v[22:23], 12, v[22:23]
	v_lshlrev_b64 v[24:25], 12, v[24:25]
	v_lshlrev_b64 v[26:27], 12, v[26:27]
	v_lshlrev_b64 v[28:29], 12, v[28:29]
	v_lshlrev_b64 v[42:43], 12, v[42:43]
	v_lshlrev_b64 v[44:45], 12, v[44:45]
	v_lshlrev_b64 v[46:47], 12, v[46:47]
	v_lshl_add_u64 v[4:5], v[2:3], 0, v[4:5]
	v_lshl_add_u64 v[10:11], v[2:3], 0, v[10:11]
	v_lshl_add_u64 v[8:9], v[2:3], 0, v[8:9]
	v_lshl_add_u64 v[14:15], v[2:3], 0, v[14:15]
	v_lshl_add_u64 v[12:13], v[2:3], 0, v[12:13]
	v_lshl_add_u64 v[18:19], v[2:3], 0, v[18:19]
	v_lshl_add_u64 v[16:17], v[2:3], 0, v[16:17]
	v_lshl_add_u64 v[22:23], v[2:3], 0, v[22:23]
	v_lshl_add_u64 v[20:21], v[2:3], 0, v[20:21]
	v_lshl_add_u64 v[26:27], v[2:3], 0, v[26:27]
	v_lshl_add_u64 v[24:25], v[2:3], 0, v[24:25]
	v_lshl_add_u64 v[42:43], v[2:3], 0, v[42:43]
	v_lshl_add_u64 v[28:29], v[2:3], 0, v[28:29]
	v_lshl_add_u64 v[46:47], v[2:3], 0, v[46:47]
	v_lshl_add_u64 v[44:45], v[2:3], 0, v[44:45]
	global_load_dword v79, v[6:7], off nt
	global_load_dword v80, v[4:5], off nt
	global_load_dword v81, v[10:11], off nt
	global_load_dword v82, v[8:9], off nt
	global_load_dword v83, v[14:15], off nt
	global_load_dword v84, v[12:13], off nt
	global_load_dword v85, v[18:19], off nt
	global_load_dword v86, v[16:17], off nt
	global_load_dword v87, v[22:23], off nt
	global_load_dword v88, v[20:21], off nt
	global_load_dword v89, v[26:27], off nt
	global_load_dword v90, v[24:25], off nt
	global_load_dword v91, v[42:43], off nt
	global_load_dword v92, v[28:29], off nt
	global_load_dword v93, v[46:47], off nt
	global_load_dword v94, v[44:45], off nt
	s_add_i32 s9, s9, 16
	s_add_i32 s12, s12, 16
	s_add_i32 s14, s14, -16
	s_lshl_b32 s15, s12, 1
	s_lshl_b32 s16, s9, 1
	v_or_b32_e32 v170, s15, v1
	v_or_b32_e32 v181, s16, v32
	s_add_i32 s17, s15, 4
	s_add_i32 s18, s16, 4
	s_add_i32 s19, s15, 8
	s_add_i32 s20, s16, 8
	s_add_i32 s21, s15, 12
	s_add_i32 s22, s16, 12
	s_add_i32 s23, s15, 16
	s_add_i32 s26, s16, 16
	s_add_i32 s27, s15, 20
	s_add_i32 s34, s16, 20
	s_add_i32 s35, s15, 24
	s_add_i32 s40, s16, 24
	s_add_i32 s15, s15, 28
	s_add_i32 s16, s16, 28
	v_add_u32_e32 v146, s8, v181
	v_or_b32_e32 v188, s17, v1
	v_or_b32_e32 v189, s18, v32
	v_or_b32_e32 v190, s19, v1
	v_or_b32_e32 v191, s20, v32
	v_or_b32_e32 v192, s21, v1
	v_or_b32_e32 v193, s22, v32
	v_or_b32_e32 v194, s23, v1
	v_or_b32_e32 v195, s26, v32
	v_or_b32_e32 v196, s27, v1
	v_or_b32_e32 v197, s34, v32
	v_or_b32_e32 v211, s35, v1
	v_or_b32_e32 v216, s40, v32
	v_or_b32_e32 v217, s15, v1
	v_or_b32_e32 v218, s16, v32
	v_add_u32_e32 v144, s13, v170
	v_ashrrev_i32_e32 v147, 31, v146
	v_add_u32_e32 v148, s13, v188
	v_add_u32_e32 v150, s8, v189
	v_add_u32_e32 v152, s13, v190
	v_add_u32_e32 v154, s8, v191
	v_add_u32_e32 v156, s13, v192
	v_add_u32_e32 v158, s8, v193
	v_add_u32_e32 v160, s13, v194
	v_add_u32_e32 v162, s8, v195
	v_add_u32_e32 v164, s13, v196
	v_add_u32_e32 v166, s8, v197
	v_add_u32_e32 v168, s13, v211
	v_add_u32_e32 v182, s8, v216
	v_add_u32_e32 v184, s13, v217
	v_add_u32_e32 v186, s8, v218
	v_ashrrev_i32_e32 v145, 31, v144
	v_lshlrev_b64 v[146:147], 12, v[146:147]
	v_ashrrev_i32_e32 v151, 31, v150
	v_ashrrev_i32_e32 v149, 31, v148
	v_ashrrev_i32_e32 v155, 31, v154
	v_ashrrev_i32_e32 v153, 31, v152
	v_ashrrev_i32_e32 v159, 31, v158
	v_ashrrev_i32_e32 v157, 31, v156
	v_ashrrev_i32_e32 v163, 31, v162
	v_ashrrev_i32_e32 v161, 31, v160
	v_ashrrev_i32_e32 v167, 31, v166
	v_ashrrev_i32_e32 v165, 31, v164
	v_ashrrev_i32_e32 v183, 31, v182
; #define LDS_WAIT() asm volatile("s_waitcnt lgkmcnt(0)" ::: "memory")
; __device__ __forceinline__ void transpose_item(const float* W, int N, bf16_t* WT, int ldw, int drow0, int dk0, LAS float* scr, int k0, int n0, int lane) {
; #pragma unroll 8
;     for (int i = 0; i < 32; ++i) { const int kk = 2 * i + (lane >> 5); scr[kk * 33 + (lane & 31)] = W[(size_t)(k0 + kk) * N + n0 + (lane & 31)]; }
;     LDS_WAIT(); asm volatile("" ::: "memory");
	v_ashrrev_i32_e32 v169, 31, v168
	v_ashrrev_i32_e32 v187, 31, v186
	v_ashrrev_i32_e32 v185, 31, v184
	v_lshlrev_b64 v[144:145], 12, v[144:145]
	v_lshl_add_u64 v[146:147], v[2:3], 0, v[146:147]
	v_lshlrev_b64 v[148:149], 12, v[148:149]
	v_lshlrev_b64 v[150:151], 12, v[150:151]
	v_lshlrev_b64 v[152:153], 12, v[152:153]
	v_lshlrev_b64 v[154:155], 12, v[154:155]
	v_lshlrev_b64 v[156:157], 12, v[156:157]
	v_lshlrev_b64 v[158:159], 12, v[158:159]
	v_lshlrev_b64 v[160:161], 12, v[160:161]
	v_lshlrev_b64 v[162:163], 12, v[162:163]
	v_lshlrev_b64 v[164:165], 12, v[164:165]
	v_lshlrev_b64 v[166:167], 12, v[166:167]
	v_lshlrev_b64 v[168:169], 12, v[168:169]
	v_lshlrev_b64 v[182:183], 12, v[182:183]
	v_lshlrev_b64 v[184:185], 12, v[184:185]
	v_lshlrev_b64 v[186:187], 12, v[186:187]
	v_lshl_add_u64 v[144:145], v[2:3], 0, v[144:145]
	v_lshl_add_u64 v[150:151], v[2:3], 0, v[150:151]
	v_lshl_add_u64 v[148:149], v[2:3], 0, v[148:149]
	v_lshl_add_u64 v[154:155], v[2:3], 0, v[154:155]
	v_lshl_add_u64 v[152:153], v[2:3], 0, v[152:153]
	v_lshl_add_u64 v[158:159], v[2:3], 0, v[158:159]
	v_lshl_add_u64 v[156:157], v[2:3], 0, v[156:157]
	v_lshl_add_u64 v[162:163], v[2:3], 0, v[162:163]
	v_lshl_add_u64 v[160:161], v[2:3], 0, v[160:161]
	v_lshl_add_u64 v[166:167], v[2:3], 0, v[166:167]
	v_lshl_add_u64 v[164:165], v[2:3], 0, v[164:165]
	v_lshl_add_u64 v[182:183], v[2:3], 0, v[182:183]
	v_lshl_add_u64 v[168:169], v[2:3], 0, v[168:169]
	v_lshl_add_u64 v[186:187], v[2:3], 0, v[186:187]
	v_lshl_add_u64 v[184:185], v[2:3], 0, v[184:185]
	global_load_dword v219, v[146:147], off nt
	global_load_dword v220, v[144:145], off nt
	global_load_dword v221, v[150:151], off nt
	global_load_dword v222, v[148:149], off nt
	global_load_dword v223, v[154:155], off nt
	global_load_dword v224, v[152:153], off nt
	global_load_dword v225, v[158:159], off nt
	global_load_dword v226, v[156:157], off nt
	global_load_dword v227, v[162:163], off nt
	global_load_dword v228, v[160:161], off nt
	global_load_dword v229, v[166:167], off nt
	global_load_dword v230, v[164:165], off nt
	global_load_dword v231, v[182:183], off nt
	global_load_dword v232, v[168:169], off nt
	global_load_dword v233, v[186:187], off nt
	global_load_dword v234, v[184:185], off nt
	v_mad_u64_u32 v[4:5], s[16:17], v41, s67, v[36:37]
	v_mad_u64_u32 v[6:7], s[16:17], v30, s67, v[36:37]
	v_mad_u64_u32 v[8:9], s[16:17], v49, s67, v[36:37]
	v_mad_u64_u32 v[10:11], s[16:17], v48, s67, v[36:37]
	v_mad_u64_u32 v[12:13], s[16:17], v51, s67, v[36:37]
	v_mad_u64_u32 v[14:15], s[16:17], v50, s67, v[36:37]
	v_mad_u64_u32 v[16:17], s[16:17], v53, s67, v[36:37]
	v_mad_u64_u32 v[18:19], s[16:17], v52, s67, v[36:37]
	v_mad_u64_u32 v[20:21], s[16:17], v55, s67, v[36:37]
	v_mad_u64_u32 v[22:23], s[16:17], v54, s67, v[36:37]
	v_mad_u64_u32 v[24:25], s[16:17], v57, s67, v[36:37]
	v_mad_u64_u32 v[26:27], s[16:17], v56, s67, v[36:37]
	v_mad_u64_u32 v[28:29], s[16:17], v76, s67, v[36:37]
	v_mad_u64_u32 v[42:43], s[16:17], v71, s67, v[36:37]
	v_mad_u64_u32 v[44:45], s[16:17], v78, s67, v[36:37]
	v_mad_u64_u32 v[46:47], s[16:17], v77, s67, v[36:37]
	s_waitcnt vmcnt(31)
	ds_write_b32 v4, v79
	s_waitcnt vmcnt(30)
	ds_write_b32 v6, v80
	s_waitcnt vmcnt(29)
	ds_write_b32 v8, v81
	s_waitcnt vmcnt(28)
	ds_write_b32 v10, v82
	s_waitcnt vmcnt(27)
	ds_write_b32 v12, v83
	s_waitcnt vmcnt(26)
	ds_write_b32 v14, v84
	s_waitcnt vmcnt(25)
	ds_write_b32 v16, v85
	s_waitcnt vmcnt(24)
	ds_write_b32 v18, v86
	s_waitcnt vmcnt(23)
	ds_write_b32 v20, v87
	s_waitcnt vmcnt(22)
	ds_write_b32 v22, v88
	s_waitcnt vmcnt(21)
	ds_write_b32 v24, v89
	s_waitcnt vmcnt(20)
	ds_write_b32 v26, v90
	s_waitcnt vmcnt(19)
	ds_write_b32 v28, v91
	s_waitcnt vmcnt(18)
	ds_write_b32 v42, v92
	s_waitcnt vmcnt(17)
	ds_write_b32 v44, v93
	s_waitcnt vmcnt(16)
; #define LAS __attribute__((address_space(3)))
; __device__ __forceinline__ unsigned cvtpk_s(float lo, float hi) { f32x2_t v = {lo, hi}; bf16x2_t b = __builtin_convertvector(v, bf16x2_t); return __builtin_bit_cast(unsigned, b); }
; #define LDS_WAIT() asm volatile("s_waitcnt lgkmcnt(0)" ::: "memory")
; __device__ __forceinline__ void transpose_item(const float* W, int N, bf16_t* WT, int ldw, int drow0, int dk0, LAS float* scr, int k0, int n0, int lane) {
;     ...
;     for (int i = 0; i < 32; ++i) { const int kk = 2 * i + (lane >> 5); scr[kk * 33 + (lane & 31)] = W[(size_t)(k0 + kk) * N + n0 + (lane & 31)]; }
;     LDS_WAIT(); asm volatile("" ::: "memory");
;     const int c = lane & 7;
; #pragma unroll
;     for (int j = 0; j < 4; ++j) { const int n = (lane >> 3) + 8 * j; const LAS float* s = scr + (8 * c) * 33 + n;
;         u32x4 o; o.x = cvtpk_s(s[0 * 33], s[1 * 33]); o.y = cvtpk_s(s[2 * 33], s[3 * 33]); o.z = cvtpk_s(s[4 * 33], s[5 * 33]); o.w = cvtpk_s(s[6 * 33], s[7 * 33]);
;         *(u32x4*)(WT + (size_t)(drow0 + n) * ldw + dk0 + k0 + 8 * c) = o; }
;     LDS_WAIT(); asm volatile("" ::: "memory");
	ds_write_b32 v46, v94
	s_add_i32 s9, s9, 16
	s_add_i32 s12, s12, 16
	s_add_i32 s14, s14, -16
	v_mad_u64_u32 v[144:145], s[16:17], v181, s67, v[36:37]
	v_mad_u64_u32 v[146:147], s[16:17], v170, s67, v[36:37]
	v_mad_u64_u32 v[148:149], s[16:17], v189, s67, v[36:37]
	v_mad_u64_u32 v[150:151], s[16:17], v188, s67, v[36:37]
	v_mad_u64_u32 v[152:153], s[16:17], v191, s67, v[36:37]
	v_mad_u64_u32 v[154:155], s[16:17], v190, s67, v[36:37]
	v_mad_u64_u32 v[156:157], s[16:17], v193, s67, v[36:37]
	v_mad_u64_u32 v[158:159], s[16:17], v192, s67, v[36:37]
	v_mad_u64_u32 v[160:161], s[16:17], v195, s67, v[36:37]
	v_mad_u64_u32 v[162:163], s[16:17], v194, s67, v[36:37]
	v_mad_u64_u32 v[164:165], s[16:17], v197, s67, v[36:37]
	v_mad_u64_u32 v[166:167], s[16:17], v196, s67, v[36:37]
	v_mad_u64_u32 v[168:169], s[16:17], v216, s67, v[36:37]
	v_mad_u64_u32 v[182:183], s[16:17], v211, s67, v[36:37]
	v_mad_u64_u32 v[184:185], s[16:17], v218, s67, v[36:37]
	v_mad_u64_u32 v[186:187], s[16:17], v217, s67, v[36:37]
	s_waitcnt vmcnt(15)
	ds_write_b32 v144, v219
	s_waitcnt vmcnt(14)
	ds_write_b32 v146, v220
	s_waitcnt vmcnt(13)
	ds_write_b32 v148, v221
	s_waitcnt vmcnt(12)
	ds_write_b32 v150, v222
	s_waitcnt vmcnt(11)
	ds_write_b32 v152, v223
	s_waitcnt vmcnt(10)
	ds_write_b32 v154, v224
	s_waitcnt vmcnt(9)
	ds_write_b32 v156, v225
	s_waitcnt vmcnt(8)
	ds_write_b32 v158, v226
	s_waitcnt vmcnt(7)
	ds_write_b32 v160, v227
	s_waitcnt vmcnt(6)
	ds_write_b32 v162, v228
	s_waitcnt vmcnt(5)
	ds_write_b32 v164, v229
	s_waitcnt vmcnt(4)
	ds_write_b32 v166, v230
	s_waitcnt vmcnt(3)
	ds_write_b32 v168, v231
	s_waitcnt vmcnt(2)
	ds_write_b32 v182, v232
	s_waitcnt vmcnt(1)
	ds_write_b32 v184, v233
	s_waitcnt vmcnt(0)
	ds_write_b32 v186, v234
	s_mov_b32 s9, s41
	s_waitcnt lgkmcnt(0)
	s_lshl_b64 s[8:9], s[8:9], 1
	s_add_u32 s8, s4, s8
	s_addc_u32 s9, s5, s9
	v_lshlrev_b32_e32 v30, 1, v38
	ds_read2_b32 v[6:7], v60 offset0:33 offset1:41
	ds_read2_b32 v[8:9], v60 offset1:8
	ds_read2_b32 v[10:11], v60 offset0:66 offset1:74
	ds_read2_b32 v[12:13], v60 offset0:99 offset1:107
	ds_read2_b32 v[14:15], v60 offset0:132 offset1:140
	ds_read2_b32 v[16:17], v60 offset0:165 offset1:173
	ds_read2_b32 v[18:19], v60 offset0:198 offset1:206
	ds_read2_b32 v[20:21], v60 offset0:231 offset1:239
	v_lshl_add_u64 v[2:3], s[8:9], 0, v[30:31]
	v_lshl_add_u64 v[22:23], v[2:3], 0, s[46:47]
	s_waitcnt lgkmcnt(6)
	v_cvt_pk_bf16_f32 v2, v8, v6
	v_or_b32_e32 v6, s11, v59
	v_mul_u32_u24_e32 v6, 0xb00, v6
	v_lshlrev_b32_e32 v30, 1, v6
	s_waitcnt lgkmcnt(4)
	v_cvt_pk_bf16_f32 v3, v10, v12
	s_waitcnt lgkmcnt(2)
	v_cvt_pk_bf16_f32 v4, v14, v16
	s_waitcnt lgkmcnt(0)
	v_cvt_pk_bf16_f32 v5, v18, v20
	v_lshl_add_u64 v[24:25], v[22:23], 0, v[30:31]
	v_or_b32_e32 v6, s11, v61
	global_store_dwordx4 v[24:25], v[2:5], off
	v_mul_u32_u24_e32 v6, 0xb00, v6
	v_lshlrev_b32_e32 v30, 1, v6
	v_cvt_pk_bf16_f32 v2, v9, v7
	v_cvt_pk_bf16_f32 v3, v11, v13
	v_cvt_pk_bf16_f32 v4, v15, v17
	v_cvt_pk_bf16_f32 v5, v19, v21
	ds_read2_b32 v[8:9], v60 offset0:16 offset1:24
	ds_read2_b32 v[10:11], v60 offset0:49 offset1:57
	ds_read2_b32 v[12:13], v60 offset0:82 offset1:90
	ds_read2_b32 v[14:15], v60 offset0:115 offset1:123
	ds_read2_b32 v[16:17], v60 offset0:148 offset1:156
	ds_read2_b32 v[18:19], v60 offset0:181 offset1:189
	ds_read2_b32 v[20:21], v60 offset0:214 offset1:222
	ds_read2_b32 v[24:25], v60 offset0:247 offset1:255
	v_lshl_add_u64 v[6:7], v[22:23], 0, v[30:31]
	global_store_dwordx4 v[6:7], v[2:5], off
	v_or_b32_e32 v6, s11, v62
	v_mul_u32_u24_e32 v6, 0xb00, v6
	v_lshlrev_b32_e32 v30, 1, v6
	s_waitcnt lgkmcnt(6)
	v_cvt_pk_bf16_f32 v2, v8, v10
	s_waitcnt lgkmcnt(4)
	v_cvt_pk_bf16_f32 v3, v12, v14
	s_waitcnt lgkmcnt(2)
	v_cvt_pk_bf16_f32 v4, v16, v18
	s_waitcnt lgkmcnt(0)
	v_cvt_pk_bf16_f32 v5, v20, v24
	v_lshl_add_u64 v[6:7], v[22:23], 0, v[30:31]
	global_store_dwordx4 v[6:7], v[2:5], off
	v_or_b32_e32 v6, s11, v63
	v_mul_u32_u24_e32 v6, 0xb00, v6
	v_lshlrev_b32_e32 v30, 1, v6
	v_cvt_pk_bf16_f32 v2, v9, v11
	v_cvt_pk_bf16_f32 v3, v13, v15
	v_cvt_pk_bf16_f32 v4, v17, v19
	v_cvt_pk_bf16_f32 v5, v21, v25
	v_lshl_add_u64 v[6:7], v[22:23], 0, v[30:31]
	global_store_dwordx4 v[6:7], v[2:5], off
	s_waitcnt lgkmcnt(0)

; #define LAS __attribute__((address_space(3)))
; __device__ __forceinline__ void transpose_item(const float* W, int N, bf16_t* WT, int ldw, int drow0, int dk0, LAS float* scr, int k0, int n0, int lane) {
; #pragma unroll 8
;     for (int i = 0; i < 32; ++i) { const int kk = 2 * i + (lane >> 5); scr[kk * 33 + (lane & 31)] = W[(size_t)(k0 + kk) * N + n0 + (lane & 31)]; }
.LBB0_50:
	s_lshl_b32 s16, s14, 1
	s_lshl_b32 s17, s8, 1
	v_or_b32_e32 v30, s16, v1
	v_or_b32_e32 v41, s17, v32
	s_add_i32 s18, s16, 4
	s_add_i32 s19, s17, 4
	s_add_i32 s20, s16, 8
	s_add_i32 s21, s17, 8
	s_add_i32 s22, s16, 12
	s_add_i32 s23, s17, 12
	s_add_i32 s26, s16, 16
	s_add_i32 s27, s17, 16
	s_add_i32 s34, s16, 20
	s_add_i32 s35, s17, 20
	s_add_i32 s40, s16, 24
	s_add_i32 s64, s17, 24
	s_add_i32 s16, s16, 28
	s_add_i32 s17, s17, 28
	v_add_u32_e32 v4, s12, v41
	v_or_b32_e32 v48, s18, v1
	v_or_b32_e32 v49, s19, v32
	v_or_b32_e32 v50, s20, v1
	v_or_b32_e32 v51, s21, v32
	v_or_b32_e32 v52, s22, v1
	v_or_b32_e32 v53, s23, v32
	v_or_b32_e32 v54, s26, v1
	v_or_b32_e32 v55, s27, v32
	v_or_b32_e32 v56, s34, v1
	v_or_b32_e32 v57, s35, v32
	v_or_b32_e32 v71, s40, v1
	v_or_b32_e32 v76, s64, v32
	v_or_b32_e32 v77, s16, v1
	v_or_b32_e32 v78, s17, v32
	v_add_u32_e32 v6, s13, v30
	v_mad_u64_u32 v[4:5], s[16:17], v4, s81, v[2:3]
	v_add_u32_e32 v10, s13, v48
	v_add_u32_e32 v8, s12, v49
	v_add_u32_e32 v14, s13, v50
	v_add_u32_e32 v12, s12, v51
	v_add_u32_e32 v18, s13, v52
	v_add_u32_e32 v16, s12, v53
	v_add_u32_e32 v22, s13, v54
	v_add_u32_e32 v20, s12, v55
	v_add_u32_e32 v26, s13, v56
	v_add_u32_e32 v24, s12, v57
	v_add_u32_e32 v42, s13, v71
	v_add_u32_e32 v28, s12, v76
	v_add_u32_e32 v46, s13, v77
	v_add_u32_e32 v44, s12, v78
	v_mad_u64_u32 v[6:7], s[16:17], v6, s81, v[2:3]
	v_mad_u64_u32 v[8:9], s[16:17], v8, s81, v[2:3]
	v_mad_u64_u32 v[10:11], s[16:17], v10, s81, v[2:3]
	v_mad_u64_u32 v[12:13], s[16:17], v12, s81, v[2:3]
	v_mad_u64_u32 v[14:15], s[16:17], v14, s81, v[2:3]
	v_mad_u64_u32 v[16:17], s[16:17], v16, s81, v[2:3]
	v_mad_u64_u32 v[18:19], s[16:17], v18, s81, v[2:3]
	v_mad_u64_u32 v[20:21], s[16:17], v20, s81, v[2:3]
	v_mad_u64_u32 v[22:23], s[16:17], v22, s81, v[2:3]
	v_mad_u64_u32 v[24:25], s[16:17], v24, s81, v[2:3]
	v_mad_u64_u32 v[26:27], s[16:17], v26, s81, v[2:3]
	v_mad_u64_u32 v[28:29], s[16:17], v28, s81, v[2:3]
	v_mad_u64_u32 v[42:43], s[16:17], v42, s81, v[2:3]
	v_mad_u64_u32 v[44:45], s[16:17], v44, s81, v[2:3]
	v_mad_u64_u32 v[46:47], s[16:17], v46, s81, v[2:3]
	global_load_dword v79, v[4:5], off nt
	global_load_dword v80, v[6:7], off nt
	global_load_dword v81, v[8:9], off nt
	global_load_dword v82, v[10:11], off nt
	global_load_dword v83, v[12:13], off nt
	global_load_dword v84, v[14:15], off nt
	global_load_dword v85, v[16:17], off nt
	global_load_dword v86, v[18:19], off nt
	global_load_dword v87, v[20:21], off nt
	global_load_dword v88, v[22:23], off nt
	global_load_dword v89, v[24:25], off nt
	global_load_dword v90, v[26:27], off nt
	global_load_dword v91, v[28:29], off nt
	global_load_dword v92, v[42:43], off nt
	global_load_dword v93, v[44:45], off nt
	global_load_dword v94, v[46:47], off nt
	s_add_i32 s8, s8, 16
	s_add_i32 s14, s14, 16
	s_add_i32 s15, s15, -16
	s_lshl_b32 s16, s14, 1
	s_lshl_b32 s17, s8, 1
	v_or_b32_e32 v170, s16, v1
	v_or_b32_e32 v181, s17, v32
	s_add_i32 s18, s16, 4
	s_add_i32 s19, s17, 4
	s_add_i32 s20, s16, 8
	s_add_i32 s21, s17, 8
	s_add_i32 s22, s16, 12
	s_add_i32 s23, s17, 12
	s_add_i32 s26, s16, 16
	s_add_i32 s27, s17, 16
	s_add_i32 s34, s16, 20
	s_add_i32 s35, s17, 20
	s_add_i32 s40, s16, 24
	s_add_i32 s64, s17, 24
	s_add_i32 s16, s16, 28
	s_add_i32 s17, s17, 28
	v_add_u32_e32 v144, s12, v181
	v_or_b32_e32 v188, s18, v1
	v_or_b32_e32 v189, s19, v32
	v_or_b32_e32 v190, s20, v1
	v_or_b32_e32 v191, s21, v32
	v_or_b32_e32 v192, s22, v1
	v_or_b32_e32 v193, s23, v32
	v_or_b32_e32 v194, s26, v1
	v_or_b32_e32 v195, s27, v32
	v_or_b32_e32 v196, s34, v1
	v_or_b32_e32 v197, s35, v32
	v_or_b32_e32 v211, s40, v1
	v_or_b32_e32 v216, s64, v32
	v_or_b32_e32 v217, s16, v1
	v_or_b32_e32 v218, s17, v32
	v_add_u32_e32 v146, s13, v170
	v_mad_u64_u32 v[144:145], s[16:17], v144, s81, v[2:3]
	v_add_u32_e32 v150, s13, v188
	v_add_u32_e32 v148, s12, v189
	v_add_u32_e32 v154, s13, v190
	v_add_u32_e32 v152, s12, v191
	v_add_u32_e32 v158, s13, v192
	v_add_u32_e32 v156, s12, v193
	v_add_u32_e32 v162, s13, v194
	v_add_u32_e32 v160, s12, v195
	v_add_u32_e32 v166, s13, v196
	v_add_u32_e32 v164, s12, v197
	v_add_u32_e32 v182, s13, v211
	v_add_u32_e32 v168, s12, v216
	v_add_u32_e32 v186, s13, v217
	v_add_u32_e32 v184, s12, v218
	v_mad_u64_u32 v[146:147], s[16:17], v146, s81, v[2:3]
	v_mad_u64_u32 v[148:149], s[16:17], v148, s81, v[2:3]
	v_mad_u64_u32 v[150:151], s[16:17], v150, s81, v[2:3]
	v_mad_u64_u32 v[152:153], s[16:17], v152, s81, v[2:3]
	v_mad_u64_u32 v[154:155], s[16:17], v154, s81, v[2:3]
	v_mad_u64_u32 v[156:157], s[16:17], v156, s81, v[2:3]
	v_mad_u64_u32 v[158:159], s[16:17], v158, s81, v[2:3]
	v_mad_u64_u32 v[160:161], s[16:17], v160, s81, v[2:3]
	v_mad_u64_u32 v[162:163], s[16:17], v162, s81, v[2:3]
	v_mad_u64_u32 v[164:165], s[16:17], v164, s81, v[2:3]
	v_mad_u64_u32 v[166:167], s[16:17], v166, s81, v[2:3]
	v_mad_u64_u32 v[168:169], s[16:17], v168, s81, v[2:3]
	v_mad_u64_u32 v[182:183], s[16:17], v182, s81, v[2:3]
	v_mad_u64_u32 v[184:185], s[16:17], v184, s81, v[2:3]
	v_mad_u64_u32 v[186:187], s[16:17], v186, s81, v[2:3]
	global_load_dword v219, v[144:145], off nt
	global_load_dword v220, v[146:147], off nt
	global_load_dword v221, v[148:149], off nt
	global_load_dword v222, v[150:151], off nt
	global_load_dword v223, v[152:153], off nt
	global_load_dword v224, v[154:155], off nt
	global_load_dword v225, v[156:157], off nt
	global_load_dword v226, v[158:159], off nt
	global_load_dword v227, v[160:161], off nt
	global_load_dword v228, v[162:163], off nt
	global_load_dword v229, v[164:165], off nt
	global_load_dword v230, v[166:167], off nt
	global_load_dword v231, v[168:169], off nt
	global_load_dword v232, v[182:183], off nt
	global_load_dword v233, v[184:185], off nt
	global_load_dword v234, v[186:187], off nt
	v_mad_u64_u32 v[4:5], s[16:17], v41, s67, v[36:37]
	v_mad_u64_u32 v[6:7], s[16:17], v30, s67, v[36:37]
	v_mad_u64_u32 v[8:9], s[16:17], v49, s67, v[36:37]
	v_mad_u64_u32 v[10:11], s[16:17], v48, s67, v[36:37]
	v_mad_u64_u32 v[12:13], s[16:17], v51, s67, v[36:37]
	v_mad_u64_u32 v[14:15], s[16:17], v50, s67, v[36:37]
	v_mad_u64_u32 v[16:17], s[16:17], v53, s67, v[36:37]
	v_mad_u64_u32 v[18:19], s[16:17], v52, s67, v[36:37]
	v_mad_u64_u32 v[20:21], s[16:17], v55, s67, v[36:37]
	v_mad_u64_u32 v[22:23], s[16:17], v54, s67, v[36:37]
	v_mad_u64_u32 v[24:25], s[16:17], v57, s67, v[36:37]
	v_mad_u64_u32 v[26:27], s[16:17], v56, s67, v[36:37]
	v_mad_u64_u32 v[28:29], s[16:17], v76, s67, v[36:37]
	v_mad_u64_u32 v[42:43], s[16:17], v71, s67, v[36:37]
	v_mad_u64_u32 v[44:45], s[16:17], v78, s67, v[36:37]
	v_mad_u64_u32 v[46:47], s[16:17], v77, s67, v[36:37]
	s_waitcnt vmcnt(31)
; #define LAS __attribute__((address_space(3)))
; __device__ __forceinline__ unsigned cvtpk_s(float lo, float hi) { f32x2_t v = {lo, hi}; bf16x2_t b = __builtin_convertvector(v, bf16x2_t); return __builtin_bit_cast(unsigned, b); }
; #define LDS_WAIT() asm volatile("s_waitcnt lgkmcnt(0)" ::: "memory")
; __device__ __forceinline__ void transpose_item(const float* W, int N, bf16_t* WT, int ldw, int drow0, int dk0, LAS float* scr, int k0, int n0, int lane) {
;     ...
;     for (int i = 0; i < 32; ++i) { const int kk = 2 * i + (lane >> 5); scr[kk * 33 + (lane & 31)] = W[(size_t)(k0 + kk) * N + n0 + (lane & 31)]; }
;     LDS_WAIT(); asm volatile("" ::: "memory");
;     const int c = lane & 7;
; #pragma unroll
;     for (int j = 0; j < 4; ++j) { const int n = (lane >> 3) + 8 * j; const LAS float* s = scr + (8 * c) * 33 + n;
;         u32x4 o; o.x = cvtpk_s(s[0 * 33], s[1 * 33]); o.y = cvtpk_s(s[2 * 33], s[3 * 33]); o.z = cvtpk_s(s[4 * 33], s[5 * 33]); o.w = cvtpk_s(s[6 * 33], s[7 * 33]);
;         *(u32x4*)(WT + (size_t)(drow0 + n) * ldw + dk0 + k0 + 8 * c) = o; }
;     LDS_WAIT(); asm volatile("" ::: "memory");
	ds_write_b32 v4, v79
	s_waitcnt vmcnt(30)
	ds_write_b32 v6, v80
	s_waitcnt vmcnt(29)
	ds_write_b32 v8, v81
	s_waitcnt vmcnt(28)
	ds_write_b32 v10, v82
	s_waitcnt vmcnt(27)
	ds_write_b32 v12, v83
	s_waitcnt vmcnt(26)
	ds_write_b32 v14, v84
	s_waitcnt vmcnt(25)
	ds_write_b32 v16, v85
	s_waitcnt vmcnt(24)
	ds_write_b32 v18, v86
	s_waitcnt vmcnt(23)
	ds_write_b32 v20, v87
	s_waitcnt vmcnt(22)
	ds_write_b32 v22, v88
	s_waitcnt vmcnt(21)
	ds_write_b32 v24, v89
	s_waitcnt vmcnt(20)
	ds_write_b32 v26, v90
	s_waitcnt vmcnt(19)
	ds_write_b32 v28, v91
	s_waitcnt vmcnt(18)
	ds_write_b32 v42, v92
	s_waitcnt vmcnt(17)
	ds_write_b32 v44, v93
	s_waitcnt vmcnt(16)
	ds_write_b32 v46, v94
	s_add_i32 s8, s8, 16
	s_add_i32 s14, s14, 16
	s_add_i32 s15, s15, -16
	v_mad_u64_u32 v[144:145], s[16:17], v181, s67, v[36:37]
	v_mad_u64_u32 v[146:147], s[16:17], v170, s67, v[36:37]
	v_mad_u64_u32 v[148:149], s[16:17], v189, s67, v[36:37]
	v_mad_u64_u32 v[150:151], s[16:17], v188, s67, v[36:37]
	v_mad_u64_u32 v[152:153], s[16:17], v191, s67, v[36:37]
	v_mad_u64_u32 v[154:155], s[16:17], v190, s67, v[36:37]
	v_mad_u64_u32 v[156:157], s[16:17], v193, s67, v[36:37]
	v_mad_u64_u32 v[158:159], s[16:17], v192, s67, v[36:37]
	v_mad_u64_u32 v[160:161], s[16:17], v195, s67, v[36:37]
	v_mad_u64_u32 v[162:163], s[16:17], v194, s67, v[36:37]
	v_mad_u64_u32 v[164:165], s[16:17], v197, s67, v[36:37]
	v_mad_u64_u32 v[166:167], s[16:17], v196, s67, v[36:37]
	v_mad_u64_u32 v[168:169], s[16:17], v216, s67, v[36:37]
	v_mad_u64_u32 v[182:183], s[16:17], v211, s67, v[36:37]
	v_mad_u64_u32 v[184:185], s[16:17], v218, s67, v[36:37]
	v_mad_u64_u32 v[186:187], s[16:17], v217, s67, v[36:37]
	s_waitcnt vmcnt(15)
	ds_write_b32 v144, v219
	s_waitcnt vmcnt(14)
	ds_write_b32 v146, v220
	s_waitcnt vmcnt(13)
	ds_write_b32 v148, v221
	s_waitcnt vmcnt(12)
	ds_write_b32 v150, v222
	s_waitcnt vmcnt(11)
	ds_write_b32 v152, v223
	s_waitcnt vmcnt(10)
	ds_write_b32 v154, v224
	s_waitcnt vmcnt(9)
	ds_write_b32 v156, v225
	s_waitcnt vmcnt(8)
	ds_write_b32 v158, v226
	s_waitcnt vmcnt(7)
	ds_write_b32 v160, v227
	s_waitcnt vmcnt(6)
	ds_write_b32 v162, v228
	s_waitcnt vmcnt(5)
	ds_write_b32 v164, v229
	s_waitcnt vmcnt(4)
	ds_write_b32 v166, v230
	s_waitcnt vmcnt(3)
	ds_write_b32 v168, v231
	s_waitcnt vmcnt(2)
	ds_write_b32 v182, v232
	s_waitcnt vmcnt(1)
	ds_write_b32 v184, v233
	s_waitcnt vmcnt(0)
	ds_write_b32 v186, v234
	s_waitcnt lgkmcnt(0)
	s_and_b32 s8, 0xffff, s9
	s_lshl_b32 s8, s8, 1
	ds_read2_b32 v[6:7], v60 offset0:33 offset1:41
	ds_read2_b32 v[8:9], v60 offset1:8
	ds_read2_b32 v[10:11], v60 offset0:66 offset1:74
	ds_read2_b32 v[12:13], v60 offset0:99 offset1:107
	ds_read2_b32 v[14:15], v60 offset0:132 offset1:140
	ds_read2_b32 v[16:17], v60 offset0:165 offset1:173
	ds_read2_b32 v[18:19], v60 offset0:198 offset1:206
	ds_read2_b32 v[20:21], v60 offset0:231 offset1:239
	s_add_u32 s8, s4, s8
	s_addc_u32 s9, s5, 0
	v_lshlrev_b32_e32 v30, 1, v38
	v_lshl_add_u64 v[2:3], s[8:9], 0, v[30:31]
	v_add_u32_e32 v30, s11, v59
	v_lshl_add_u64 v[22:23], v[2:3], 0, s[48:49]
	v_lshlrev_b64 v[24:25], 11, v[30:31]
	s_waitcnt lgkmcnt(6)
	v_cvt_pk_bf16_f32 v2, v8, v6
	s_waitcnt lgkmcnt(4)
	v_cvt_pk_bf16_f32 v3, v10, v12
	s_waitcnt lgkmcnt(2)
	v_cvt_pk_bf16_f32 v4, v14, v16
	s_waitcnt lgkmcnt(0)
	v_cvt_pk_bf16_f32 v5, v18, v20
	v_lshl_add_u64 v[24:25], v[22:23], 0, v[24:25]
	global_store_dwordx4 v[24:25], v[2:5], off
	v_add_u32_e32 v30, s11, v61
	s_nop 0
	v_cvt_pk_bf16_f32 v2, v9, v7
	v_cvt_pk_bf16_f32 v3, v11, v13
	v_cvt_pk_bf16_f32 v4, v15, v17
	v_cvt_pk_bf16_f32 v5, v19, v21
	ds_read2_b32 v[8:9], v60 offset0:49 offset1:57
	ds_read2_b32 v[10:11], v60 offset0:16 offset1:24
	ds_read2_b32 v[12:13], v60 offset0:82 offset1:90
	ds_read2_b32 v[14:15], v60 offset0:115 offset1:123
	ds_read2_b32 v[16:17], v60 offset0:148 offset1:156
	ds_read2_b32 v[18:19], v60 offset0:181 offset1:189
	ds_read2_b32 v[20:21], v60 offset0:214 offset1:222
	ds_read2_b32 v[24:25], v60 offset0:247 offset1:255
	v_lshlrev_b64 v[6:7], 11, v[30:31]
	v_lshl_add_u64 v[6:7], v[22:23], 0, v[6:7]
	v_add_u32_e32 v30, s11, v62
	global_store_dwordx4 v[6:7], v[2:5], off
	v_lshlrev_b64 v[6:7], 11, v[30:31]
	v_lshl_add_u64 v[6:7], v[22:23], 0, v[6:7]
	s_waitcnt lgkmcnt(6)
	v_cvt_pk_bf16_f32 v2, v10, v8
	s_waitcnt lgkmcnt(4)
	v_cvt_pk_bf16_f32 v3, v12, v14
	s_waitcnt lgkmcnt(2)
	v_cvt_pk_bf16_f32 v4, v16, v18
	s_waitcnt lgkmcnt(0)
	v_cvt_pk_bf16_f32 v5, v20, v24
	v_add_u32_e32 v30, s11, v63
	global_store_dwordx4 v[6:7], v[2:5], off
	v_lshlrev_b64 v[6:7], 11, v[30:31]
	v_lshl_add_u64 v[6:7], v[22:23], 0, v[6:7]
	v_cvt_pk_bf16_f32 v2, v11, v9
	v_cvt_pk_bf16_f32 v3, v13, v15
	v_cvt_pk_bf16_f32 v4, v17, v19
	v_cvt_pk_bf16_f32 v5, v21, v25
	global_store_dwordx4 v[6:7], v[2:5], off
	s_waitcnt lgkmcnt(0)

; #define LAS __attribute__((address_space(3)))
; __device__ __forceinline__ void transpose_item(const float* W, int N, bf16_t* WT, int ldw, int drow0, int dk0, LAS float* scr, int k0, int n0, int lane) {
; #pragma unroll 8
;     for (int i = 0; i < 32; ++i) { const int kk = 2 * i + (lane >> 5); scr[kk * 33 + (lane & 31)] = W[(size_t)(k0 + kk) * N + n0 + (lane & 31)]; }
.LBB0_55:
	s_lshl_b32 s15, s12, 1
	s_lshl_b32 s16, s9, 1
	v_or_b32_e32 v30, s15, v1
	v_or_b32_e32 v41, s16, v32
	s_add_i32 s17, s15, 4
	s_add_i32 s18, s16, 4
	s_add_i32 s19, s15, 8
	s_add_i32 s20, s16, 8
	s_add_i32 s21, s15, 12
	s_add_i32 s22, s16, 12
	s_add_i32 s23, s15, 16
	s_add_i32 s26, s16, 16
	s_add_i32 s27, s15, 20
	s_add_i32 s34, s16, 20
	s_add_i32 s35, s15, 24
	s_add_i32 s40, s16, 24
	s_add_i32 s15, s15, 28
	s_add_i32 s16, s16, 28
	v_add_u32_e32 v6, s8, v41
	v_or_b32_e32 v48, s17, v1
	v_or_b32_e32 v49, s18, v32
	v_or_b32_e32 v50, s19, v1
	v_or_b32_e32 v51, s20, v32
	v_or_b32_e32 v52, s21, v1
	v_or_b32_e32 v53, s22, v32
	v_or_b32_e32 v54, s23, v1
	v_or_b32_e32 v55, s26, v32
	v_or_b32_e32 v56, s27, v1
	v_or_b32_e32 v57, s34, v32
	v_or_b32_e32 v71, s35, v1
	v_or_b32_e32 v76, s40, v32
	v_or_b32_e32 v77, s15, v1
	v_or_b32_e32 v78, s16, v32
	v_add_u32_e32 v4, s13, v30
	v_ashrrev_i32_e32 v7, 31, v6
	v_add_u32_e32 v8, s13, v48
	v_add_u32_e32 v10, s8, v49
	v_add_u32_e32 v12, s13, v50
	v_add_u32_e32 v14, s8, v51
	v_add_u32_e32 v16, s13, v52
	v_add_u32_e32 v18, s8, v53
	v_add_u32_e32 v20, s13, v54
	v_add_u32_e32 v22, s8, v55
	v_add_u32_e32 v24, s13, v56
	v_add_u32_e32 v26, s8, v57
	v_add_u32_e32 v28, s13, v71
	v_add_u32_e32 v42, s8, v76
	v_add_u32_e32 v44, s13, v77
	v_add_u32_e32 v46, s8, v78
	v_ashrrev_i32_e32 v5, 31, v4
	v_lshlrev_b64 v[6:7], 12, v[6:7]
	v_ashrrev_i32_e32 v11, 31, v10
	v_ashrrev_i32_e32 v9, 31, v8
	v_ashrrev_i32_e32 v15, 31, v14
	v_ashrrev_i32_e32 v13, 31, v12
	v_ashrrev_i32_e32 v19, 31, v18
	v_ashrrev_i32_e32 v17, 31, v16
	v_ashrrev_i32_e32 v23, 31, v22
	v_ashrrev_i32_e32 v21, 31, v20
	v_ashrrev_i32_e32 v27, 31, v26
	v_ashrrev_i32_e32 v25, 31, v24
	v_ashrrev_i32_e32 v43, 31, v42
	v_ashrrev_i32_e32 v29, 31, v28
	v_ashrrev_i32_e32 v47, 31, v46
	v_ashrrev_i32_e32 v45, 31, v44
	v_lshlrev_b64 v[4:5], 12, v[4:5]
	v_lshl_add_u64 v[6:7], v[2:3], 0, v[6:7]
	v_lshlrev_b64 v[8:9], 12, v[8:9]
	v_lshlrev_b64 v[10:11], 12, v[10:11]
	v_lshlrev_b64 v[12:13], 12, v[12:13]
	v_lshlrev_b64 v[14:15], 12, v[14:15]
	v_lshlrev_b64 v[16:17], 12, v[16:17]
	v_lshlrev_b64 v[18:19], 12, v[18:19]
	v_lshlrev_b64 v[20:21], 12, v[20:21]
	v_lshlrev_b64 v[22:23], 12, v[22:23]
	v_lshlrev_b64 v[24:25], 12, v[24:25]
	v_lshlrev_b64 v[26:27], 12, v[26:27]
	v_lshlrev_b64 v[28:29], 12, v[28:29]
	v_lshlrev_b64 v[42:43], 12, v[42:43]
	v_lshlrev_b64 v[44:45], 12, v[44:45]
	v_lshlrev_b64 v[46:47], 12, v[46:47]
	v_lshl_add_u64 v[4:5], v[2:3], 0, v[4:5]
	v_lshl_add_u64 v[10:11], v[2:3], 0, v[10:11]
	v_lshl_add_u64 v[8:9], v[2:3], 0, v[8:9]
	v_lshl_add_u64 v[14:15], v[2:3], 0, v[14:15]
	v_lshl_add_u64 v[12:13], v[2:3], 0, v[12:13]
	v_lshl_add_u64 v[18:19], v[2:3], 0, v[18:19]
	v_lshl_add_u64 v[16:17], v[2:3], 0, v[16:17]
	v_lshl_add_u64 v[22:23], v[2:3], 0, v[22:23]
	v_lshl_add_u64 v[20:21], v[2:3], 0, v[20:21]
	v_lshl_add_u64 v[26:27], v[2:3], 0, v[26:27]
	v_lshl_add_u64 v[24:25], v[2:3], 0, v[24:25]
	v_lshl_add_u64 v[42:43], v[2:3], 0, v[42:43]
	v_lshl_add_u64 v[28:29], v[2:3], 0, v[28:29]
	v_lshl_add_u64 v[46:47], v[2:3], 0, v[46:47]
	v_lshl_add_u64 v[44:45], v[2:3], 0, v[44:45]
	global_load_dword v79, v[6:7], off nt
	global_load_dword v80, v[4:5], off nt
	global_load_dword v81, v[10:11], off nt
	global_load_dword v82, v[8:9], off nt
	global_load_dword v83, v[14:15], off nt
	global_load_dword v84, v[12:13], off nt
	global_load_dword v85, v[18:19], off nt
	global_load_dword v86, v[16:17], off nt
	global_load_dword v87, v[22:23], off nt
	global_load_dword v88, v[20:21], off nt
	global_load_dword v89, v[26:27], off nt
	global_load_dword v90, v[24:25], off nt
	global_load_dword v91, v[42:43], off nt
	global_load_dword v92, v[28:29], off nt
	global_load_dword v93, v[46:47], off nt
	global_load_dword v94, v[44:45], off nt
	s_add_i32 s9, s9, 16
	s_add_i32 s12, s12, 16
	s_add_i32 s14, s14, -16
	s_lshl_b32 s15, s12, 1
	s_lshl_b32 s16, s9, 1
	v_or_b32_e32 v170, s15, v1
	v_or_b32_e32 v181, s16, v32
	s_add_i32 s17, s15, 4
	s_add_i32 s18, s16, 4
	s_add_i32 s19, s15, 8
	s_add_i32 s20, s16, 8
	s_add_i32 s21, s15, 12
	s_add_i32 s22, s16, 12
	s_add_i32 s23, s15, 16
	s_add_i32 s26, s16, 16
	s_add_i32 s27, s15, 20
	s_add_i32 s34, s16, 20
	s_add_i32 s35, s15, 24
	s_add_i32 s40, s16, 24
	s_add_i32 s15, s15, 28
	s_add_i32 s16, s16, 28
	v_add_u32_e32 v146, s8, v181
	v_or_b32_e32 v188, s17, v1
	v_or_b32_e32 v189, s18, v32
	v_or_b32_e32 v190, s19, v1
	v_or_b32_e32 v191, s20, v32
	v_or_b32_e32 v192, s21, v1
	v_or_b32_e32 v193, s22, v32
	v_or_b32_e32 v194, s23, v1
	v_or_b32_e32 v195, s26, v32
	v_or_b32_e32 v196, s27, v1
	v_or_b32_e32 v197, s34, v32
	v_or_b32_e32 v211, s35, v1
	v_or_b32_e32 v216, s40, v32
	v_or_b32_e32 v217, s15, v1
	v_or_b32_e32 v218, s16, v32
	v_add_u32_e32 v144, s13, v170
	v_ashrrev_i32_e32 v147, 31, v146
	v_add_u32_e32 v148, s13, v188
	v_add_u32_e32 v150, s8, v189
	v_add_u32_e32 v152, s13, v190
	v_add_u32_e32 v154, s8, v191
	v_add_u32_e32 v156, s13, v192
	v_add_u32_e32 v158, s8, v193
	v_add_u32_e32 v160, s13, v194
	v_add_u32_e32 v162, s8, v195
	v_add_u32_e32 v164, s13, v196
	v_add_u32_e32 v166, s8, v197
	v_add_u32_e32 v168, s13, v211
	v_add_u32_e32 v182, s8, v216
	v_add_u32_e32 v184, s13, v217
	v_add_u32_e32 v186, s8, v218
	v_ashrrev_i32_e32 v145, 31, v144
	v_lshlrev_b64 v[146:147], 12, v[146:147]
	v_ashrrev_i32_e32 v151, 31, v150
	v_ashrrev_i32_e32 v149, 31, v148
	v_ashrrev_i32_e32 v155, 31, v154
	v_ashrrev_i32_e32 v153, 31, v152
	v_ashrrev_i32_e32 v159, 31, v158
	v_ashrrev_i32_e32 v157, 31, v156
	v_ashrrev_i32_e32 v163, 31, v162
	v_ashrrev_i32_e32 v161, 31, v160
	v_ashrrev_i32_e32 v167, 31, v166
	v_ashrrev_i32_e32 v165, 31, v164
	v_ashrrev_i32_e32 v183, 31, v182
; #define LDS_WAIT() asm volatile("s_waitcnt lgkmcnt(0)" ::: "memory")
; __device__ __forceinline__ void transpose_item(const float* W, int N, bf16_t* WT, int ldw, int drow0, int dk0, LAS float* scr, int k0, int n0, int lane) {
; #pragma unroll 8
;     for (int i = 0; i < 32; ++i) { const int kk = 2 * i + (lane >> 5); scr[kk * 33 + (lane & 31)] = W[(size_t)(k0 + kk) * N + n0 + (lane & 31)]; }
;     LDS_WAIT(); asm volatile("" ::: "memory");
	v_ashrrev_i32_e32 v169, 31, v168
	v_ashrrev_i32_e32 v187, 31, v186
	v_ashrrev_i32_e32 v185, 31, v184
	v_lshlrev_b64 v[144:145], 12, v[144:145]
	v_lshl_add_u64 v[146:147], v[2:3], 0, v[146:147]
	v_lshlrev_b64 v[148:149], 12, v[148:149]
	v_lshlrev_b64 v[150:151], 12, v[150:151]
	v_lshlrev_b64 v[152:153], 12, v[152:153]
	v_lshlrev_b64 v[154:155], 12, v[154:155]
	v_lshlrev_b64 v[156:157], 12, v[156:157]
	v_lshlrev_b64 v[158:159], 12, v[158:159]
	v_lshlrev_b64 v[160:161], 12, v[160:161]
	v_lshlrev_b64 v[162:163], 12, v[162:163]
	v_lshlrev_b64 v[164:165], 12, v[164:165]
	v_lshlrev_b64 v[166:167], 12, v[166:167]
	v_lshlrev_b64 v[168:169], 12, v[168:169]
	v_lshlrev_b64 v[182:183], 12, v[182:183]
	v_lshlrev_b64 v[184:185], 12, v[184:185]
	v_lshlrev_b64 v[186:187], 12, v[186:187]
	v_lshl_add_u64 v[144:145], v[2:3], 0, v[144:145]
	v_lshl_add_u64 v[150:151], v[2:3], 0, v[150:151]
	v_lshl_add_u64 v[148:149], v[2:3], 0, v[148:149]
	v_lshl_add_u64 v[154:155], v[2:3], 0, v[154:155]
	v_lshl_add_u64 v[152:153], v[2:3], 0, v[152:153]
	v_lshl_add_u64 v[158:159], v[2:3], 0, v[158:159]
	v_lshl_add_u64 v[156:157], v[2:3], 0, v[156:157]
	v_lshl_add_u64 v[162:163], v[2:3], 0, v[162:163]
	v_lshl_add_u64 v[160:161], v[2:3], 0, v[160:161]
	v_lshl_add_u64 v[166:167], v[2:3], 0, v[166:167]
	v_lshl_add_u64 v[164:165], v[2:3], 0, v[164:165]
	v_lshl_add_u64 v[182:183], v[2:3], 0, v[182:183]
	v_lshl_add_u64 v[168:169], v[2:3], 0, v[168:169]
	v_lshl_add_u64 v[186:187], v[2:3], 0, v[186:187]
	v_lshl_add_u64 v[184:185], v[2:3], 0, v[184:185]
	global_load_dword v219, v[146:147], off nt
	global_load_dword v220, v[144:145], off nt
	global_load_dword v221, v[150:151], off nt
	global_load_dword v222, v[148:149], off nt
	global_load_dword v223, v[154:155], off nt
	global_load_dword v224, v[152:153], off nt
	global_load_dword v225, v[158:159], off nt
	global_load_dword v226, v[156:157], off nt
	global_load_dword v227, v[162:163], off nt
	global_load_dword v228, v[160:161], off nt
	global_load_dword v229, v[166:167], off nt
	global_load_dword v230, v[164:165], off nt
	global_load_dword v231, v[182:183], off nt
	global_load_dword v232, v[168:169], off nt
	global_load_dword v233, v[186:187], off nt
	global_load_dword v234, v[184:185], off nt
	v_mad_u64_u32 v[4:5], s[16:17], v41, s67, v[36:37]
	v_mad_u64_u32 v[6:7], s[16:17], v30, s67, v[36:37]
	v_mad_u64_u32 v[8:9], s[16:17], v49, s67, v[36:37]
	v_mad_u64_u32 v[10:11], s[16:17], v48, s67, v[36:37]
	v_mad_u64_u32 v[12:13], s[16:17], v51, s67, v[36:37]
	v_mad_u64_u32 v[14:15], s[16:17], v50, s67, v[36:37]
	v_mad_u64_u32 v[16:17], s[16:17], v53, s67, v[36:37]
	v_mad_u64_u32 v[18:19], s[16:17], v52, s67, v[36:37]
	v_mad_u64_u32 v[20:21], s[16:17], v55, s67, v[36:37]
	v_mad_u64_u32 v[22:23], s[16:17], v54, s67, v[36:37]
	v_mad_u64_u32 v[24:25], s[16:17], v57, s67, v[36:37]
	v_mad_u64_u32 v[26:27], s[16:17], v56, s67, v[36:37]
	v_mad_u64_u32 v[28:29], s[16:17], v76, s67, v[36:37]
	v_mad_u64_u32 v[42:43], s[16:17], v71, s67, v[36:37]
	v_mad_u64_u32 v[44:45], s[16:17], v78, s67, v[36:37]
	v_mad_u64_u32 v[46:47], s[16:17], v77, s67, v[36:37]
	s_waitcnt vmcnt(31)
	ds_write_b32 v4, v79
	s_waitcnt vmcnt(30)
	ds_write_b32 v6, v80
	s_waitcnt vmcnt(29)
	ds_write_b32 v8, v81
	s_waitcnt vmcnt(28)
	ds_write_b32 v10, v82
	s_waitcnt vmcnt(27)
	ds_write_b32 v12, v83
	s_waitcnt vmcnt(26)
	ds_write_b32 v14, v84
	s_waitcnt vmcnt(25)
	ds_write_b32 v16, v85
	s_waitcnt vmcnt(24)
	ds_write_b32 v18, v86
	s_waitcnt vmcnt(23)
	ds_write_b32 v20, v87
	s_waitcnt vmcnt(22)
	ds_write_b32 v22, v88
	s_waitcnt vmcnt(21)
	ds_write_b32 v24, v89
	s_waitcnt vmcnt(20)
	ds_write_b32 v26, v90
	s_waitcnt vmcnt(19)
	ds_write_b32 v28, v91
	s_waitcnt vmcnt(18)
	ds_write_b32 v42, v92
	s_waitcnt vmcnt(17)
	ds_write_b32 v44, v93
	s_waitcnt vmcnt(16)
; #define LAS __attribute__((address_space(3)))
; __device__ __forceinline__ unsigned cvtpk_s(float lo, float hi) { f32x2_t v = {lo, hi}; bf16x2_t b = __builtin_convertvector(v, bf16x2_t); return __builtin_bit_cast(unsigned, b); }
; #define LDS_WAIT() asm volatile("s_waitcnt lgkmcnt(0)" ::: "memory")
; __device__ __forceinline__ void transpose_item(const float* W, int N, bf16_t* WT, int ldw, int drow0, int dk0, LAS float* scr, int k0, int n0, int lane) {
;     ...
;     for (int i = 0; i < 32; ++i) { const int kk = 2 * i + (lane >> 5); scr[kk * 33 + (lane & 31)] = W[(size_t)(k0 + kk) * N + n0 + (lane & 31)]; }
;     LDS_WAIT(); asm volatile("" ::: "memory");
;     const int c = lane & 7;
; #pragma unroll
;     for (int j = 0; j < 4; ++j) { const int n = (lane >> 3) + 8 * j; const LAS float* s = scr + (8 * c) * 33 + n;
;         u32x4 o; o.x = cvtpk_s(s[0 * 33], s[1 * 33]); o.y = cvtpk_s(s[2 * 33], s[3 * 33]); o.z = cvtpk_s(s[4 * 33], s[5 * 33]); o.w = cvtpk_s(s[6 * 33], s[7 * 33]);
;         *(u32x4*)(WT + (size_t)(drow0 + n) * ldw + dk0 + k0 + 8 * c) = o; }
;     LDS_WAIT(); asm volatile("" ::: "memory");
	ds_write_b32 v46, v94
	s_add_i32 s9, s9, 16
	s_add_i32 s12, s12, 16
	s_add_i32 s14, s14, -16
	v_mad_u64_u32 v[144:145], s[16:17], v181, s67, v[36:37]
	v_mad_u64_u32 v[146:147], s[16:17], v170, s67, v[36:37]
	v_mad_u64_u32 v[148:149], s[16:17], v189, s67, v[36:37]
	v_mad_u64_u32 v[150:151], s[16:17], v188, s67, v[36:37]
	v_mad_u64_u32 v[152:153], s[16:17], v191, s67, v[36:37]
	v_mad_u64_u32 v[154:155], s[16:17], v190, s67, v[36:37]
	v_mad_u64_u32 v[156:157], s[16:17], v193, s67, v[36:37]
	v_mad_u64_u32 v[158:159], s[16:17], v192, s67, v[36:37]
	v_mad_u64_u32 v[160:161], s[16:17], v195, s67, v[36:37]
	v_mad_u64_u32 v[162:163], s[16:17], v194, s67, v[36:37]
	v_mad_u64_u32 v[164:165], s[16:17], v197, s67, v[36:37]
	v_mad_u64_u32 v[166:167], s[16:17], v196, s67, v[36:37]
	v_mad_u64_u32 v[168:169], s[16:17], v216, s67, v[36:37]
	v_mad_u64_u32 v[182:183], s[16:17], v211, s67, v[36:37]
	v_mad_u64_u32 v[184:185], s[16:17], v218, s67, v[36:37]
	v_mad_u64_u32 v[186:187], s[16:17], v217, s67, v[36:37]
	s_waitcnt vmcnt(15)
	ds_write_b32 v144, v219
	s_waitcnt vmcnt(14)
	ds_write_b32 v146, v220
	s_waitcnt vmcnt(13)
	ds_write_b32 v148, v221
	s_waitcnt vmcnt(12)
	ds_write_b32 v150, v222
	s_waitcnt vmcnt(11)
	ds_write_b32 v152, v223
	s_waitcnt vmcnt(10)
	ds_write_b32 v154, v224
	s_waitcnt vmcnt(9)
	ds_write_b32 v156, v225
	s_waitcnt vmcnt(8)
	ds_write_b32 v158, v226
	s_waitcnt vmcnt(7)
	ds_write_b32 v160, v227
	s_waitcnt vmcnt(6)
	ds_write_b32 v162, v228
	s_waitcnt vmcnt(5)
	ds_write_b32 v164, v229
	s_waitcnt vmcnt(4)
	ds_write_b32 v166, v230
	s_waitcnt vmcnt(3)
	ds_write_b32 v168, v231
	s_waitcnt vmcnt(2)
	ds_write_b32 v182, v232
	s_waitcnt vmcnt(1)
	ds_write_b32 v184, v233
	s_waitcnt vmcnt(0)
	ds_write_b32 v186, v234
	s_waitcnt lgkmcnt(0)
	s_mov_b32 s9, s41
	s_lshl_b64 s[8:9], s[8:9], 1
	s_add_u32 s8, s4, s8
	ds_read2_b32 v[6:7], v60 offset0:33 offset1:41
	ds_read2_b32 v[8:9], v60 offset1:8
	ds_read2_b32 v[10:11], v60 offset0:66 offset1:74
	ds_read2_b32 v[12:13], v60 offset0:99 offset1:107
	ds_read2_b32 v[14:15], v60 offset0:132 offset1:140
	ds_read2_b32 v[16:17], v60 offset0:165 offset1:173
	ds_read2_b32 v[18:19], v60 offset0:198 offset1:206
	ds_read2_b32 v[20:21], v60 offset0:231 offset1:239
	s_addc_u32 s9, s5, s9
	v_lshlrev_b32_e32 v30, 1, v38
	v_lshl_add_u64 v[2:3], s[8:9], 0, v[30:31]
	v_lshl_add_u64 v[22:23], v[2:3], 0, s[50:51]
	s_waitcnt lgkmcnt(6)
	v_cvt_pk_bf16_f32 v2, v8, v6
	v_or_b32_e32 v6, s11, v59
	v_lshlrev_b32_e32 v30, 11, v6
	s_waitcnt lgkmcnt(4)
	v_cvt_pk_bf16_f32 v3, v10, v12
	s_waitcnt lgkmcnt(2)
	v_cvt_pk_bf16_f32 v4, v14, v16
	s_waitcnt lgkmcnt(0)
	v_cvt_pk_bf16_f32 v5, v18, v20
	v_lshl_add_u64 v[24:25], v[22:23], 0, v[30:31]
	global_store_dwordx4 v[24:25], v[2:5], off
	v_or_b32_e32 v6, s11, v61
	v_lshlrev_b32_e32 v30, 11, v6
	v_cvt_pk_bf16_f32 v2, v9, v7
	v_cvt_pk_bf16_f32 v3, v11, v13
	v_cvt_pk_bf16_f32 v4, v15, v17
	v_cvt_pk_bf16_f32 v5, v19, v21
	ds_read2_b32 v[8:9], v60 offset0:49 offset1:57
	ds_read2_b32 v[10:11], v60 offset0:16 offset1:24
	ds_read2_b32 v[12:13], v60 offset0:82 offset1:90
	ds_read2_b32 v[14:15], v60 offset0:115 offset1:123
	ds_read2_b32 v[16:17], v60 offset0:148 offset1:156
	ds_read2_b32 v[18:19], v60 offset0:181 offset1:189
	ds_read2_b32 v[20:21], v60 offset0:214 offset1:222
	ds_read2_b32 v[24:25], v60 offset0:247 offset1:255
	v_lshl_add_u64 v[6:7], v[22:23], 0, v[30:31]
	global_store_dwordx4 v[6:7], v[2:5], off
	v_or_b32_e32 v6, s11, v62
	v_lshlrev_b32_e32 v30, 11, v6
	s_waitcnt lgkmcnt(6)
	v_cvt_pk_bf16_f32 v2, v10, v8
	s_waitcnt lgkmcnt(4)
	v_cvt_pk_bf16_f32 v3, v12, v14
	s_waitcnt lgkmcnt(2)
	v_cvt_pk_bf16_f32 v4, v16, v18
	s_waitcnt lgkmcnt(0)
	v_cvt_pk_bf16_f32 v5, v20, v24
	v_lshl_add_u64 v[6:7], v[22:23], 0, v[30:31]
	global_store_dwordx4 v[6:7], v[2:5], off
	v_or_b32_e32 v6, s11, v63
	v_lshlrev_b32_e32 v30, 11, v6
	v_cvt_pk_bf16_f32 v2, v11, v9
	v_cvt_pk_bf16_f32 v3, v13, v15
	v_cvt_pk_bf16_f32 v4, v17, v19
	v_cvt_pk_bf16_f32 v5, v21, v25
	v_lshl_add_u64 v[6:7], v[22:23], 0, v[30:31]
	global_store_dwordx4 v[6:7], v[2:5], off
	s_waitcnt lgkmcnt(0)

; #define LAS __attribute__((address_space(3)))
; __device__ __forceinline__ void transpose_item(const float* W, int N, bf16_t* WT, int ldw, int drow0, int dk0, LAS float* scr, int k0, int n0, int lane) {
; #pragma unroll 8
;     for (int i = 0; i < 32; ++i) { const int kk = 2 * i + (lane >> 5); scr[kk * 33 + (lane & 31)] = W[(size_t)(k0 + kk) * N + n0 + (lane & 31)]; }
.LBB0_60:
	s_lshl_b32 s15, s12, 1
	s_lshl_b32 s16, s11, 1
	v_or_b32_e32 v30, s15, v1
	v_or_b32_e32 v41, s16, v32
	s_add_i32 s17, s15, 4
	s_add_i32 s18, s16, 4
	s_add_i32 s19, s15, 8
	s_add_i32 s20, s16, 8
	s_add_i32 s21, s15, 12
	s_add_i32 s22, s16, 12
	s_add_i32 s23, s15, 16
	s_add_i32 s26, s16, 16
	s_add_i32 s27, s15, 20
	s_add_i32 s34, s16, 20
	s_add_i32 s35, s15, 24
	s_add_i32 s40, s16, 24
	s_add_i32 s15, s15, 28
	s_add_i32 s16, s16, 28
	v_add_u32_e32 v6, s8, v41
	v_or_b32_e32 v48, s17, v1
	v_or_b32_e32 v49, s18, v32
	v_or_b32_e32 v50, s19, v1
	v_or_b32_e32 v51, s20, v32
	v_or_b32_e32 v52, s21, v1
	v_or_b32_e32 v53, s22, v32
	v_or_b32_e32 v54, s23, v1
	v_or_b32_e32 v55, s26, v32
	v_or_b32_e32 v56, s27, v1
	v_or_b32_e32 v57, s34, v32
	v_or_b32_e32 v71, s35, v1
	v_or_b32_e32 v76, s40, v32
	v_or_b32_e32 v77, s15, v1
	v_or_b32_e32 v78, s16, v32
	v_add_u32_e32 v4, s13, v30
	v_ashrrev_i32_e32 v7, 31, v6
	v_add_u32_e32 v8, s13, v48
	v_add_u32_e32 v10, s8, v49
	v_add_u32_e32 v12, s13, v50
	v_add_u32_e32 v14, s8, v51
	v_add_u32_e32 v16, s13, v52
	v_add_u32_e32 v18, s8, v53
	v_add_u32_e32 v20, s13, v54
	v_add_u32_e32 v22, s8, v55
	v_add_u32_e32 v24, s13, v56
	v_add_u32_e32 v26, s8, v57
	v_add_u32_e32 v28, s13, v71
	v_add_u32_e32 v42, s8, v76
	v_add_u32_e32 v44, s13, v77
	v_add_u32_e32 v46, s8, v78
	v_ashrrev_i32_e32 v5, 31, v4
	v_lshlrev_b64 v[6:7], 12, v[6:7]
	v_ashrrev_i32_e32 v11, 31, v10
	v_ashrrev_i32_e32 v9, 31, v8
	v_ashrrev_i32_e32 v15, 31, v14
	v_ashrrev_i32_e32 v13, 31, v12
	v_ashrrev_i32_e32 v19, 31, v18
	v_ashrrev_i32_e32 v17, 31, v16
	v_ashrrev_i32_e32 v23, 31, v22
	v_ashrrev_i32_e32 v21, 31, v20
	v_ashrrev_i32_e32 v27, 31, v26
	v_ashrrev_i32_e32 v25, 31, v24
	v_ashrrev_i32_e32 v43, 31, v42
	v_ashrrev_i32_e32 v29, 31, v28
	v_ashrrev_i32_e32 v47, 31, v46
	v_ashrrev_i32_e32 v45, 31, v44
	v_lshlrev_b64 v[4:5], 12, v[4:5]
	v_lshl_add_u64 v[6:7], v[2:3], 0, v[6:7]
	v_lshlrev_b64 v[8:9], 12, v[8:9]
	v_lshlrev_b64 v[10:11], 12, v[10:11]
	v_lshlrev_b64 v[12:13], 12, v[12:13]
	v_lshlrev_b64 v[14:15], 12, v[14:15]
	v_lshlrev_b64 v[16:17], 12, v[16:17]
	v_lshlrev_b64 v[18:19], 12, v[18:19]
	v_lshlrev_b64 v[20:21], 12, v[20:21]
	v_lshlrev_b64 v[22:23], 12, v[22:23]
	v_lshlrev_b64 v[24:25], 12, v[24:25]
	v_lshlrev_b64 v[26:27], 12, v[26:27]
	v_lshlrev_b64 v[28:29], 12, v[28:29]
	v_lshlrev_b64 v[42:43], 12, v[42:43]
	v_lshlrev_b64 v[44:45], 12, v[44:45]
	v_lshlrev_b64 v[46:47], 12, v[46:47]
	v_lshl_add_u64 v[4:5], v[2:3], 0, v[4:5]
	v_lshl_add_u64 v[10:11], v[2:3], 0, v[10:11]
	v_lshl_add_u64 v[8:9], v[2:3], 0, v[8:9]
	v_lshl_add_u64 v[14:15], v[2:3], 0, v[14:15]
	v_lshl_add_u64 v[12:13], v[2:3], 0, v[12:13]
	v_lshl_add_u64 v[18:19], v[2:3], 0, v[18:19]
	v_lshl_add_u64 v[16:17], v[2:3], 0, v[16:17]
	v_lshl_add_u64 v[22:23], v[2:3], 0, v[22:23]
	v_lshl_add_u64 v[20:21], v[2:3], 0, v[20:21]
	v_lshl_add_u64 v[26:27], v[2:3], 0, v[26:27]
	v_lshl_add_u64 v[24:25], v[2:3], 0, v[24:25]
	v_lshl_add_u64 v[42:43], v[2:3], 0, v[42:43]
	v_lshl_add_u64 v[28:29], v[2:3], 0, v[28:29]
	v_lshl_add_u64 v[46:47], v[2:3], 0, v[46:47]
	v_lshl_add_u64 v[44:45], v[2:3], 0, v[44:45]
	global_load_dword v79, v[6:7], off nt
	global_load_dword v80, v[4:5], off nt
	global_load_dword v81, v[10:11], off nt
	global_load_dword v82, v[8:9], off nt
	global_load_dword v83, v[14:15], off nt
	global_load_dword v84, v[12:13], off nt
	global_load_dword v85, v[18:19], off nt
	global_load_dword v86, v[16:17], off nt
	global_load_dword v87, v[22:23], off nt
	global_load_dword v88, v[20:21], off nt
	global_load_dword v89, v[26:27], off nt
	global_load_dword v90, v[24:25], off nt
	global_load_dword v91, v[42:43], off nt
	global_load_dword v92, v[28:29], off nt
	global_load_dword v93, v[46:47], off nt
	global_load_dword v94, v[44:45], off nt
	s_add_i32 s11, s11, 16
	s_add_i32 s12, s12, 16
	s_add_i32 s14, s14, -16
	s_lshl_b32 s15, s12, 1
	s_lshl_b32 s16, s11, 1
	v_or_b32_e32 v170, s15, v1
	v_or_b32_e32 v181, s16, v32
	s_add_i32 s17, s15, 4
	s_add_i32 s18, s16, 4
	s_add_i32 s19, s15, 8
	s_add_i32 s20, s16, 8
	s_add_i32 s21, s15, 12
	s_add_i32 s22, s16, 12
	s_add_i32 s23, s15, 16
	s_add_i32 s26, s16, 16
	s_add_i32 s27, s15, 20
	s_add_i32 s34, s16, 20
	s_add_i32 s35, s15, 24
	s_add_i32 s40, s16, 24
	s_add_i32 s15, s15, 28
	s_add_i32 s16, s16, 28
	v_add_u32_e32 v146, s8, v181
	v_or_b32_e32 v188, s17, v1
	v_or_b32_e32 v189, s18, v32
	v_or_b32_e32 v190, s19, v1
	v_or_b32_e32 v191, s20, v32
	v_or_b32_e32 v192, s21, v1
	v_or_b32_e32 v193, s22, v32
	v_or_b32_e32 v194, s23, v1
	v_or_b32_e32 v195, s26, v32
	v_or_b32_e32 v196, s27, v1
	v_or_b32_e32 v197, s34, v32
	v_or_b32_e32 v211, s35, v1
	v_or_b32_e32 v216, s40, v32
	v_or_b32_e32 v217, s15, v1
	v_or_b32_e32 v218, s16, v32
	v_add_u32_e32 v144, s13, v170
	v_ashrrev_i32_e32 v147, 31, v146
	v_add_u32_e32 v148, s13, v188
	v_add_u32_e32 v150, s8, v189
	v_add_u32_e32 v152, s13, v190
	v_add_u32_e32 v154, s8, v191
	v_add_u32_e32 v156, s13, v192
	v_add_u32_e32 v158, s8, v193
	v_add_u32_e32 v160, s13, v194
	v_add_u32_e32 v162, s8, v195
	v_add_u32_e32 v164, s13, v196
	v_add_u32_e32 v166, s8, v197
	v_add_u32_e32 v168, s13, v211
	v_add_u32_e32 v182, s8, v216
	v_add_u32_e32 v184, s13, v217
	v_add_u32_e32 v186, s8, v218
	v_ashrrev_i32_e32 v145, 31, v144
	v_lshlrev_b64 v[146:147], 12, v[146:147]
	v_ashrrev_i32_e32 v151, 31, v150
	v_ashrrev_i32_e32 v149, 31, v148
	v_ashrrev_i32_e32 v155, 31, v154
	v_ashrrev_i32_e32 v153, 31, v152
	v_ashrrev_i32_e32 v159, 31, v158
	v_ashrrev_i32_e32 v157, 31, v156
	v_ashrrev_i32_e32 v163, 31, v162
	v_ashrrev_i32_e32 v161, 31, v160
	v_ashrrev_i32_e32 v167, 31, v166
	v_ashrrev_i32_e32 v165, 31, v164
	v_ashrrev_i32_e32 v183, 31, v182
; #define LDS_WAIT() asm volatile("s_waitcnt lgkmcnt(0)" ::: "memory")
; __device__ __forceinline__ void transpose_item(const float* W, int N, bf16_t* WT, int ldw, int drow0, int dk0, LAS float* scr, int k0, int n0, int lane) {
; #pragma unroll 8
;     for (int i = 0; i < 32; ++i) { const int kk = 2 * i + (lane >> 5); scr[kk * 33 + (lane & 31)] = W[(size_t)(k0 + kk) * N + n0 + (lane & 31)]; }
;     LDS_WAIT(); asm volatile("" ::: "memory");
	v_ashrrev_i32_e32 v169, 31, v168
	v_ashrrev_i32_e32 v187, 31, v186
	v_ashrrev_i32_e32 v185, 31, v184
	v_lshlrev_b64 v[144:145], 12, v[144:145]
	v_lshl_add_u64 v[146:147], v[2:3], 0, v[146:147]
	v_lshlrev_b64 v[148:149], 12, v[148:149]
	v_lshlrev_b64 v[150:151], 12, v[150:151]
	v_lshlrev_b64 v[152:153], 12, v[152:153]
	v_lshlrev_b64 v[154:155], 12, v[154:155]
	v_lshlrev_b64 v[156:157], 12, v[156:157]
	v_lshlrev_b64 v[158:159], 12, v[158:159]
	v_lshlrev_b64 v[160:161], 12, v[160:161]
	v_lshlrev_b64 v[162:163], 12, v[162:163]
	v_lshlrev_b64 v[164:165], 12, v[164:165]
	v_lshlrev_b64 v[166:167], 12, v[166:167]
	v_lshlrev_b64 v[168:169], 12, v[168:169]
	v_lshlrev_b64 v[182:183], 12, v[182:183]
	v_lshlrev_b64 v[184:185], 12, v[184:185]
	v_lshlrev_b64 v[186:187], 12, v[186:187]
	v_lshl_add_u64 v[144:145], v[2:3], 0, v[144:145]
	v_lshl_add_u64 v[150:151], v[2:3], 0, v[150:151]
	v_lshl_add_u64 v[148:149], v[2:3], 0, v[148:149]
	v_lshl_add_u64 v[154:155], v[2:3], 0, v[154:155]
	v_lshl_add_u64 v[152:153], v[2:3], 0, v[152:153]
	v_lshl_add_u64 v[158:159], v[2:3], 0, v[158:159]
	v_lshl_add_u64 v[156:157], v[2:3], 0, v[156:157]
	v_lshl_add_u64 v[162:163], v[2:3], 0, v[162:163]
	v_lshl_add_u64 v[160:161], v[2:3], 0, v[160:161]
	v_lshl_add_u64 v[166:167], v[2:3], 0, v[166:167]
	v_lshl_add_u64 v[164:165], v[2:3], 0, v[164:165]
	v_lshl_add_u64 v[182:183], v[2:3], 0, v[182:183]
	v_lshl_add_u64 v[168:169], v[2:3], 0, v[168:169]
	v_lshl_add_u64 v[186:187], v[2:3], 0, v[186:187]
	v_lshl_add_u64 v[184:185], v[2:3], 0, v[184:185]
	global_load_dword v219, v[146:147], off nt
	global_load_dword v220, v[144:145], off nt
	global_load_dword v221, v[150:151], off nt
	global_load_dword v222, v[148:149], off nt
	global_load_dword v223, v[154:155], off nt
	global_load_dword v224, v[152:153], off nt
	global_load_dword v225, v[158:159], off nt
	global_load_dword v226, v[156:157], off nt
	global_load_dword v227, v[162:163], off nt
	global_load_dword v228, v[160:161], off nt
	global_load_dword v229, v[166:167], off nt
	global_load_dword v230, v[164:165], off nt
	global_load_dword v231, v[182:183], off nt
	global_load_dword v232, v[168:169], off nt
	global_load_dword v233, v[186:187], off nt
	global_load_dword v234, v[184:185], off nt
	v_mad_u64_u32 v[4:5], s[16:17], v41, s67, v[36:37]
	v_mad_u64_u32 v[6:7], s[16:17], v30, s67, v[36:37]
	v_mad_u64_u32 v[8:9], s[16:17], v49, s67, v[36:37]
	v_mad_u64_u32 v[10:11], s[16:17], v48, s67, v[36:37]
	v_mad_u64_u32 v[12:13], s[16:17], v51, s67, v[36:37]
	v_mad_u64_u32 v[14:15], s[16:17], v50, s67, v[36:37]
	v_mad_u64_u32 v[16:17], s[16:17], v53, s67, v[36:37]
	v_mad_u64_u32 v[18:19], s[16:17], v52, s67, v[36:37]
	v_mad_u64_u32 v[20:21], s[16:17], v55, s67, v[36:37]
	v_mad_u64_u32 v[22:23], s[16:17], v54, s67, v[36:37]
	v_mad_u64_u32 v[24:25], s[16:17], v57, s67, v[36:37]
	v_mad_u64_u32 v[26:27], s[16:17], v56, s67, v[36:37]
	v_mad_u64_u32 v[28:29], s[16:17], v76, s67, v[36:37]
	v_mad_u64_u32 v[42:43], s[16:17], v71, s67, v[36:37]
	v_mad_u64_u32 v[44:45], s[16:17], v78, s67, v[36:37]
	v_mad_u64_u32 v[46:47], s[16:17], v77, s67, v[36:37]
	s_waitcnt vmcnt(31)
	ds_write_b32 v4, v79
	s_waitcnt vmcnt(30)
	ds_write_b32 v6, v80
	s_waitcnt vmcnt(29)
	ds_write_b32 v8, v81
	s_waitcnt vmcnt(28)
	ds_write_b32 v10, v82
	s_waitcnt vmcnt(27)
	ds_write_b32 v12, v83
	s_waitcnt vmcnt(26)
	ds_write_b32 v14, v84
	s_waitcnt vmcnt(25)
	ds_write_b32 v16, v85
	s_waitcnt vmcnt(24)
	ds_write_b32 v18, v86
	s_waitcnt vmcnt(23)
	ds_write_b32 v20, v87
	s_waitcnt vmcnt(22)
	ds_write_b32 v22, v88
	s_waitcnt vmcnt(21)
	ds_write_b32 v24, v89
	s_waitcnt vmcnt(20)
	ds_write_b32 v26, v90
	s_waitcnt vmcnt(19)
	ds_write_b32 v28, v91
	s_waitcnt vmcnt(18)
	ds_write_b32 v42, v92
	s_waitcnt vmcnt(17)
	ds_write_b32 v44, v93
	s_waitcnt vmcnt(16)
; #define LAS __attribute__((address_space(3)))
; __device__ __forceinline__ unsigned cvtpk_s(float lo, float hi) { f32x2_t v = {lo, hi}; bf16x2_t b = __builtin_convertvector(v, bf16x2_t); return __builtin_bit_cast(unsigned, b); }
; #define LDS_WAIT() asm volatile("s_waitcnt lgkmcnt(0)" ::: "memory")
; __device__ __forceinline__ void transpose_item(const float* W, int N, bf16_t* WT, int ldw, int drow0, int dk0, LAS float* scr, int k0, int n0, int lane) {
;     ...
;     for (int i = 0; i < 32; ++i) { const int kk = 2 * i + (lane >> 5); scr[kk * 33 + (lane & 31)] = W[(size_t)(k0 + kk) * N + n0 + (lane & 31)]; }
;     LDS_WAIT(); asm volatile("" ::: "memory");
;     const int c = lane & 7;
; #pragma unroll
;     for (int j = 0; j < 4; ++j) { const int n = (lane >> 3) + 8 * j; const LAS float* s = scr + (8 * c) * 33 + n;
;         u32x4 o; o.x = cvtpk_s(s[0 * 33], s[1 * 33]); o.y = cvtpk_s(s[2 * 33], s[3 * 33]); o.z = cvtpk_s(s[4 * 33], s[5 * 33]); o.w = cvtpk_s(s[6 * 33], s[7 * 33]);
;         *(u32x4*)(WT + (size_t)(drow0 + n) * ldw + dk0 + k0 + 8 * c) = o; }
;     LDS_WAIT(); asm volatile("" ::: "memory");
; __device__ __forceinline__ void prologue(const kptr_t kp, LAS float* scr, int gw, int NGW, int lane) {
;     ...
;             if (r < IT_P) { const int kb = r / 32, nb = r % 32, n0 = 32 * nb; transpose_item(KPTR(const float, 16) + (size_t)l * 512 * D, D, (bf16_t*)(wl + W_PAB), D, 256 * (n0 / 128) + (n0 % 128), 0, scr, 64 * kb, n0, lane); continue; } r -= IT_P;
;             if (r < IT_P) { const int kb = r / 32, nb = r % 32, n0 = 32 * nb; transpose_item(KPTR(const float, 17) + (size_t)l * 512 * D, D, (bf16_t*)(wl + W_PAB), D, 256 * (n0 / 128) + 128 + (n0 % 128), 512, scr, 64 * kb, n0, lane); continue; } r -= IT_P;
	ds_write_b32 v46, v94
	s_add_i32 s11, s11, 16
	s_add_i32 s12, s12, 16
	s_add_i32 s14, s14, -16
	v_mad_u64_u32 v[144:145], s[16:17], v181, s67, v[36:37]
	v_mad_u64_u32 v[146:147], s[16:17], v170, s67, v[36:37]
	v_mad_u64_u32 v[148:149], s[16:17], v189, s67, v[36:37]
	v_mad_u64_u32 v[150:151], s[16:17], v188, s67, v[36:37]
	v_mad_u64_u32 v[152:153], s[16:17], v191, s67, v[36:37]
	v_mad_u64_u32 v[154:155], s[16:17], v190, s67, v[36:37]
	v_mad_u64_u32 v[156:157], s[16:17], v193, s67, v[36:37]
	v_mad_u64_u32 v[158:159], s[16:17], v192, s67, v[36:37]
	v_mad_u64_u32 v[160:161], s[16:17], v195, s67, v[36:37]
	v_mad_u64_u32 v[162:163], s[16:17], v194, s67, v[36:37]
	v_mad_u64_u32 v[164:165], s[16:17], v197, s67, v[36:37]
	v_mad_u64_u32 v[166:167], s[16:17], v196, s67, v[36:37]
	v_mad_u64_u32 v[168:169], s[16:17], v216, s67, v[36:37]
	v_mad_u64_u32 v[182:183], s[16:17], v211, s67, v[36:37]
	v_mad_u64_u32 v[184:185], s[16:17], v218, s67, v[36:37]
	v_mad_u64_u32 v[186:187], s[16:17], v217, s67, v[36:37]
	s_waitcnt vmcnt(15)
	ds_write_b32 v144, v219
	s_waitcnt vmcnt(14)
	ds_write_b32 v146, v220
	s_waitcnt vmcnt(13)
	ds_write_b32 v148, v221
	s_waitcnt vmcnt(12)
	ds_write_b32 v150, v222
	s_waitcnt vmcnt(11)
	ds_write_b32 v152, v223
	s_waitcnt vmcnt(10)
	ds_write_b32 v154, v224
	s_waitcnt vmcnt(9)
	ds_write_b32 v156, v225
	s_waitcnt vmcnt(8)
	ds_write_b32 v158, v226
	s_waitcnt vmcnt(7)
	ds_write_b32 v160, v227
	s_waitcnt vmcnt(6)
	ds_write_b32 v162, v228
	s_waitcnt vmcnt(5)
	ds_write_b32 v164, v229
	s_waitcnt vmcnt(4)
	ds_write_b32 v166, v230
	s_waitcnt vmcnt(3)
	ds_write_b32 v168, v231
	s_waitcnt vmcnt(2)
	ds_write_b32 v182, v232
	s_waitcnt vmcnt(1)
	ds_write_b32 v184, v233
	s_waitcnt vmcnt(0)
	ds_write_b32 v186, v234
	s_lshl_b32 s11, s3, 6
	s_and_b32 s11, s11, 0x700
	s_and_b32 s9, s9, 0x60
	s_or_b32 s9, s11, s9
	s_or_b32 s11, s9, 0x80
	s_waitcnt lgkmcnt(0)
	s_mov_b32 s9, s41
	s_lshl_b64 s[8:9], s[8:9], 1
	s_add_u32 s8, s4, s8
	ds_read2_b32 v[6:7], v60 offset0:33 offset1:41
	ds_read2_b32 v[8:9], v60 offset1:8
	ds_read2_b32 v[10:11], v60 offset0:66 offset1:74
	ds_read2_b32 v[12:13], v60 offset0:99 offset1:107
	ds_read2_b32 v[14:15], v60 offset0:132 offset1:140
	ds_read2_b32 v[16:17], v60 offset0:165 offset1:173
	ds_read2_b32 v[18:19], v60 offset0:198 offset1:206
	ds_read2_b32 v[20:21], v60 offset0:231 offset1:239
	s_addc_u32 s9, s5, s9
	v_lshlrev_b32_e32 v30, 1, v38
	v_lshl_add_u64 v[2:3], s[8:9], 0, v[30:31]
	v_lshl_add_u64 v[22:23], v[2:3], 0, s[52:53]
	s_waitcnt lgkmcnt(6)
	v_cvt_pk_bf16_f32 v2, v8, v6
	v_or_b32_e32 v6, s11, v59
	v_lshlrev_b32_e32 v30, 11, v6
	s_waitcnt lgkmcnt(4)
	v_cvt_pk_bf16_f32 v3, v10, v12
	s_waitcnt lgkmcnt(2)
	v_cvt_pk_bf16_f32 v4, v14, v16
	s_waitcnt lgkmcnt(0)
	v_cvt_pk_bf16_f32 v5, v18, v20
	v_lshl_add_u64 v[24:25], v[22:23], 0, v[30:31]
	global_store_dwordx4 v[24:25], v[2:5], off
	v_or_b32_e32 v6, s11, v61
	v_lshlrev_b32_e32 v30, 11, v6
	v_cvt_pk_bf16_f32 v2, v9, v7
	v_cvt_pk_bf16_f32 v3, v11, v13
	v_cvt_pk_bf16_f32 v4, v15, v17
	v_cvt_pk_bf16_f32 v5, v19, v21
	ds_read2_b32 v[8:9], v60 offset0:49 offset1:57
	ds_read2_b32 v[10:11], v60 offset0:16 offset1:24
	ds_read2_b32 v[12:13], v60 offset0:82 offset1:90
	ds_read2_b32 v[14:15], v60 offset0:115 offset1:123
	ds_read2_b32 v[16:17], v60 offset0:148 offset1:156
	ds_read2_b32 v[18:19], v60 offset0:181 offset1:189
	ds_read2_b32 v[20:21], v60 offset0:214 offset1:222
	ds_read2_b32 v[24:25], v60 offset0:247 offset1:255
	v_lshl_add_u64 v[6:7], v[22:23], 0, v[30:31]
	global_store_dwordx4 v[6:7], v[2:5], off
	v_or_b32_e32 v6, s11, v62
	v_lshlrev_b32_e32 v30, 11, v6
	s_waitcnt lgkmcnt(6)
	v_cvt_pk_bf16_f32 v2, v10, v8
	s_waitcnt lgkmcnt(4)
	v_cvt_pk_bf16_f32 v3, v12, v14
	s_waitcnt lgkmcnt(2)
	v_cvt_pk_bf16_f32 v4, v16, v18
	s_waitcnt lgkmcnt(0)
	v_cvt_pk_bf16_f32 v5, v20, v24
	v_lshl_add_u64 v[6:7], v[22:23], 0, v[30:31]
	global_store_dwordx4 v[6:7], v[2:5], off
	v_or_b32_e32 v6, s11, v63
	v_lshlrev_b32_e32 v30, 11, v6
	v_cvt_pk_bf16_f32 v2, v11, v9
	v_cvt_pk_bf16_f32 v3, v13, v15
	v_cvt_pk_bf16_f32 v4, v17, v19
	v_cvt_pk_bf16_f32 v5, v21, v25
	v_lshl_add_u64 v[6:7], v[22:23], 0, v[30:31]
	global_store_dwordx4 v[6:7], v[2:5], off
	s_waitcnt lgkmcnt(0)

; #define LAS __attribute__((address_space(3)))
; __device__ __forceinline__ void transpose_item(const float* W, int N, bf16_t* WT, int ldw, int drow0, int dk0, LAS float* scr, int k0, int n0, int lane) {
; #pragma unroll 8
;     for (int i = 0; i < 32; ++i) { const int kk = 2 * i + (lane >> 5); scr[kk * 33 + (lane & 31)] = W[(size_t)(k0 + kk) * N + n0 + (lane & 31)]; }
.LBB0_65:
	s_lshl_b32 s15, s12, 1
	s_lshl_b32 s16, s11, 1
	v_or_b32_e32 v30, s15, v1
	v_or_b32_e32 v41, s16, v32
	s_add_i32 s17, s15, 4
	s_add_i32 s18, s16, 4
	s_add_i32 s19, s15, 8
	s_add_i32 s20, s16, 8
	s_add_i32 s21, s15, 12
	s_add_i32 s22, s16, 12
	s_add_i32 s23, s15, 16
	s_add_i32 s26, s16, 16
	s_add_i32 s27, s15, 20
	s_add_i32 s34, s16, 20
	s_add_i32 s35, s15, 24
	s_add_i32 s40, s16, 24
	s_add_i32 s15, s15, 28
	s_add_i32 s16, s16, 28
	v_add_u32_e32 v6, s8, v41
	v_or_b32_e32 v48, s17, v1
	v_or_b32_e32 v49, s18, v32
	v_or_b32_e32 v50, s19, v1
	v_or_b32_e32 v51, s20, v32
	v_or_b32_e32 v52, s21, v1
	v_or_b32_e32 v53, s22, v32
	v_or_b32_e32 v54, s23, v1
	v_or_b32_e32 v55, s26, v32
	v_or_b32_e32 v56, s27, v1
	v_or_b32_e32 v57, s34, v32
	v_or_b32_e32 v71, s35, v1
	v_or_b32_e32 v76, s40, v32
	v_or_b32_e32 v77, s15, v1
	v_or_b32_e32 v78, s16, v32
	v_add_u32_e32 v4, s13, v30
	v_ashrrev_i32_e32 v7, 31, v6
	v_add_u32_e32 v8, s13, v48
	v_add_u32_e32 v10, s8, v49
	v_add_u32_e32 v12, s13, v50
	v_add_u32_e32 v14, s8, v51
	v_add_u32_e32 v16, s13, v52
	v_add_u32_e32 v18, s8, v53
	v_add_u32_e32 v20, s13, v54
	v_add_u32_e32 v22, s8, v55
	v_add_u32_e32 v24, s13, v56
	v_add_u32_e32 v26, s8, v57
	v_add_u32_e32 v28, s13, v71
	v_add_u32_e32 v42, s8, v76
	v_add_u32_e32 v44, s13, v77
	v_add_u32_e32 v46, s8, v78
	v_ashrrev_i32_e32 v5, 31, v4
	v_lshlrev_b64 v[6:7], 12, v[6:7]
	v_ashrrev_i32_e32 v11, 31, v10
	v_ashrrev_i32_e32 v9, 31, v8
	v_ashrrev_i32_e32 v15, 31, v14
	v_ashrrev_i32_e32 v13, 31, v12
	v_ashrrev_i32_e32 v19, 31, v18
	v_ashrrev_i32_e32 v17, 31, v16
	v_ashrrev_i32_e32 v23, 31, v22
	v_ashrrev_i32_e32 v21, 31, v20
	v_ashrrev_i32_e32 v27, 31, v26
	v_ashrrev_i32_e32 v25, 31, v24
	v_ashrrev_i32_e32 v43, 31, v42
	v_ashrrev_i32_e32 v29, 31, v28
	v_ashrrev_i32_e32 v47, 31, v46
	v_ashrrev_i32_e32 v45, 31, v44
	v_lshlrev_b64 v[4:5], 12, v[4:5]
	v_lshl_add_u64 v[6:7], v[2:3], 0, v[6:7]
	v_lshlrev_b64 v[8:9], 12, v[8:9]
	v_lshlrev_b64 v[10:11], 12, v[10:11]
	v_lshlrev_b64 v[12:13], 12, v[12:13]
	v_lshlrev_b64 v[14:15], 12, v[14:15]
	v_lshlrev_b64 v[16:17], 12, v[16:17]
	v_lshlrev_b64 v[18:19], 12, v[18:19]
	v_lshlrev_b64 v[20:21], 12, v[20:21]
	v_lshlrev_b64 v[22:23], 12, v[22:23]
	v_lshlrev_b64 v[24:25], 12, v[24:25]
	v_lshlrev_b64 v[26:27], 12, v[26:27]
	v_lshlrev_b64 v[28:29], 12, v[28:29]
	v_lshlrev_b64 v[42:43], 12, v[42:43]
	v_lshlrev_b64 v[44:45], 12, v[44:45]
	v_lshlrev_b64 v[46:47], 12, v[46:47]
	v_lshl_add_u64 v[4:5], v[2:3], 0, v[4:5]
	v_lshl_add_u64 v[10:11], v[2:3], 0, v[10:11]
	v_lshl_add_u64 v[8:9], v[2:3], 0, v[8:9]
	v_lshl_add_u64 v[14:15], v[2:3], 0, v[14:15]
	v_lshl_add_u64 v[12:13], v[2:3], 0, v[12:13]
	v_lshl_add_u64 v[18:19], v[2:3], 0, v[18:19]
	v_lshl_add_u64 v[16:17], v[2:3], 0, v[16:17]
	v_lshl_add_u64 v[22:23], v[2:3], 0, v[22:23]
	v_lshl_add_u64 v[20:21], v[2:3], 0, v[20:21]
	v_lshl_add_u64 v[26:27], v[2:3], 0, v[26:27]
	v_lshl_add_u64 v[24:25], v[2:3], 0, v[24:25]
	v_lshl_add_u64 v[42:43], v[2:3], 0, v[42:43]
	v_lshl_add_u64 v[28:29], v[2:3], 0, v[28:29]
	v_lshl_add_u64 v[46:47], v[2:3], 0, v[46:47]
	v_lshl_add_u64 v[44:45], v[2:3], 0, v[44:45]
	global_load_dword v79, v[6:7], off nt
	global_load_dword v80, v[4:5], off nt
	global_load_dword v81, v[10:11], off nt
	global_load_dword v82, v[8:9], off nt
	global_load_dword v83, v[14:15], off nt
	global_load_dword v84, v[12:13], off nt
	global_load_dword v85, v[18:19], off nt
	global_load_dword v86, v[16:17], off nt
	global_load_dword v87, v[22:23], off nt
	global_load_dword v88, v[20:21], off nt
	global_load_dword v89, v[26:27], off nt
	global_load_dword v90, v[24:25], off nt
	global_load_dword v91, v[42:43], off nt
	global_load_dword v92, v[28:29], off nt
	global_load_dword v93, v[46:47], off nt
	global_load_dword v94, v[44:45], off nt
	s_add_i32 s11, s11, 16
	s_add_i32 s12, s12, 16
	s_add_i32 s14, s14, -16
	s_lshl_b32 s15, s12, 1
	s_lshl_b32 s16, s11, 1
	v_or_b32_e32 v170, s15, v1
	v_or_b32_e32 v181, s16, v32
	s_add_i32 s17, s15, 4
	s_add_i32 s18, s16, 4
	s_add_i32 s19, s15, 8
	s_add_i32 s20, s16, 8
	s_add_i32 s21, s15, 12
	s_add_i32 s22, s16, 12
	s_add_i32 s23, s15, 16
	s_add_i32 s26, s16, 16
	s_add_i32 s27, s15, 20
	s_add_i32 s34, s16, 20
	s_add_i32 s35, s15, 24
	s_add_i32 s40, s16, 24
	s_add_i32 s15, s15, 28
	s_add_i32 s16, s16, 28
	v_add_u32_e32 v146, s8, v181
	v_or_b32_e32 v188, s17, v1
	v_or_b32_e32 v189, s18, v32
	v_or_b32_e32 v190, s19, v1
	v_or_b32_e32 v191, s20, v32
	v_or_b32_e32 v192, s21, v1
	v_or_b32_e32 v193, s22, v32
	v_or_b32_e32 v194, s23, v1
	v_or_b32_e32 v195, s26, v32
	v_or_b32_e32 v196, s27, v1
	v_or_b32_e32 v197, s34, v32
	v_or_b32_e32 v211, s35, v1
	v_or_b32_e32 v216, s40, v32
	v_or_b32_e32 v217, s15, v1
	v_or_b32_e32 v218, s16, v32
	v_add_u32_e32 v144, s13, v170
	v_ashrrev_i32_e32 v147, 31, v146
	v_add_u32_e32 v148, s13, v188
	v_add_u32_e32 v150, s8, v189
	v_add_u32_e32 v152, s13, v190
	v_add_u32_e32 v154, s8, v191
	v_add_u32_e32 v156, s13, v192
	v_add_u32_e32 v158, s8, v193
	v_add_u32_e32 v160, s13, v194
	v_add_u32_e32 v162, s8, v195
	v_add_u32_e32 v164, s13, v196
	v_add_u32_e32 v166, s8, v197
	v_add_u32_e32 v168, s13, v211
	v_add_u32_e32 v182, s8, v216
	v_add_u32_e32 v184, s13, v217
	v_add_u32_e32 v186, s8, v218
	v_ashrrev_i32_e32 v145, 31, v144
	v_lshlrev_b64 v[146:147], 12, v[146:147]
	v_ashrrev_i32_e32 v151, 31, v150
	v_ashrrev_i32_e32 v149, 31, v148
	v_ashrrev_i32_e32 v155, 31, v154
	v_ashrrev_i32_e32 v153, 31, v152
	v_ashrrev_i32_e32 v159, 31, v158
	v_ashrrev_i32_e32 v157, 31, v156
	v_ashrrev_i32_e32 v163, 31, v162
	v_ashrrev_i32_e32 v161, 31, v160
	v_ashrrev_i32_e32 v167, 31, v166
	v_ashrrev_i32_e32 v165, 31, v164
	v_ashrrev_i32_e32 v183, 31, v182
; #define LDS_WAIT() asm volatile("s_waitcnt lgkmcnt(0)" ::: "memory")
; __device__ __forceinline__ void transpose_item(const float* W, int N, bf16_t* WT, int ldw, int drow0, int dk0, LAS float* scr, int k0, int n0, int lane) {
; #pragma unroll 8
;     for (int i = 0; i < 32; ++i) { const int kk = 2 * i + (lane >> 5); scr[kk * 33 + (lane & 31)] = W[(size_t)(k0 + kk) * N + n0 + (lane & 31)]; }
;     LDS_WAIT(); asm volatile("" ::: "memory");
	v_ashrrev_i32_e32 v169, 31, v168
	v_ashrrev_i32_e32 v187, 31, v186
	v_ashrrev_i32_e32 v185, 31, v184
	v_lshlrev_b64 v[144:145], 12, v[144:145]
	v_lshl_add_u64 v[146:147], v[2:3], 0, v[146:147]
	v_lshlrev_b64 v[148:149], 12, v[148:149]
	v_lshlrev_b64 v[150:151], 12, v[150:151]
	v_lshlrev_b64 v[152:153], 12, v[152:153]
	v_lshlrev_b64 v[154:155], 12, v[154:155]
	v_lshlrev_b64 v[156:157], 12, v[156:157]
	v_lshlrev_b64 v[158:159], 12, v[158:159]
	v_lshlrev_b64 v[160:161], 12, v[160:161]
	v_lshlrev_b64 v[162:163], 12, v[162:163]
	v_lshlrev_b64 v[164:165], 12, v[164:165]
	v_lshlrev_b64 v[166:167], 12, v[166:167]
	v_lshlrev_b64 v[168:169], 12, v[168:169]
	v_lshlrev_b64 v[182:183], 12, v[182:183]
	v_lshlrev_b64 v[184:185], 12, v[184:185]
	v_lshlrev_b64 v[186:187], 12, v[186:187]
	v_lshl_add_u64 v[144:145], v[2:3], 0, v[144:145]
	v_lshl_add_u64 v[150:151], v[2:3], 0, v[150:151]
	v_lshl_add_u64 v[148:149], v[2:3], 0, v[148:149]
	v_lshl_add_u64 v[154:155], v[2:3], 0, v[154:155]
	v_lshl_add_u64 v[152:153], v[2:3], 0, v[152:153]
	v_lshl_add_u64 v[158:159], v[2:3], 0, v[158:159]
	v_lshl_add_u64 v[156:157], v[2:3], 0, v[156:157]
	v_lshl_add_u64 v[162:163], v[2:3], 0, v[162:163]
	v_lshl_add_u64 v[160:161], v[2:3], 0, v[160:161]
	v_lshl_add_u64 v[166:167], v[2:3], 0, v[166:167]
	v_lshl_add_u64 v[164:165], v[2:3], 0, v[164:165]
	v_lshl_add_u64 v[182:183], v[2:3], 0, v[182:183]
	v_lshl_add_u64 v[168:169], v[2:3], 0, v[168:169]
	v_lshl_add_u64 v[186:187], v[2:3], 0, v[186:187]
	v_lshl_add_u64 v[184:185], v[2:3], 0, v[184:185]
	global_load_dword v219, v[146:147], off nt
	global_load_dword v220, v[144:145], off nt
	global_load_dword v221, v[150:151], off nt
	global_load_dword v222, v[148:149], off nt
	global_load_dword v223, v[154:155], off nt
	global_load_dword v224, v[152:153], off nt
	global_load_dword v225, v[158:159], off nt
	global_load_dword v226, v[156:157], off nt
	global_load_dword v227, v[162:163], off nt
	global_load_dword v228, v[160:161], off nt
	global_load_dword v229, v[166:167], off nt
	global_load_dword v230, v[164:165], off nt
	global_load_dword v231, v[182:183], off nt
	global_load_dword v232, v[168:169], off nt
	global_load_dword v233, v[186:187], off nt
	global_load_dword v234, v[184:185], off nt
	v_mad_u64_u32 v[4:5], s[16:17], v41, s67, v[36:37]
	v_mad_u64_u32 v[6:7], s[16:17], v30, s67, v[36:37]
	v_mad_u64_u32 v[8:9], s[16:17], v49, s67, v[36:37]
	v_mad_u64_u32 v[10:11], s[16:17], v48, s67, v[36:37]
	v_mad_u64_u32 v[12:13], s[16:17], v51, s67, v[36:37]
	v_mad_u64_u32 v[14:15], s[16:17], v50, s67, v[36:37]
	v_mad_u64_u32 v[16:17], s[16:17], v53, s67, v[36:37]
	v_mad_u64_u32 v[18:19], s[16:17], v52, s67, v[36:37]
	v_mad_u64_u32 v[20:21], s[16:17], v55, s67, v[36:37]
	v_mad_u64_u32 v[22:23], s[16:17], v54, s67, v[36:37]
	v_mad_u64_u32 v[24:25], s[16:17], v57, s67, v[36:37]
	v_mad_u64_u32 v[26:27], s[16:17], v56, s67, v[36:37]
	v_mad_u64_u32 v[28:29], s[16:17], v76, s67, v[36:37]
	v_mad_u64_u32 v[42:43], s[16:17], v71, s67, v[36:37]
	v_mad_u64_u32 v[44:45], s[16:17], v78, s67, v[36:37]
	v_mad_u64_u32 v[46:47], s[16:17], v77, s67, v[36:37]
	s_waitcnt vmcnt(31)
	ds_write_b32 v4, v79
	s_waitcnt vmcnt(30)
	ds_write_b32 v6, v80
	s_waitcnt vmcnt(29)
	ds_write_b32 v8, v81
	s_waitcnt vmcnt(28)
	ds_write_b32 v10, v82
	s_waitcnt vmcnt(27)
	ds_write_b32 v12, v83
	s_waitcnt vmcnt(26)
	ds_write_b32 v14, v84
	s_waitcnt vmcnt(25)
	ds_write_b32 v16, v85
	s_waitcnt vmcnt(24)
	ds_write_b32 v18, v86
	s_waitcnt vmcnt(23)
	ds_write_b32 v20, v87
	s_waitcnt vmcnt(22)
	ds_write_b32 v22, v88
	s_waitcnt vmcnt(21)
	ds_write_b32 v24, v89
	s_waitcnt vmcnt(20)
	ds_write_b32 v26, v90
	s_waitcnt vmcnt(19)
	ds_write_b32 v28, v91
	s_waitcnt vmcnt(18)
	ds_write_b32 v42, v92
	s_waitcnt vmcnt(17)
	ds_write_b32 v44, v93
	s_waitcnt vmcnt(16)
; #define LAS __attribute__((address_space(3)))
; __device__ __forceinline__ unsigned cvtpk_s(float lo, float hi) { f32x2_t v = {lo, hi}; bf16x2_t b = __builtin_convertvector(v, bf16x2_t); return __builtin_bit_cast(unsigned, b); }
; #define LDS_WAIT() asm volatile("s_waitcnt lgkmcnt(0)" ::: "memory")
; __device__ __forceinline__ void transpose_item(const float* W, int N, bf16_t* WT, int ldw, int drow0, int dk0, LAS float* scr, int k0, int n0, int lane) {
;     ...
;     for (int i = 0; i < 32; ++i) { const int kk = 2 * i + (lane >> 5); scr[kk * 33 + (lane & 31)] = W[(size_t)(k0 + kk) * N + n0 + (lane & 31)]; }
;     LDS_WAIT(); asm volatile("" ::: "memory");
;     const int c = lane & 7;
; #pragma unroll
;     for (int j = 0; j < 4; ++j) { const int n = (lane >> 3) + 8 * j; const LAS float* s = scr + (8 * c) * 33 + n;
;         u32x4 o; o.x = cvtpk_s(s[0 * 33], s[1 * 33]); o.y = cvtpk_s(s[2 * 33], s[3 * 33]); o.z = cvtpk_s(s[4 * 33], s[5 * 33]); o.w = cvtpk_s(s[6 * 33], s[7 * 33]);
;         *(u32x4*)(WT + (size_t)(drow0 + n) * ldw + dk0 + k0 + 8 * c) = o; }
;     LDS_WAIT(); asm volatile("" ::: "memory");
; __device__ __forceinline__ void prologue(const kptr_t kp, LAS float* scr, int gw, int NGW, int lane) {
;     ...
;             if (r < IT_P) { const int kb = r / 32, nb = r % 32, n0 = 32 * nb; transpose_item(KPTR(const float, 16) + (size_t)l * 512 * D, D, (bf16_t*)(wl + W_PAB), D, 256 * (n0 / 128) + (n0 % 128), 0, scr, 64 * kb, n0, lane); continue; } r -= IT_P;
	ds_write_b32 v46, v94
	s_add_i32 s11, s11, 16
	s_add_i32 s12, s12, 16
	s_add_i32 s14, s14, -16
	v_mad_u64_u32 v[144:145], s[16:17], v181, s67, v[36:37]
	v_mad_u64_u32 v[146:147], s[16:17], v170, s67, v[36:37]
	v_mad_u64_u32 v[148:149], s[16:17], v189, s67, v[36:37]
	v_mad_u64_u32 v[150:151], s[16:17], v188, s67, v[36:37]
	v_mad_u64_u32 v[152:153], s[16:17], v191, s67, v[36:37]
	v_mad_u64_u32 v[154:155], s[16:17], v190, s67, v[36:37]
	v_mad_u64_u32 v[156:157], s[16:17], v193, s67, v[36:37]
	v_mad_u64_u32 v[158:159], s[16:17], v192, s67, v[36:37]
	v_mad_u64_u32 v[160:161], s[16:17], v195, s67, v[36:37]
	v_mad_u64_u32 v[162:163], s[16:17], v194, s67, v[36:37]
	v_mad_u64_u32 v[164:165], s[16:17], v197, s67, v[36:37]
	v_mad_u64_u32 v[166:167], s[16:17], v196, s67, v[36:37]
	v_mad_u64_u32 v[168:169], s[16:17], v216, s67, v[36:37]
	v_mad_u64_u32 v[182:183], s[16:17], v211, s67, v[36:37]
	v_mad_u64_u32 v[184:185], s[16:17], v218, s67, v[36:37]
	v_mad_u64_u32 v[186:187], s[16:17], v217, s67, v[36:37]
	s_waitcnt vmcnt(15)
	ds_write_b32 v144, v219
	s_waitcnt vmcnt(14)
	ds_write_b32 v146, v220
	s_waitcnt vmcnt(13)
	ds_write_b32 v148, v221
	s_waitcnt vmcnt(12)
	ds_write_b32 v150, v222
	s_waitcnt vmcnt(11)
	ds_write_b32 v152, v223
	s_waitcnt vmcnt(10)
	ds_write_b32 v154, v224
	s_waitcnt vmcnt(9)
	ds_write_b32 v156, v225
	s_waitcnt vmcnt(8)
	ds_write_b32 v158, v226
	s_waitcnt vmcnt(7)
	ds_write_b32 v160, v227
	s_waitcnt vmcnt(6)
	ds_write_b32 v162, v228
	s_waitcnt vmcnt(5)
	ds_write_b32 v164, v229
	s_waitcnt vmcnt(4)
	ds_write_b32 v166, v230
	s_waitcnt vmcnt(3)
	ds_write_b32 v168, v231
	s_waitcnt vmcnt(2)
	ds_write_b32 v182, v232
	s_waitcnt vmcnt(1)
	ds_write_b32 v184, v233
	s_waitcnt vmcnt(0)
	ds_write_b32 v186, v234
	s_lshl_b32 s11, s3, 6
	s_and_b32 s9, s9, 0x60
	s_and_b32 s11, s11, 0x700
	s_or_b32 s11, s11, s9
	s_waitcnt lgkmcnt(0)
	s_mov_b32 s9, s41
	s_lshl_b64 s[8:9], s[8:9], 1
	s_add_u32 s8, s4, s8
	ds_read2_b32 v[6:7], v60 offset0:33 offset1:41
	ds_read2_b32 v[8:9], v60 offset1:8
	ds_read2_b32 v[10:11], v60 offset0:66 offset1:74
	ds_read2_b32 v[12:13], v60 offset0:99 offset1:107
	ds_read2_b32 v[14:15], v60 offset0:132 offset1:140
	ds_read2_b32 v[16:17], v60 offset0:165 offset1:173
	ds_read2_b32 v[18:19], v60 offset0:198 offset1:206
	ds_read2_b32 v[20:21], v60 offset0:231 offset1:239
	s_addc_u32 s9, s5, s9
	v_lshlrev_b32_e32 v30, 1, v38
	v_lshl_add_u64 v[2:3], s[8:9], 0, v[30:31]
	v_lshl_add_u64 v[22:23], v[2:3], 0, s[54:55]
	s_waitcnt lgkmcnt(6)
	v_cvt_pk_bf16_f32 v2, v8, v6
	v_or_b32_e32 v6, s11, v59
	v_lshlrev_b32_e32 v30, 11, v6
	s_waitcnt lgkmcnt(4)
	v_cvt_pk_bf16_f32 v3, v10, v12
	s_waitcnt lgkmcnt(2)
	v_cvt_pk_bf16_f32 v4, v14, v16
	s_waitcnt lgkmcnt(0)
	v_cvt_pk_bf16_f32 v5, v18, v20
	v_lshl_add_u64 v[24:25], v[22:23], 0, v[30:31]
	global_store_dwordx4 v[24:25], v[2:5], off
	v_or_b32_e32 v6, s11, v61
	v_lshlrev_b32_e32 v30, 11, v6
	v_cvt_pk_bf16_f32 v2, v9, v7
	v_cvt_pk_bf16_f32 v3, v11, v13
	v_cvt_pk_bf16_f32 v4, v15, v17
	v_cvt_pk_bf16_f32 v5, v19, v21
	ds_read2_b32 v[8:9], v60 offset0:49 offset1:57
	ds_read2_b32 v[10:11], v60 offset0:16 offset1:24
	ds_read2_b32 v[12:13], v60 offset0:82 offset1:90
	ds_read2_b32 v[14:15], v60 offset0:115 offset1:123
	ds_read2_b32 v[16:17], v60 offset0:148 offset1:156
	ds_read2_b32 v[18:19], v60 offset0:181 offset1:189
	ds_read2_b32 v[20:21], v60 offset0:214 offset1:222
	ds_read2_b32 v[24:25], v60 offset0:247 offset1:255
	v_lshl_add_u64 v[6:7], v[22:23], 0, v[30:31]
	global_store_dwordx4 v[6:7], v[2:5], off
	v_or_b32_e32 v6, s11, v62
	v_lshlrev_b32_e32 v30, 11, v6
	s_waitcnt lgkmcnt(6)
	v_cvt_pk_bf16_f32 v2, v10, v8
	s_waitcnt lgkmcnt(4)
	v_cvt_pk_bf16_f32 v3, v12, v14
	s_waitcnt lgkmcnt(2)
	v_cvt_pk_bf16_f32 v4, v16, v18
	s_waitcnt lgkmcnt(0)
	v_cvt_pk_bf16_f32 v5, v20, v24
	v_lshl_add_u64 v[6:7], v[22:23], 0, v[30:31]
	global_store_dwordx4 v[6:7], v[2:5], off
	v_or_b32_e32 v6, s11, v63
	v_lshlrev_b32_e32 v30, 11, v6
	v_cvt_pk_bf16_f32 v2, v11, v9
	v_cvt_pk_bf16_f32 v3, v13, v15
	v_cvt_pk_bf16_f32 v4, v17, v19
	v_cvt_pk_bf16_f32 v5, v21, v25
	v_lshl_add_u64 v[6:7], v[22:23], 0, v[30:31]
	global_store_dwordx4 v[6:7], v[2:5], off
	s_waitcnt lgkmcnt(0)

; #define LAS __attribute__((address_space(3)))
; #define LDS_WAIT() asm volatile("s_waitcnt lgkmcnt(0)" ::: "memory")
; __device__ __forceinline__ void transpose_item(const float* W, int N, bf16_t* WT, int ldw, int drow0, int dk0, LAS float* scr, int k0, int n0, int lane) {
; #pragma unroll 8
;     for (int i = 0; i < 32; ++i) { const int kk = 2 * i + (lane >> 5); scr[kk * 33 + (lane & 31)] = W[(size_t)(k0 + kk) * N + n0 + (lane & 31)]; }
;     LDS_WAIT(); asm volatile("" ::: "memory");
.LBB0_70:
	s_lshl_b32 s15, s13, 1
	s_lshl_b32 s16, s8, 1
	v_or_b32_e32 v30, s15, v1
	v_or_b32_e32 v41, s16, v32
	s_add_i32 s17, s15, 4
	s_add_i32 s18, s16, 4
	s_add_i32 s19, s15, 8
	s_add_i32 s20, s16, 8
	s_add_i32 s21, s15, 12
	s_add_i32 s22, s16, 12
	s_add_i32 s23, s15, 16
	s_add_i32 s26, s16, 16
	s_add_i32 s27, s15, 20
	s_add_i32 s34, s16, 20
	s_add_i32 s35, s15, 24
	s_add_i32 s40, s16, 24
	s_add_i32 s15, s15, 28
	s_add_i32 s16, s16, 28
	v_add_u32_e32 v4, s9, v41
	v_or_b32_e32 v48, s17, v1
	v_or_b32_e32 v49, s18, v32
	v_or_b32_e32 v50, s19, v1
	v_or_b32_e32 v51, s20, v32
	v_or_b32_e32 v52, s21, v1
	v_or_b32_e32 v53, s22, v32
	v_or_b32_e32 v54, s23, v1
	v_or_b32_e32 v55, s26, v32
	v_or_b32_e32 v56, s27, v1
	v_or_b32_e32 v57, s34, v32
	v_or_b32_e32 v71, s35, v1
	v_or_b32_e32 v76, s40, v32
	v_or_b32_e32 v77, s15, v1
	v_or_b32_e32 v78, s16, v32
	v_add_u32_e32 v6, s12, v30
	v_mad_u64_u32 v[4:5], s[16:17], v4, s83, v[2:3]
	v_add_u32_e32 v10, s12, v48
	v_add_u32_e32 v8, s9, v49
	v_add_u32_e32 v14, s12, v50
	v_add_u32_e32 v12, s9, v51
	v_add_u32_e32 v18, s12, v52
	v_add_u32_e32 v16, s9, v53
	v_add_u32_e32 v22, s12, v54
	v_add_u32_e32 v20, s9, v55
	v_add_u32_e32 v26, s12, v56
	v_add_u32_e32 v24, s9, v57
	v_add_u32_e32 v42, s12, v71
	v_add_u32_e32 v28, s9, v76
	v_add_u32_e32 v46, s12, v77
	v_add_u32_e32 v44, s9, v78
	v_mad_u64_u32 v[6:7], s[16:17], v6, s83, v[2:3]
	v_mad_u64_u32 v[8:9], s[16:17], v8, s83, v[2:3]
	v_mad_u64_u32 v[10:11], s[16:17], v10, s83, v[2:3]
	v_mad_u64_u32 v[12:13], s[16:17], v12, s83, v[2:3]
	v_mad_u64_u32 v[14:15], s[16:17], v14, s83, v[2:3]
	v_mad_u64_u32 v[16:17], s[16:17], v16, s83, v[2:3]
	v_mad_u64_u32 v[18:19], s[16:17], v18, s83, v[2:3]
	v_mad_u64_u32 v[20:21], s[16:17], v20, s83, v[2:3]
	v_mad_u64_u32 v[22:23], s[16:17], v22, s83, v[2:3]
	v_mad_u64_u32 v[24:25], s[16:17], v24, s83, v[2:3]
	v_mad_u64_u32 v[26:27], s[16:17], v26, s83, v[2:3]
	v_mad_u64_u32 v[28:29], s[16:17], v28, s83, v[2:3]
	v_mad_u64_u32 v[42:43], s[16:17], v42, s83, v[2:3]
	v_mad_u64_u32 v[44:45], s[16:17], v44, s83, v[2:3]
	v_mad_u64_u32 v[46:47], s[16:17], v46, s83, v[2:3]
	global_load_dword v79, v[4:5], off nt
	global_load_dword v80, v[6:7], off nt
	global_load_dword v81, v[8:9], off nt
	global_load_dword v82, v[10:11], off nt
	global_load_dword v83, v[12:13], off nt
	global_load_dword v84, v[14:15], off nt
	global_load_dword v85, v[16:17], off nt
	global_load_dword v86, v[18:19], off nt
	global_load_dword v87, v[20:21], off nt
	global_load_dword v88, v[22:23], off nt
	global_load_dword v89, v[24:25], off nt
	global_load_dword v90, v[26:27], off nt
	global_load_dword v91, v[28:29], off nt
	global_load_dword v92, v[42:43], off nt
	global_load_dword v93, v[44:45], off nt
	global_load_dword v94, v[46:47], off nt
	s_add_i32 s8, s8, 16
	s_add_i32 s13, s13, 16
	s_add_i32 s14, s14, -16
	s_lshl_b32 s15, s13, 1
	s_lshl_b32 s16, s8, 1
	v_or_b32_e32 v170, s15, v1
	v_or_b32_e32 v181, s16, v32
	s_add_i32 s17, s15, 4
	s_add_i32 s18, s16, 4
	s_add_i32 s19, s15, 8
	s_add_i32 s20, s16, 8
	s_add_i32 s21, s15, 12
	s_add_i32 s22, s16, 12
	s_add_i32 s23, s15, 16
	s_add_i32 s26, s16, 16
	s_add_i32 s27, s15, 20
	s_add_i32 s34, s16, 20
	s_add_i32 s35, s15, 24
	s_add_i32 s40, s16, 24
	s_add_i32 s15, s15, 28
	s_add_i32 s16, s16, 28
	v_add_u32_e32 v144, s9, v181
	v_or_b32_e32 v188, s17, v1
	v_or_b32_e32 v189, s18, v32
	v_or_b32_e32 v190, s19, v1
	v_or_b32_e32 v191, s20, v32
	v_or_b32_e32 v192, s21, v1
	v_or_b32_e32 v193, s22, v32
	v_or_b32_e32 v194, s23, v1
	v_or_b32_e32 v195, s26, v32
	v_or_b32_e32 v196, s27, v1
	v_or_b32_e32 v197, s34, v32
	v_or_b32_e32 v211, s35, v1
	v_or_b32_e32 v216, s40, v32
	v_or_b32_e32 v217, s15, v1
	v_or_b32_e32 v218, s16, v32
	v_add_u32_e32 v146, s12, v170
	v_mad_u64_u32 v[144:145], s[16:17], v144, s83, v[2:3]
	v_add_u32_e32 v150, s12, v188
	v_add_u32_e32 v148, s9, v189
	v_add_u32_e32 v154, s12, v190
	v_add_u32_e32 v152, s9, v191
	v_add_u32_e32 v158, s12, v192
	v_add_u32_e32 v156, s9, v193
	v_add_u32_e32 v162, s12, v194
	v_add_u32_e32 v160, s9, v195
	v_add_u32_e32 v166, s12, v196
	v_add_u32_e32 v164, s9, v197
	v_add_u32_e32 v182, s12, v211
	v_add_u32_e32 v168, s9, v216
	v_add_u32_e32 v186, s12, v217
	v_add_u32_e32 v184, s9, v218
	v_mad_u64_u32 v[146:147], s[16:17], v146, s83, v[2:3]
	v_mad_u64_u32 v[148:149], s[16:17], v148, s83, v[2:3]
	v_mad_u64_u32 v[150:151], s[16:17], v150, s83, v[2:3]
	v_mad_u64_u32 v[152:153], s[16:17], v152, s83, v[2:3]
	v_mad_u64_u32 v[154:155], s[16:17], v154, s83, v[2:3]
	v_mad_u64_u32 v[156:157], s[16:17], v156, s83, v[2:3]
	v_mad_u64_u32 v[158:159], s[16:17], v158, s83, v[2:3]
	v_mad_u64_u32 v[160:161], s[16:17], v160, s83, v[2:3]
	v_mad_u64_u32 v[162:163], s[16:17], v162, s83, v[2:3]
	v_mad_u64_u32 v[164:165], s[16:17], v164, s83, v[2:3]
	v_mad_u64_u32 v[166:167], s[16:17], v166, s83, v[2:3]
	v_mad_u64_u32 v[168:169], s[16:17], v168, s83, v[2:3]
	v_mad_u64_u32 v[182:183], s[16:17], v182, s83, v[2:3]
	v_mad_u64_u32 v[184:185], s[16:17], v184, s83, v[2:3]
	v_mad_u64_u32 v[186:187], s[16:17], v186, s83, v[2:3]
	global_load_dword v219, v[144:145], off nt
	global_load_dword v220, v[146:147], off nt
	global_load_dword v221, v[148:149], off nt
	global_load_dword v222, v[150:151], off nt
	global_load_dword v223, v[152:153], off nt
	global_load_dword v224, v[154:155], off nt
	global_load_dword v225, v[156:157], off nt
	global_load_dword v226, v[158:159], off nt
	global_load_dword v227, v[160:161], off nt
	global_load_dword v228, v[162:163], off nt
	global_load_dword v229, v[164:165], off nt
	global_load_dword v230, v[166:167], off nt
	global_load_dword v231, v[168:169], off nt
	global_load_dword v232, v[182:183], off nt
	global_load_dword v233, v[184:185], off nt
	global_load_dword v234, v[186:187], off nt
	v_mad_u64_u32 v[4:5], s[16:17], v41, s67, v[36:37]
	v_mad_u64_u32 v[6:7], s[16:17], v30, s67, v[36:37]
	v_mad_u64_u32 v[8:9], s[16:17], v49, s67, v[36:37]
	v_mad_u64_u32 v[10:11], s[16:17], v48, s67, v[36:37]
	v_mad_u64_u32 v[12:13], s[16:17], v51, s67, v[36:37]
	v_mad_u64_u32 v[14:15], s[16:17], v50, s67, v[36:37]
	v_mad_u64_u32 v[16:17], s[16:17], v53, s67, v[36:37]
	v_mad_u64_u32 v[18:19], s[16:17], v52, s67, v[36:37]
	v_mad_u64_u32 v[20:21], s[16:17], v55, s67, v[36:37]
	v_mad_u64_u32 v[22:23], s[16:17], v54, s67, v[36:37]
	v_mad_u64_u32 v[24:25], s[16:17], v57, s67, v[36:37]
	v_mad_u64_u32 v[26:27], s[16:17], v56, s67, v[36:37]
	v_mad_u64_u32 v[28:29], s[16:17], v76, s67, v[36:37]
	v_mad_u64_u32 v[42:43], s[16:17], v71, s67, v[36:37]
	v_mad_u64_u32 v[44:45], s[16:17], v78, s67, v[36:37]
	v_mad_u64_u32 v[46:47], s[16:17], v77, s67, v[36:37]
	s_waitcnt vmcnt(31)
; #define LAS __attribute__((address_space(3)))
; __device__ __forceinline__ unsigned cvtpk_s(float lo, float hi) { f32x2_t v = {lo, hi}; bf16x2_t b = __builtin_convertvector(v, bf16x2_t); return __builtin_bit_cast(unsigned, b); }
; #define LDS_WAIT() asm volatile("s_waitcnt lgkmcnt(0)" ::: "memory")
; __device__ __forceinline__ void transpose_item(const float* W, int N, bf16_t* WT, int ldw, int drow0, int dk0, LAS float* scr, int k0, int n0, int lane) {
;     ...
;     for (int i = 0; i < 32; ++i) { const int kk = 2 * i + (lane >> 5); scr[kk * 33 + (lane & 31)] = W[(size_t)(k0 + kk) * N + n0 + (lane & 31)]; }
;     LDS_WAIT(); asm volatile("" ::: "memory");
;     const int c = lane & 7;
; #pragma unroll
;     for (int j = 0; j < 4; ++j) { const int n = (lane >> 3) + 8 * j; const LAS float* s = scr + (8 * c) * 33 + n;
;         u32x4 o; o.x = cvtpk_s(s[0 * 33], s[1 * 33]); o.y = cvtpk_s(s[2 * 33], s[3 * 33]); o.z = cvtpk_s(s[4 * 33], s[5 * 33]); o.w = cvtpk_s(s[6 * 33], s[7 * 33]);
;         *(u32x4*)(WT + (size_t)(drow0 + n) * ldw + dk0 + k0 + 8 * c) = o; }
;     LDS_WAIT(); asm volatile("" ::: "memory");
	ds_write_b32 v4, v79
	s_waitcnt vmcnt(30)
	ds_write_b32 v6, v80
	s_waitcnt vmcnt(29)
	ds_write_b32 v8, v81
	s_waitcnt vmcnt(28)
	ds_write_b32 v10, v82
	s_waitcnt vmcnt(27)
	ds_write_b32 v12, v83
	s_waitcnt vmcnt(26)
	ds_write_b32 v14, v84
	s_waitcnt vmcnt(25)
	ds_write_b32 v16, v85
	s_waitcnt vmcnt(24)
	ds_write_b32 v18, v86
	s_waitcnt vmcnt(23)
	ds_write_b32 v20, v87
	s_waitcnt vmcnt(22)
	ds_write_b32 v22, v88
	s_waitcnt vmcnt(21)
	ds_write_b32 v24, v89
	s_waitcnt vmcnt(20)
	ds_write_b32 v26, v90
	s_waitcnt vmcnt(19)
	ds_write_b32 v28, v91
	s_waitcnt vmcnt(18)
	ds_write_b32 v42, v92
	s_waitcnt vmcnt(17)
	ds_write_b32 v44, v93
	s_waitcnt vmcnt(16)
	ds_write_b32 v46, v94
	s_add_i32 s8, s8, 16
	s_add_i32 s13, s13, 16
	s_add_i32 s14, s14, -16
	v_mad_u64_u32 v[144:145], s[16:17], v181, s67, v[36:37]
	v_mad_u64_u32 v[146:147], s[16:17], v170, s67, v[36:37]
	v_mad_u64_u32 v[148:149], s[16:17], v189, s67, v[36:37]
	v_mad_u64_u32 v[150:151], s[16:17], v188, s67, v[36:37]
	v_mad_u64_u32 v[152:153], s[16:17], v191, s67, v[36:37]
	v_mad_u64_u32 v[154:155], s[16:17], v190, s67, v[36:37]
	v_mad_u64_u32 v[156:157], s[16:17], v193, s67, v[36:37]
	v_mad_u64_u32 v[158:159], s[16:17], v192, s67, v[36:37]
	v_mad_u64_u32 v[160:161], s[16:17], v195, s67, v[36:37]
	v_mad_u64_u32 v[162:163], s[16:17], v194, s67, v[36:37]
	v_mad_u64_u32 v[164:165], s[16:17], v197, s67, v[36:37]
	v_mad_u64_u32 v[166:167], s[16:17], v196, s67, v[36:37]
	v_mad_u64_u32 v[168:169], s[16:17], v216, s67, v[36:37]
	v_mad_u64_u32 v[182:183], s[16:17], v211, s67, v[36:37]
	v_mad_u64_u32 v[184:185], s[16:17], v218, s67, v[36:37]
	v_mad_u64_u32 v[186:187], s[16:17], v217, s67, v[36:37]
	s_waitcnt vmcnt(15)
	ds_write_b32 v144, v219
	s_waitcnt vmcnt(14)
	ds_write_b32 v146, v220
	s_waitcnt vmcnt(13)
	ds_write_b32 v148, v221
	s_waitcnt vmcnt(12)
	ds_write_b32 v150, v222
	s_waitcnt vmcnt(11)
	ds_write_b32 v152, v223
	s_waitcnt vmcnt(10)
	ds_write_b32 v154, v224
	s_waitcnt vmcnt(9)
	ds_write_b32 v156, v225
	s_waitcnt vmcnt(8)
	ds_write_b32 v158, v226
	s_waitcnt vmcnt(7)
	ds_write_b32 v160, v227
	s_waitcnt vmcnt(6)
	ds_write_b32 v162, v228
	s_waitcnt vmcnt(5)
	ds_write_b32 v164, v229
	s_waitcnt vmcnt(4)
	ds_write_b32 v166, v230
	s_waitcnt vmcnt(3)
	ds_write_b32 v168, v231
	s_waitcnt vmcnt(2)
	ds_write_b32 v182, v232
	s_waitcnt vmcnt(1)
	ds_write_b32 v184, v233
	s_waitcnt vmcnt(0)
	ds_write_b32 v186, v234
	s_waitcnt lgkmcnt(0)
	s_and_b32 s8, 0xffff, s9
	s_and_b32 s11, 0xffff, s11
	s_lshl_b32 s8, s8, 1
	s_add_u32 s8, s4, s8
	ds_read2_b32 v[6:7], v60 offset0:33 offset1:41
	ds_read2_b32 v[8:9], v60 offset1:8
	ds_read2_b32 v[10:11], v60 offset0:66 offset1:74
	ds_read2_b32 v[12:13], v60 offset0:99 offset1:107
	ds_read2_b32 v[14:15], v60 offset0:132 offset1:140
	ds_read2_b32 v[16:17], v60 offset0:165 offset1:173
	ds_read2_b32 v[18:19], v60 offset0:198 offset1:206
	ds_read2_b32 v[20:21], v60 offset0:231 offset1:239
	s_addc_u32 s9, s5, 0
	v_lshlrev_b32_e32 v30, 1, v38
	v_lshl_add_u64 v[2:3], s[8:9], 0, v[30:31]
	v_lshl_add_u64 v[22:23], v[2:3], 0, s[56:57]
	s_waitcnt lgkmcnt(6)
	v_cvt_pk_bf16_f32 v2, v8, v6
	v_or_b32_e32 v6, s11, v59
	v_lshlrev_b32_e32 v30, 11, v6
	s_waitcnt lgkmcnt(4)
	v_cvt_pk_bf16_f32 v3, v10, v12
	s_waitcnt lgkmcnt(2)
	v_cvt_pk_bf16_f32 v4, v14, v16
	s_waitcnt lgkmcnt(0)
	v_cvt_pk_bf16_f32 v5, v18, v20
	v_lshl_add_u64 v[24:25], v[22:23], 0, v[30:31]
	global_store_dwordx4 v[24:25], v[2:5], off
	v_or_b32_e32 v6, s11, v61
	v_lshlrev_b32_e32 v30, 11, v6
	v_cvt_pk_bf16_f32 v2, v9, v7
	v_cvt_pk_bf16_f32 v3, v11, v13
	v_cvt_pk_bf16_f32 v4, v15, v17
	v_cvt_pk_bf16_f32 v5, v19, v21
	ds_read2_b32 v[8:9], v60 offset0:49 offset1:57
	ds_read2_b32 v[10:11], v60 offset0:16 offset1:24
	ds_read2_b32 v[12:13], v60 offset0:82 offset1:90
	ds_read2_b32 v[14:15], v60 offset0:115 offset1:123
	ds_read2_b32 v[16:17], v60 offset0:148 offset1:156
	ds_read2_b32 v[18:19], v60 offset0:181 offset1:189
	ds_read2_b32 v[20:21], v60 offset0:214 offset1:222
	ds_read2_b32 v[24:25], v60 offset0:247 offset1:255
	v_lshl_add_u64 v[6:7], v[22:23], 0, v[30:31]
	global_store_dwordx4 v[6:7], v[2:5], off
	v_or_b32_e32 v6, s11, v62
	v_lshlrev_b32_e32 v30, 11, v6
	s_waitcnt lgkmcnt(6)
	v_cvt_pk_bf16_f32 v2, v10, v8
	s_waitcnt lgkmcnt(4)
	v_cvt_pk_bf16_f32 v3, v12, v14
	s_waitcnt lgkmcnt(2)
	v_cvt_pk_bf16_f32 v4, v16, v18
	s_waitcnt lgkmcnt(0)
	v_cvt_pk_bf16_f32 v5, v20, v24
	v_lshl_add_u64 v[6:7], v[22:23], 0, v[30:31]
	global_store_dwordx4 v[6:7], v[2:5], off
	v_or_b32_e32 v6, s11, v63
	v_lshlrev_b32_e32 v30, 11, v6
	v_cvt_pk_bf16_f32 v2, v11, v9
	v_cvt_pk_bf16_f32 v3, v13, v15
	v_cvt_pk_bf16_f32 v4, v17, v19
	v_cvt_pk_bf16_f32 v5, v21, v25
	v_lshl_add_u64 v[6:7], v[22:23], 0, v[30:31]
	global_store_dwordx4 v[6:7], v[2:5], off
	s_waitcnt lgkmcnt(0)

; #define LAS __attribute__((address_space(3)))
; #define LDS_WAIT() asm volatile("s_waitcnt lgkmcnt(0)" ::: "memory")
; __device__ __forceinline__ void transpose_item(const float* W, int N, bf16_t* WT, int ldw, int drow0, int dk0, LAS float* scr, int k0, int n0, int lane) {
; #pragma unroll 8
;     for (int i = 0; i < 32; ++i) { const int kk = 2 * i + (lane >> 5); scr[kk * 33 + (lane & 31)] = W[(size_t)(k0 + kk) * N + n0 + (lane & 31)]; }
;     LDS_WAIT(); asm volatile("" ::: "memory");
.LBB0_75:
	s_lshl_b32 s15, s12, 1
	s_lshl_b32 s16, s9, 1
	v_or_b32_e32 v30, s15, v1
	v_or_b32_e32 v41, s16, v32
	s_add_i32 s17, s15, 4
	s_add_i32 s18, s16, 4
	s_add_i32 s19, s15, 8
	s_add_i32 s20, s16, 8
	s_add_i32 s21, s15, 12
	s_add_i32 s22, s16, 12
	s_add_i32 s23, s15, 16
	s_add_i32 s26, s16, 16
	s_add_i32 s27, s15, 20
	s_add_i32 s34, s16, 20
	s_add_i32 s35, s15, 24
	s_add_i32 s40, s16, 24
	s_add_i32 s15, s15, 28
	s_add_i32 s16, s16, 28
	v_add_u32_e32 v6, s8, v41
	v_or_b32_e32 v48, s17, v1
	v_or_b32_e32 v49, s18, v32
	v_or_b32_e32 v50, s19, v1
	v_or_b32_e32 v51, s20, v32
	v_or_b32_e32 v52, s21, v1
	v_or_b32_e32 v53, s22, v32
	v_or_b32_e32 v54, s23, v1
	v_or_b32_e32 v55, s26, v32
	v_or_b32_e32 v56, s27, v1
	v_or_b32_e32 v57, s34, v32
	v_or_b32_e32 v71, s35, v1
	v_or_b32_e32 v76, s40, v32
	v_or_b32_e32 v77, s15, v1
	v_or_b32_e32 v78, s16, v32
	v_add_u32_e32 v4, s13, v30
	v_ashrrev_i32_e32 v7, 31, v6
	v_add_u32_e32 v8, s13, v48
	v_add_u32_e32 v10, s8, v49
	v_add_u32_e32 v12, s13, v50
	v_add_u32_e32 v14, s8, v51
	v_add_u32_e32 v16, s13, v52
	v_add_u32_e32 v18, s8, v53
	v_add_u32_e32 v20, s13, v54
	v_add_u32_e32 v22, s8, v55
	v_add_u32_e32 v24, s13, v56
	v_add_u32_e32 v26, s8, v57
	v_add_u32_e32 v28, s13, v71
	v_add_u32_e32 v42, s8, v76
	v_add_u32_e32 v44, s13, v77
	v_add_u32_e32 v46, s8, v78
	v_ashrrev_i32_e32 v5, 31, v4
	v_lshlrev_b64 v[6:7], 12, v[6:7]
	v_ashrrev_i32_e32 v11, 31, v10
	v_ashrrev_i32_e32 v9, 31, v8
	v_ashrrev_i32_e32 v15, 31, v14
	v_ashrrev_i32_e32 v13, 31, v12
	v_ashrrev_i32_e32 v19, 31, v18
	v_ashrrev_i32_e32 v17, 31, v16
	v_ashrrev_i32_e32 v23, 31, v22
	v_ashrrev_i32_e32 v21, 31, v20
	v_ashrrev_i32_e32 v27, 31, v26
	v_ashrrev_i32_e32 v25, 31, v24
	v_ashrrev_i32_e32 v43, 31, v42
	v_ashrrev_i32_e32 v29, 31, v28
	v_ashrrev_i32_e32 v47, 31, v46
	v_ashrrev_i32_e32 v45, 31, v44
	v_lshlrev_b64 v[4:5], 12, v[4:5]
	v_lshl_add_u64 v[6:7], v[2:3], 0, v[6:7]
	v_lshlrev_b64 v[8:9], 12, v[8:9]
	v_lshlrev_b64 v[10:11], 12, v[10:11]
	v_lshlrev_b64 v[12:13], 12, v[12:13]
	v_lshlrev_b64 v[14:15], 12, v[14:15]
	v_lshlrev_b64 v[16:17], 12, v[16:17]
	v_lshlrev_b64 v[18:19], 12, v[18:19]
	v_lshlrev_b64 v[20:21], 12, v[20:21]
	v_lshlrev_b64 v[22:23], 12, v[22:23]
	v_lshlrev_b64 v[24:25], 12, v[24:25]
	v_lshlrev_b64 v[26:27], 12, v[26:27]
	v_lshlrev_b64 v[28:29], 12, v[28:29]
	v_lshlrev_b64 v[42:43], 12, v[42:43]
	v_lshlrev_b64 v[44:45], 12, v[44:45]
	v_lshlrev_b64 v[46:47], 12, v[46:47]
	v_lshl_add_u64 v[4:5], v[2:3], 0, v[4:5]
	v_lshl_add_u64 v[10:11], v[2:3], 0, v[10:11]
	v_lshl_add_u64 v[8:9], v[2:3], 0, v[8:9]
	v_lshl_add_u64 v[14:15], v[2:3], 0, v[14:15]
	v_lshl_add_u64 v[12:13], v[2:3], 0, v[12:13]
	v_lshl_add_u64 v[18:19], v[2:3], 0, v[18:19]
	v_lshl_add_u64 v[16:17], v[2:3], 0, v[16:17]
	v_lshl_add_u64 v[22:23], v[2:3], 0, v[22:23]
	v_lshl_add_u64 v[20:21], v[2:3], 0, v[20:21]
	v_lshl_add_u64 v[26:27], v[2:3], 0, v[26:27]
	v_lshl_add_u64 v[24:25], v[2:3], 0, v[24:25]
	v_lshl_add_u64 v[42:43], v[2:3], 0, v[42:43]
	v_lshl_add_u64 v[28:29], v[2:3], 0, v[28:29]
	v_lshl_add_u64 v[46:47], v[2:3], 0, v[46:47]
	v_lshl_add_u64 v[44:45], v[2:3], 0, v[44:45]
	global_load_dword v79, v[6:7], off nt
	global_load_dword v80, v[4:5], off nt
	global_load_dword v81, v[10:11], off nt
	global_load_dword v82, v[8:9], off nt
	global_load_dword v83, v[14:15], off nt
	global_load_dword v84, v[12:13], off nt
	global_load_dword v85, v[18:19], off nt
	global_load_dword v86, v[16:17], off nt
	global_load_dword v87, v[22:23], off nt
	global_load_dword v88, v[20:21], off nt
	global_load_dword v89, v[26:27], off nt
	global_load_dword v90, v[24:25], off nt
	global_load_dword v91, v[42:43], off nt
	global_load_dword v92, v[28:29], off nt
	global_load_dword v93, v[46:47], off nt
	global_load_dword v94, v[44:45], off nt
	s_add_i32 s9, s9, 16
	s_add_i32 s12, s12, 16
	s_add_i32 s14, s14, -16
	s_lshl_b32 s15, s12, 1
	s_lshl_b32 s16, s9, 1
	v_or_b32_e32 v170, s15, v1
	v_or_b32_e32 v181, s16, v32
	s_add_i32 s17, s15, 4
	s_add_i32 s18, s16, 4
	s_add_i32 s19, s15, 8
	s_add_i32 s20, s16, 8
	s_add_i32 s21, s15, 12
	s_add_i32 s22, s16, 12
	s_add_i32 s23, s15, 16
	s_add_i32 s26, s16, 16
	s_add_i32 s27, s15, 20
	s_add_i32 s34, s16, 20
	s_add_i32 s35, s15, 24
	s_add_i32 s40, s16, 24
	s_add_i32 s15, s15, 28
	s_add_i32 s16, s16, 28
	v_add_u32_e32 v146, s8, v181
	v_or_b32_e32 v188, s17, v1
	v_or_b32_e32 v189, s18, v32
	v_or_b32_e32 v190, s19, v1
	v_or_b32_e32 v191, s20, v32
	v_or_b32_e32 v192, s21, v1
	v_or_b32_e32 v193, s22, v32
	v_or_b32_e32 v194, s23, v1
	v_or_b32_e32 v195, s26, v32
	v_or_b32_e32 v196, s27, v1
	v_or_b32_e32 v197, s34, v32
	v_or_b32_e32 v211, s35, v1
	v_or_b32_e32 v216, s40, v32
	v_or_b32_e32 v217, s15, v1
	v_or_b32_e32 v218, s16, v32
	v_add_u32_e32 v144, s13, v170
	v_ashrrev_i32_e32 v147, 31, v146
	v_add_u32_e32 v148, s13, v188
	v_add_u32_e32 v150, s8, v189
	v_add_u32_e32 v152, s13, v190
	v_add_u32_e32 v154, s8, v191
	v_add_u32_e32 v156, s13, v192
	v_add_u32_e32 v158, s8, v193
	v_add_u32_e32 v160, s13, v194
	v_add_u32_e32 v162, s8, v195
	v_add_u32_e32 v164, s13, v196
	v_add_u32_e32 v166, s8, v197
	v_add_u32_e32 v168, s13, v211
	v_add_u32_e32 v182, s8, v216
	v_add_u32_e32 v184, s13, v217
	v_add_u32_e32 v186, s8, v218
	v_ashrrev_i32_e32 v145, 31, v144
	v_lshlrev_b64 v[146:147], 12, v[146:147]
	v_ashrrev_i32_e32 v151, 31, v150
	v_ashrrev_i32_e32 v149, 31, v148
	v_ashrrev_i32_e32 v155, 31, v154
	v_ashrrev_i32_e32 v153, 31, v152
	v_ashrrev_i32_e32 v159, 31, v158
	v_ashrrev_i32_e32 v157, 31, v156
	v_ashrrev_i32_e32 v163, 31, v162
	v_ashrrev_i32_e32 v161, 31, v160
	v_ashrrev_i32_e32 v167, 31, v166
	v_ashrrev_i32_e32 v165, 31, v164
	v_ashrrev_i32_e32 v183, 31, v182
; #define LAS __attribute__((address_space(3)))
; #define LDS_WAIT() asm volatile("s_waitcnt lgkmcnt(0)" ::: "memory")
; __device__ __forceinline__ void transpose_item(const float* W, int N, bf16_t* WT, int ldw, int drow0, int dk0, LAS float* scr, int k0, int n0, int lane) {
; #pragma unroll 8
;     for (int i = 0; i < 32; ++i) { const int kk = 2 * i + (lane >> 5); scr[kk * 33 + (lane & 31)] = W[(size_t)(k0 + kk) * N + n0 + (lane & 31)]; }
;     LDS_WAIT(); asm volatile("" ::: "memory");
	v_ashrrev_i32_e32 v169, 31, v168
	v_ashrrev_i32_e32 v187, 31, v186
	v_ashrrev_i32_e32 v185, 31, v184
	v_lshlrev_b64 v[144:145], 12, v[144:145]
	v_lshl_add_u64 v[146:147], v[2:3], 0, v[146:147]
	v_lshlrev_b64 v[148:149], 12, v[148:149]
	v_lshlrev_b64 v[150:151], 12, v[150:151]
	v_lshlrev_b64 v[152:153], 12, v[152:153]
	v_lshlrev_b64 v[154:155], 12, v[154:155]
	v_lshlrev_b64 v[156:157], 12, v[156:157]
	v_lshlrev_b64 v[158:159], 12, v[158:159]
	v_lshlrev_b64 v[160:161], 12, v[160:161]
	v_lshlrev_b64 v[162:163], 12, v[162:163]
	v_lshlrev_b64 v[164:165], 12, v[164:165]
	v_lshlrev_b64 v[166:167], 12, v[166:167]
	v_lshlrev_b64 v[168:169], 12, v[168:169]
	v_lshlrev_b64 v[182:183], 12, v[182:183]
	v_lshlrev_b64 v[184:185], 12, v[184:185]
	v_lshlrev_b64 v[186:187], 12, v[186:187]
	v_lshl_add_u64 v[144:145], v[2:3], 0, v[144:145]
	v_lshl_add_u64 v[150:151], v[2:3], 0, v[150:151]
	v_lshl_add_u64 v[148:149], v[2:3], 0, v[148:149]
	v_lshl_add_u64 v[154:155], v[2:3], 0, v[154:155]
	v_lshl_add_u64 v[152:153], v[2:3], 0, v[152:153]
	v_lshl_add_u64 v[158:159], v[2:3], 0, v[158:159]
	v_lshl_add_u64 v[156:157], v[2:3], 0, v[156:157]
	v_lshl_add_u64 v[162:163], v[2:3], 0, v[162:163]
	v_lshl_add_u64 v[160:161], v[2:3], 0, v[160:161]
	v_lshl_add_u64 v[166:167], v[2:3], 0, v[166:167]
	v_lshl_add_u64 v[164:165], v[2:3], 0, v[164:165]
	v_lshl_add_u64 v[182:183], v[2:3], 0, v[182:183]
	v_lshl_add_u64 v[168:169], v[2:3], 0, v[168:169]
	v_lshl_add_u64 v[186:187], v[2:3], 0, v[186:187]
	v_lshl_add_u64 v[184:185], v[2:3], 0, v[184:185]
	global_load_dword v219, v[146:147], off nt
	global_load_dword v220, v[144:145], off nt
	global_load_dword v221, v[150:151], off nt
	global_load_dword v222, v[148:149], off nt
	global_load_dword v223, v[154:155], off nt
	global_load_dword v224, v[152:153], off nt
	global_load_dword v225, v[158:159], off nt
	global_load_dword v226, v[156:157], off nt
	global_load_dword v227, v[162:163], off nt
	global_load_dword v228, v[160:161], off nt
	global_load_dword v229, v[166:167], off nt
	global_load_dword v230, v[164:165], off nt
	global_load_dword v231, v[182:183], off nt
	global_load_dword v232, v[168:169], off nt
	global_load_dword v233, v[186:187], off nt
	global_load_dword v234, v[184:185], off nt
	v_mad_u64_u32 v[4:5], s[16:17], v41, s67, v[36:37]
	v_mad_u64_u32 v[6:7], s[16:17], v30, s67, v[36:37]
	v_mad_u64_u32 v[8:9], s[16:17], v49, s67, v[36:37]
	v_mad_u64_u32 v[10:11], s[16:17], v48, s67, v[36:37]
	v_mad_u64_u32 v[12:13], s[16:17], v51, s67, v[36:37]
	v_mad_u64_u32 v[14:15], s[16:17], v50, s67, v[36:37]
	v_mad_u64_u32 v[16:17], s[16:17], v53, s67, v[36:37]
	v_mad_u64_u32 v[18:19], s[16:17], v52, s67, v[36:37]
	v_mad_u64_u32 v[20:21], s[16:17], v55, s67, v[36:37]
	v_mad_u64_u32 v[22:23], s[16:17], v54, s67, v[36:37]
	v_mad_u64_u32 v[24:25], s[16:17], v57, s67, v[36:37]
	v_mad_u64_u32 v[26:27], s[16:17], v56, s67, v[36:37]
	v_mad_u64_u32 v[28:29], s[16:17], v76, s67, v[36:37]
	v_mad_u64_u32 v[42:43], s[16:17], v71, s67, v[36:37]
	v_mad_u64_u32 v[44:45], s[16:17], v78, s67, v[36:37]
	v_mad_u64_u32 v[46:47], s[16:17], v77, s67, v[36:37]
	s_waitcnt vmcnt(31)
	ds_write_b32 v4, v79
	s_waitcnt vmcnt(30)
	ds_write_b32 v6, v80
	s_waitcnt vmcnt(29)
	ds_write_b32 v8, v81
	s_waitcnt vmcnt(28)
	ds_write_b32 v10, v82
	s_waitcnt vmcnt(27)
	ds_write_b32 v12, v83
	s_waitcnt vmcnt(26)
	ds_write_b32 v14, v84
	s_waitcnt vmcnt(25)
	ds_write_b32 v16, v85
	s_waitcnt vmcnt(24)
	ds_write_b32 v18, v86
	s_waitcnt vmcnt(23)
	ds_write_b32 v20, v87
	s_waitcnt vmcnt(22)
	ds_write_b32 v22, v88
	s_waitcnt vmcnt(21)
	ds_write_b32 v24, v89
	s_waitcnt vmcnt(20)
	ds_write_b32 v26, v90
	s_waitcnt vmcnt(19)
	ds_write_b32 v28, v91
	s_waitcnt vmcnt(18)
	ds_write_b32 v42, v92
	s_waitcnt vmcnt(17)
	ds_write_b32 v44, v93
	s_waitcnt vmcnt(16)
; #define LAS __attribute__((address_space(3)))
; __device__ __forceinline__ unsigned cvtpk_s(float lo, float hi) { f32x2_t v = {lo, hi}; bf16x2_t b = __builtin_convertvector(v, bf16x2_t); return __builtin_bit_cast(unsigned, b); }
; #define LDS_WAIT() asm volatile("s_waitcnt lgkmcnt(0)" ::: "memory")
; __device__ __forceinline__ void transpose_item(const float* W, int N, bf16_t* WT, int ldw, int drow0, int dk0, LAS float* scr, int k0, int n0, int lane) {
;     ...
;     for (int i = 0; i < 32; ++i) { const int kk = 2 * i + (lane >> 5); scr[kk * 33 + (lane & 31)] = W[(size_t)(k0 + kk) * N + n0 + (lane & 31)]; }
;     LDS_WAIT(); asm volatile("" ::: "memory");
;     const int c = lane & 7;
; #pragma unroll
;     for (int j = 0; j < 4; ++j) { const int n = (lane >> 3) + 8 * j; const LAS float* s = scr + (8 * c) * 33 + n;
;         u32x4 o; o.x = cvtpk_s(s[0 * 33], s[1 * 33]); o.y = cvtpk_s(s[2 * 33], s[3 * 33]); o.z = cvtpk_s(s[4 * 33], s[5 * 33]); o.w = cvtpk_s(s[6 * 33], s[7 * 33]);
;         *(u32x4*)(WT + (size_t)(drow0 + n) * ldw + dk0 + k0 + 8 * c) = o; }
;     LDS_WAIT(); asm volatile("" ::: "memory");
	ds_write_b32 v46, v94
	s_add_i32 s9, s9, 16
	s_add_i32 s12, s12, 16
	s_add_i32 s14, s14, -16
	v_mad_u64_u32 v[144:145], s[16:17], v181, s67, v[36:37]
	v_mad_u64_u32 v[146:147], s[16:17], v170, s67, v[36:37]
	v_mad_u64_u32 v[148:149], s[16:17], v189, s67, v[36:37]
	v_mad_u64_u32 v[150:151], s[16:17], v188, s67, v[36:37]
	v_mad_u64_u32 v[152:153], s[16:17], v191, s67, v[36:37]
	v_mad_u64_u32 v[154:155], s[16:17], v190, s67, v[36:37]
	v_mad_u64_u32 v[156:157], s[16:17], v193, s67, v[36:37]
	v_mad_u64_u32 v[158:159], s[16:17], v192, s67, v[36:37]
	v_mad_u64_u32 v[160:161], s[16:17], v195, s67, v[36:37]
	v_mad_u64_u32 v[162:163], s[16:17], v194, s67, v[36:37]
	v_mad_u64_u32 v[164:165], s[16:17], v197, s67, v[36:37]
	v_mad_u64_u32 v[166:167], s[16:17], v196, s67, v[36:37]
	v_mad_u64_u32 v[168:169], s[16:17], v216, s67, v[36:37]
	v_mad_u64_u32 v[182:183], s[16:17], v211, s67, v[36:37]
	v_mad_u64_u32 v[184:185], s[16:17], v218, s67, v[36:37]
	v_mad_u64_u32 v[186:187], s[16:17], v217, s67, v[36:37]
	s_waitcnt vmcnt(15)
	ds_write_b32 v144, v219
	s_waitcnt vmcnt(14)
	ds_write_b32 v146, v220
	s_waitcnt vmcnt(13)
	ds_write_b32 v148, v221
	s_waitcnt vmcnt(12)
	ds_write_b32 v150, v222
	s_waitcnt vmcnt(11)
	ds_write_b32 v152, v223
	s_waitcnt vmcnt(10)
	ds_write_b32 v154, v224
	s_waitcnt vmcnt(9)
	ds_write_b32 v156, v225
	s_waitcnt vmcnt(8)
	ds_write_b32 v158, v226
	s_waitcnt vmcnt(7)
	ds_write_b32 v160, v227
	s_waitcnt vmcnt(6)
	ds_write_b32 v162, v228
	s_waitcnt vmcnt(5)
	ds_write_b32 v164, v229
	s_waitcnt vmcnt(4)
	ds_write_b32 v166, v230
	s_waitcnt vmcnt(3)
	ds_write_b32 v168, v231
	s_waitcnt vmcnt(2)
	ds_write_b32 v182, v232
	s_waitcnt vmcnt(1)
	ds_write_b32 v184, v233
	s_waitcnt vmcnt(0)
	ds_write_b32 v186, v234
	s_mov_b32 s9, s41
	s_waitcnt lgkmcnt(0)
	s_lshl_b64 s[8:9], s[8:9], 1
	s_add_u32 s8, s4, s8
	s_addc_u32 s9, s5, s9
	v_lshlrev_b32_e32 v30, 1, v38
	ds_read2_b32 v[6:7], v60 offset0:33 offset1:41
	ds_read2_b32 v[8:9], v60 offset1:8
	ds_read2_b32 v[10:11], v60 offset0:66 offset1:74
	ds_read2_b32 v[12:13], v60 offset0:99 offset1:107
	ds_read2_b32 v[14:15], v60 offset0:132 offset1:140
	ds_read2_b32 v[16:17], v60 offset0:165 offset1:173
	ds_read2_b32 v[18:19], v60 offset0:198 offset1:206
	ds_read2_b32 v[20:21], v60 offset0:231 offset1:239
	v_lshl_add_u64 v[2:3], s[8:9], 0, v[30:31]
	v_lshl_add_u64 v[22:23], v[2:3], 0, s[58:59]
	s_waitcnt lgkmcnt(6)
	v_cvt_pk_bf16_f32 v2, v8, v6
	v_or_b32_e32 v6, s11, v59
	v_mul_u32_u24_e32 v6, 0xb00, v6
	v_lshlrev_b32_e32 v30, 1, v6
	s_waitcnt lgkmcnt(4)
	v_cvt_pk_bf16_f32 v3, v10, v12
	s_waitcnt lgkmcnt(2)
	v_cvt_pk_bf16_f32 v4, v14, v16
	s_waitcnt lgkmcnt(0)
	v_cvt_pk_bf16_f32 v5, v18, v20
	v_lshl_add_u64 v[24:25], v[22:23], 0, v[30:31]
	v_or_b32_e32 v6, s11, v61
	global_store_dwordx4 v[24:25], v[2:5], off
	v_mul_u32_u24_e32 v6, 0xb00, v6
	v_lshlrev_b32_e32 v30, 1, v6
	v_cvt_pk_bf16_f32 v2, v9, v7
	v_cvt_pk_bf16_f32 v3, v11, v13
	v_cvt_pk_bf16_f32 v4, v15, v17
	v_cvt_pk_bf16_f32 v5, v19, v21
	ds_read2_b32 v[8:9], v60 offset0:16 offset1:24
	ds_read2_b32 v[10:11], v60 offset0:49 offset1:57
	ds_read2_b32 v[12:13], v60 offset0:82 offset1:90
	ds_read2_b32 v[14:15], v60 offset0:115 offset1:123
	ds_read2_b32 v[16:17], v60 offset0:148 offset1:156
	ds_read2_b32 v[18:19], v60 offset0:181 offset1:189
	ds_read2_b32 v[20:21], v60 offset0:214 offset1:222
	ds_read2_b32 v[24:25], v60 offset0:247 offset1:255
	v_lshl_add_u64 v[6:7], v[22:23], 0, v[30:31]
	global_store_dwordx4 v[6:7], v[2:5], off
	v_or_b32_e32 v6, s11, v62
	v_mul_u32_u24_e32 v6, 0xb00, v6
	v_lshlrev_b32_e32 v30, 1, v6
	s_waitcnt lgkmcnt(6)
	v_cvt_pk_bf16_f32 v2, v8, v10
	s_waitcnt lgkmcnt(4)
	v_cvt_pk_bf16_f32 v3, v12, v14
	s_waitcnt lgkmcnt(2)
	v_cvt_pk_bf16_f32 v4, v16, v18
	s_waitcnt lgkmcnt(0)
	v_cvt_pk_bf16_f32 v5, v20, v24
	v_lshl_add_u64 v[6:7], v[22:23], 0, v[30:31]
	global_store_dwordx4 v[6:7], v[2:5], off
	v_or_b32_e32 v6, s11, v63
	v_mul_u32_u24_e32 v6, 0xb00, v6
	v_lshlrev_b32_e32 v30, 1, v6
	v_cvt_pk_bf16_f32 v2, v9, v11
	v_cvt_pk_bf16_f32 v3, v13, v15
	v_cvt_pk_bf16_f32 v4, v17, v19
	v_cvt_pk_bf16_f32 v5, v21, v25
	v_lshl_add_u64 v[6:7], v[22:23], 0, v[30:31]
	global_store_dwordx4 v[6:7], v[2:5], off
	s_waitcnt lgkmcnt(0)

; #define LAS __attribute__((address_space(3)))
; #define LDS_WAIT() asm volatile("s_waitcnt lgkmcnt(0)" ::: "memory")
; __device__ __forceinline__ void transpose_item(const float* W, int N, bf16_t* WT, int ldw, int drow0, int dk0, LAS float* scr, int k0, int n0, int lane) {
; #pragma unroll 8
;     for (int i = 0; i < 32; ++i) { const int kk = 2 * i + (lane >> 5); scr[kk * 33 + (lane & 31)] = W[(size_t)(k0 + kk) * N + n0 + (lane & 31)]; }
;     LDS_WAIT(); asm volatile("" ::: "memory");
.LBB0_84:
	s_lshl_b32 s11, s8, 1
	s_lshl_b32 s13, s10, 1
	v_or_b32_e32 v30, s11, v1
	v_or_b32_e32 v41, s13, v32
	s_add_i32 s14, s11, 4
	s_add_i32 s15, s13, 4
	s_add_i32 s16, s11, 8
	s_add_i32 s17, s13, 8
	s_add_i32 s18, s11, 12
	s_add_i32 s19, s13, 12
	s_add_i32 s20, s11, 16
	s_add_i32 s21, s13, 16
	s_add_i32 s22, s11, 20
	s_add_i32 s23, s13, 20
	s_add_i32 s26, s11, 24
	s_add_i32 s27, s13, 24
	s_add_i32 s11, s11, 28
	s_add_i32 s13, s13, 28
	v_add_u32_e32 v4, s6, v41
	v_or_b32_e32 v48, s14, v1
	v_or_b32_e32 v49, s15, v32
	v_or_b32_e32 v50, s16, v1
	v_or_b32_e32 v51, s17, v32
	v_or_b32_e32 v52, s18, v1
	v_or_b32_e32 v53, s19, v32
	v_or_b32_e32 v54, s20, v1
	v_or_b32_e32 v55, s21, v32
	v_or_b32_e32 v56, s22, v1
	v_or_b32_e32 v57, s23, v32
	v_or_b32_e32 v71, s26, v1
	v_or_b32_e32 v76, s27, v32
	v_or_b32_e32 v77, s11, v1
	v_or_b32_e32 v78, s13, v32
	v_add_u32_e32 v6, s7, v30
	v_mad_i64_i32 v[4:5], s[14:15], v4, s81, v[2:3]
	v_add_u32_e32 v10, s7, v48
	v_add_u32_e32 v8, s6, v49
	v_add_u32_e32 v14, s7, v50
	v_add_u32_e32 v12, s6, v51
	v_add_u32_e32 v18, s7, v52
	v_add_u32_e32 v16, s6, v53
	v_add_u32_e32 v22, s7, v54
	v_add_u32_e32 v20, s6, v55
	v_add_u32_e32 v26, s7, v56
	v_add_u32_e32 v24, s6, v57
	v_add_u32_e32 v42, s7, v71
	v_add_u32_e32 v28, s6, v76
	v_add_u32_e32 v46, s7, v77
	v_add_u32_e32 v44, s6, v78
	v_mad_i64_i32 v[6:7], s[14:15], v6, s81, v[2:3]
	v_mad_i64_i32 v[8:9], s[14:15], v8, s81, v[2:3]
	v_mad_i64_i32 v[10:11], s[14:15], v10, s81, v[2:3]
	v_mad_i64_i32 v[12:13], s[14:15], v12, s81, v[2:3]
	v_mad_i64_i32 v[14:15], s[14:15], v14, s81, v[2:3]
	v_mad_i64_i32 v[16:17], s[14:15], v16, s81, v[2:3]
	v_mad_i64_i32 v[18:19], s[14:15], v18, s81, v[2:3]
	v_mad_i64_i32 v[20:21], s[14:15], v20, s81, v[2:3]
	v_mad_i64_i32 v[22:23], s[14:15], v22, s81, v[2:3]
	v_mad_i64_i32 v[24:25], s[14:15], v24, s81, v[2:3]
	v_mad_i64_i32 v[26:27], s[14:15], v26, s81, v[2:3]
	v_mad_i64_i32 v[28:29], s[14:15], v28, s81, v[2:3]
	v_mad_i64_i32 v[42:43], s[14:15], v42, s81, v[2:3]
	v_mad_i64_i32 v[44:45], s[14:15], v44, s81, v[2:3]
	v_mad_i64_i32 v[46:47], s[14:15], v46, s81, v[2:3]
	global_load_dword v79, v[4:5], off nt
	global_load_dword v80, v[6:7], off nt
	global_load_dword v81, v[8:9], off nt
	global_load_dword v82, v[10:11], off nt
	global_load_dword v83, v[12:13], off nt
	global_load_dword v84, v[14:15], off nt
	global_load_dword v85, v[16:17], off nt
	global_load_dword v86, v[18:19], off nt
	global_load_dword v87, v[20:21], off nt
	global_load_dword v88, v[22:23], off nt
	global_load_dword v89, v[24:25], off nt
	global_load_dword v90, v[26:27], off nt
	global_load_dword v91, v[28:29], off nt
	global_load_dword v92, v[42:43], off nt
	global_load_dword v93, v[44:45], off nt
	global_load_dword v94, v[46:47], off nt
	s_add_i32 s10, s10, 16
	s_add_i32 s8, s8, 16
	s_add_i32 s9, s9, -16
	s_lshl_b32 s11, s8, 1
	s_lshl_b32 s13, s10, 1
	v_or_b32_e32 v170, s11, v1
	v_or_b32_e32 v181, s13, v32
	s_add_i32 s14, s11, 4
	s_add_i32 s15, s13, 4
	s_add_i32 s16, s11, 8
	s_add_i32 s17, s13, 8
	s_add_i32 s18, s11, 12
	s_add_i32 s19, s13, 12
	s_add_i32 s20, s11, 16
	s_add_i32 s21, s13, 16
	s_add_i32 s22, s11, 20
	s_add_i32 s23, s13, 20
	s_add_i32 s26, s11, 24
	s_add_i32 s27, s13, 24
	s_add_i32 s11, s11, 28
	s_add_i32 s13, s13, 28
	v_add_u32_e32 v144, s6, v181
	v_or_b32_e32 v188, s14, v1
	v_or_b32_e32 v189, s15, v32
	v_or_b32_e32 v190, s16, v1
	v_or_b32_e32 v191, s17, v32
	v_or_b32_e32 v192, s18, v1
	v_or_b32_e32 v193, s19, v32
	v_or_b32_e32 v194, s20, v1
	v_or_b32_e32 v195, s21, v32
	v_or_b32_e32 v196, s22, v1
	v_or_b32_e32 v197, s23, v32
	v_or_b32_e32 v211, s26, v1
	v_or_b32_e32 v216, s27, v32
	v_or_b32_e32 v217, s11, v1
	v_or_b32_e32 v218, s13, v32
	v_add_u32_e32 v146, s7, v170
	v_mad_i64_i32 v[144:145], s[14:15], v144, s81, v[2:3]
	v_add_u32_e32 v150, s7, v188
	v_add_u32_e32 v148, s6, v189
	v_add_u32_e32 v154, s7, v190
	v_add_u32_e32 v152, s6, v191
	v_add_u32_e32 v158, s7, v192
	v_add_u32_e32 v156, s6, v193
	v_add_u32_e32 v162, s7, v194
	v_add_u32_e32 v160, s6, v195
	v_add_u32_e32 v166, s7, v196
	v_add_u32_e32 v164, s6, v197
	v_add_u32_e32 v182, s7, v211
	v_add_u32_e32 v168, s6, v216
	v_add_u32_e32 v186, s7, v217
	v_add_u32_e32 v184, s6, v218
	v_mad_i64_i32 v[146:147], s[14:15], v146, s81, v[2:3]
	v_mad_i64_i32 v[148:149], s[14:15], v148, s81, v[2:3]
	v_mad_i64_i32 v[150:151], s[14:15], v150, s81, v[2:3]
	v_mad_i64_i32 v[152:153], s[14:15], v152, s81, v[2:3]
	v_mad_i64_i32 v[154:155], s[14:15], v154, s81, v[2:3]
	v_mad_i64_i32 v[156:157], s[14:15], v156, s81, v[2:3]
	v_mad_i64_i32 v[158:159], s[14:15], v158, s81, v[2:3]
	v_mad_i64_i32 v[160:161], s[14:15], v160, s81, v[2:3]
	v_mad_i64_i32 v[162:163], s[14:15], v162, s81, v[2:3]
	v_mad_i64_i32 v[164:165], s[14:15], v164, s81, v[2:3]
	v_mad_i64_i32 v[166:167], s[14:15], v166, s81, v[2:3]
	v_mad_i64_i32 v[168:169], s[14:15], v168, s81, v[2:3]
	v_mad_i64_i32 v[182:183], s[14:15], v182, s81, v[2:3]
	v_mad_i64_i32 v[184:185], s[14:15], v184, s81, v[2:3]
	v_mad_i64_i32 v[186:187], s[14:15], v186, s81, v[2:3]
	global_load_dword v219, v[144:145], off nt
	global_load_dword v220, v[146:147], off nt
	global_load_dword v221, v[148:149], off nt
	global_load_dword v222, v[150:151], off nt
	global_load_dword v223, v[152:153], off nt
	global_load_dword v224, v[154:155], off nt
	global_load_dword v225, v[156:157], off nt
	global_load_dword v226, v[158:159], off nt
	global_load_dword v227, v[160:161], off nt
	global_load_dword v228, v[162:163], off nt
	global_load_dword v229, v[164:165], off nt
	global_load_dword v230, v[166:167], off nt
	global_load_dword v231, v[168:169], off nt
	global_load_dword v232, v[182:183], off nt
	global_load_dword v233, v[184:185], off nt
	global_load_dword v234, v[186:187], off nt
	v_mad_u64_u32 v[4:5], s[14:15], v41, s67, v[36:37]
	v_mad_u64_u32 v[6:7], s[14:15], v30, s67, v[36:37]
	v_mad_u64_u32 v[8:9], s[14:15], v49, s67, v[36:37]
	v_mad_u64_u32 v[10:11], s[14:15], v48, s67, v[36:37]
	v_mad_u64_u32 v[12:13], s[14:15], v51, s67, v[36:37]
	v_mad_u64_u32 v[14:15], s[14:15], v50, s67, v[36:37]
	v_mad_u64_u32 v[16:17], s[14:15], v53, s67, v[36:37]
	v_mad_u64_u32 v[18:19], s[14:15], v52, s67, v[36:37]
	v_mad_u64_u32 v[20:21], s[14:15], v55, s67, v[36:37]
	v_mad_u64_u32 v[22:23], s[14:15], v54, s67, v[36:37]
	v_mad_u64_u32 v[24:25], s[14:15], v57, s67, v[36:37]
	v_mad_u64_u32 v[26:27], s[14:15], v56, s67, v[36:37]
	v_mad_u64_u32 v[28:29], s[14:15], v76, s67, v[36:37]
	v_mad_u64_u32 v[42:43], s[14:15], v71, s67, v[36:37]
	v_mad_u64_u32 v[44:45], s[14:15], v78, s67, v[36:37]
	v_mad_u64_u32 v[46:47], s[14:15], v77, s67, v[36:37]
	s_waitcnt vmcnt(31)
; #define LAS __attribute__((address_space(3)))
; __device__ __forceinline__ unsigned cvtpk_s(float lo, float hi) { f32x2_t v = {lo, hi}; bf16x2_t b = __builtin_convertvector(v, bf16x2_t); return __builtin_bit_cast(unsigned, b); }
; #define LDS_WAIT() asm volatile("s_waitcnt lgkmcnt(0)" ::: "memory")
; __device__ __forceinline__ void transpose_item(const float* W, int N, bf16_t* WT, int ldw, int drow0, int dk0, LAS float* scr, int k0, int n0, int lane) {
;     ...
;     for (int i = 0; i < 32; ++i) { const int kk = 2 * i + (lane >> 5); scr[kk * 33 + (lane & 31)] = W[(size_t)(k0 + kk) * N + n0 + (lane & 31)]; }
;     LDS_WAIT(); asm volatile("" ::: "memory");
;     const int c = lane & 7;
; #pragma unroll
;     for (int j = 0; j < 4; ++j) { const int n = (lane >> 3) + 8 * j; const LAS float* s = scr + (8 * c) * 33 + n;
;         u32x4 o; o.x = cvtpk_s(s[0 * 33], s[1 * 33]); o.y = cvtpk_s(s[2 * 33], s[3 * 33]); o.z = cvtpk_s(s[4 * 33], s[5 * 33]); o.w = cvtpk_s(s[6 * 33], s[7 * 33]);
;         *(u32x4*)(WT + (size_t)(drow0 + n) * ldw + dk0 + k0 + 8 * c) = o; }
;     LDS_WAIT(); asm volatile("" ::: "memory");
	ds_write_b32 v4, v79
	s_waitcnt vmcnt(30)
	ds_write_b32 v6, v80
	s_waitcnt vmcnt(29)
	ds_write_b32 v8, v81
	s_waitcnt vmcnt(28)
	ds_write_b32 v10, v82
	s_waitcnt vmcnt(27)
	ds_write_b32 v12, v83
	s_waitcnt vmcnt(26)
	ds_write_b32 v14, v84
	s_waitcnt vmcnt(25)
	ds_write_b32 v16, v85
	s_waitcnt vmcnt(24)
	ds_write_b32 v18, v86
	s_waitcnt vmcnt(23)
	ds_write_b32 v20, v87
	s_waitcnt vmcnt(22)
	ds_write_b32 v22, v88
	s_waitcnt vmcnt(21)
	ds_write_b32 v24, v89
	s_waitcnt vmcnt(20)
	ds_write_b32 v26, v90
	s_waitcnt vmcnt(19)
	ds_write_b32 v28, v91
	s_waitcnt vmcnt(18)
	ds_write_b32 v42, v92
	s_waitcnt vmcnt(17)
	ds_write_b32 v44, v93
	s_waitcnt vmcnt(16)
	ds_write_b32 v46, v94
	s_add_i32 s10, s10, 16
	s_add_i32 s8, s8, 16
	s_add_i32 s9, s9, -16
	v_mad_u64_u32 v[144:145], s[14:15], v181, s67, v[36:37]
	v_mad_u64_u32 v[146:147], s[14:15], v170, s67, v[36:37]
	v_mad_u64_u32 v[148:149], s[14:15], v189, s67, v[36:37]
	v_mad_u64_u32 v[150:151], s[14:15], v188, s67, v[36:37]
	v_mad_u64_u32 v[152:153], s[14:15], v191, s67, v[36:37]
	v_mad_u64_u32 v[154:155], s[14:15], v190, s67, v[36:37]
	v_mad_u64_u32 v[156:157], s[14:15], v193, s67, v[36:37]
	v_mad_u64_u32 v[158:159], s[14:15], v192, s67, v[36:37]
	v_mad_u64_u32 v[160:161], s[14:15], v195, s67, v[36:37]
	v_mad_u64_u32 v[162:163], s[14:15], v194, s67, v[36:37]
	v_mad_u64_u32 v[164:165], s[14:15], v197, s67, v[36:37]
	v_mad_u64_u32 v[166:167], s[14:15], v196, s67, v[36:37]
	v_mad_u64_u32 v[168:169], s[14:15], v216, s67, v[36:37]
	v_mad_u64_u32 v[182:183], s[14:15], v211, s67, v[36:37]
	v_mad_u64_u32 v[184:185], s[14:15], v218, s67, v[36:37]
	v_mad_u64_u32 v[186:187], s[14:15], v217, s67, v[36:37]
	s_waitcnt vmcnt(15)
	ds_write_b32 v144, v219
	s_waitcnt vmcnt(14)
	ds_write_b32 v146, v220
	s_waitcnt vmcnt(13)
	ds_write_b32 v148, v221
	s_waitcnt vmcnt(12)
	ds_write_b32 v150, v222
	s_waitcnt vmcnt(11)
	ds_write_b32 v152, v223
	s_waitcnt vmcnt(10)
	ds_write_b32 v154, v224
	s_waitcnt vmcnt(9)
	ds_write_b32 v156, v225
	s_waitcnt vmcnt(8)
	ds_write_b32 v158, v226
	s_waitcnt vmcnt(7)
	ds_write_b32 v160, v227
	s_waitcnt vmcnt(6)
	ds_write_b32 v162, v228
	s_waitcnt vmcnt(5)
	ds_write_b32 v164, v229
	s_waitcnt vmcnt(4)
	ds_write_b32 v166, v230
	s_waitcnt vmcnt(3)
	ds_write_b32 v168, v231
	s_waitcnt vmcnt(2)
	ds_write_b32 v182, v232
	s_waitcnt vmcnt(1)
	ds_write_b32 v184, v233
	s_waitcnt vmcnt(0)
	ds_write_b32 v186, v234
	s_waitcnt lgkmcnt(0)
	s_ashr_i32 s7, s6, 31
	ds_read2_b32 v[6:7], v60 offset0:33 offset1:41
	ds_read2_b32 v[8:9], v60 offset1:8
	ds_read2_b32 v[10:11], v60 offset0:66 offset1:74
	ds_read2_b32 v[12:13], v60 offset0:99 offset1:107
	ds_read2_b32 v[14:15], v60 offset0:132 offset1:140
	ds_read2_b32 v[16:17], v60 offset0:165 offset1:173
	ds_read2_b32 v[18:19], v60 offset0:198 offset1:206
	ds_read2_b32 v[20:21], v60 offset0:231 offset1:239
	s_lshl_b64 s[6:7], s[6:7], 1
	s_add_u32 s4, s4, s6
	v_add_u32_e32 v24, s12, v59
	s_addc_u32 s5, s5, s7
	v_lshlrev_b32_e32 v30, 1, v38
	v_ashrrev_i32_e32 v25, 31, v24
	v_lshl_add_u64 v[22:23], s[4:5], 0, v[30:31]
	v_lshlrev_b64 v[24:25], 11, v[24:25]
	s_waitcnt lgkmcnt(6)
	v_cvt_pk_bf16_f32 v2, v8, v6
	s_waitcnt lgkmcnt(4)
	v_cvt_pk_bf16_f32 v3, v10, v12
	s_waitcnt lgkmcnt(2)
	v_cvt_pk_bf16_f32 v4, v14, v16
	s_waitcnt lgkmcnt(0)
	v_cvt_pk_bf16_f32 v5, v18, v20
	v_lshl_add_u64 v[24:25], v[22:23], 0, v[24:25]
	v_add_u32_e32 v6, s12, v61
	global_store_dwordx4 v[24:25], v[2:5], off
	s_nop 1
	v_cvt_pk_bf16_f32 v2, v9, v7
	v_ashrrev_i32_e32 v7, 31, v6
	v_cvt_pk_bf16_f32 v3, v11, v13
	v_cvt_pk_bf16_f32 v4, v15, v17
	v_cvt_pk_bf16_f32 v5, v19, v21
	v_lshlrev_b64 v[6:7], 11, v[6:7]
	ds_read2_b32 v[8:9], v60 offset0:49 offset1:57
	ds_read2_b32 v[10:11], v60 offset0:16 offset1:24
	ds_read2_b32 v[12:13], v60 offset0:82 offset1:90
	ds_read2_b32 v[14:15], v60 offset0:115 offset1:123
	ds_read2_b32 v[16:17], v60 offset0:148 offset1:156
	ds_read2_b32 v[18:19], v60 offset0:181 offset1:189
	ds_read2_b32 v[20:21], v60 offset0:214 offset1:222
	ds_read2_b32 v[24:25], v60 offset0:247 offset1:255
	v_lshl_add_u64 v[6:7], v[22:23], 0, v[6:7]
	global_store_dwordx4 v[6:7], v[2:5], off
	v_add_u32_e32 v6, s12, v62
	v_ashrrev_i32_e32 v7, 31, v6
	v_lshlrev_b64 v[6:7], 11, v[6:7]
	s_waitcnt lgkmcnt(6)
	v_cvt_pk_bf16_f32 v2, v10, v8
	s_waitcnt lgkmcnt(4)
	v_cvt_pk_bf16_f32 v3, v12, v14
	s_waitcnt lgkmcnt(2)
	v_cvt_pk_bf16_f32 v4, v16, v18
	s_waitcnt lgkmcnt(0)
	v_cvt_pk_bf16_f32 v5, v20, v24
	v_lshl_add_u64 v[6:7], v[22:23], 0, v[6:7]
	global_store_dwordx4 v[6:7], v[2:5], off
	v_add_u32_e32 v6, s12, v63
	v_ashrrev_i32_e32 v7, 31, v6
	v_lshlrev_b64 v[6:7], 11, v[6:7]
	v_cvt_pk_bf16_f32 v2, v11, v9
	v_cvt_pk_bf16_f32 v3, v13, v15
	v_cvt_pk_bf16_f32 v4, v17, v19
	v_cvt_pk_bf16_f32 v5, v21, v25
	v_lshl_add_u64 v[6:7], v[22:23], 0, v[6:7]
	global_store_dwordx4 v[6:7], v[2:5], off
	s_waitcnt lgkmcnt(0)

; __device__ __forceinline__ void prologue(const kptr_t kp, LAS float* scr, int gw, int NGW, int lane) {
;     ...
;             const int l = r / 576, rem = r % 576, cgp = rem / 16, ks = rem % 16, j0 = cgp * 256 + 4 * lane;
;             const float* c = KPTR(const float, 1); const float* cc = KPTR(const float, 3);
;             const float* wp = KPTR(const float, 4) + ((size_t)l * 1024 + ks * 64) * 9216 + j0;
;             f32x4 a0 = {0.f, 0.f, 0.f, 0.f}, a1 = a0, a2 = a0;
; #pragma unroll 4
;             for (int kk = 0; kk < 64; ++kk) {
;                 const int k = ks * 64 + kk; const float x0 = c[k], x1 = c[1024 + k], x2 = cc[k];
;                 const float s0 = x0 / (1.0f + expf(-x0)), s1 = x1 / (1.0f + expf(-x1)), s2 = x2 / (1.0f + expf(-x2));
;                 const f32x4 w = *(const f32x4*)(wp + (size_t)kk * 9216);
;                 a0 += w * s0; a1 += w * s1; a2 += w * s2;
;             }
.LBB0_88:
	v_lshlrev_b32_e32 v2, 2, v42
	v_add_u32_e32 v3, 0x1000, v64
	global_load_dword v4, v64, s[92:93]
	global_load_dword v5, v3, s[92:93]
	global_load_dword v6, v64, s[90:91]
	s_mov_b64 s[12:13], s[4:5]
	global_load_dwordx4 v[76:79], v2, s[12:13] nt
	s_add_u32 s12, s12, 0x9000
	s_addc_u32 s13, s13, 0
	global_load_dwordx4 v[80:83], v2, s[12:13] nt
	s_add_u32 s12, s12, 0x9000
	s_addc_u32 s13, s13, 0
	global_load_dwordx4 v[84:87], v2, s[12:13] nt
	s_add_u32 s12, s12, 0x9000
	s_addc_u32 s13, s13, 0
	global_load_dwordx4 v[88:91], v2, s[12:13] nt
	s_add_u32 s12, s12, 0x9000
	s_addc_u32 s13, s13, 0
	global_load_dwordx4 v[92:95], v2, s[12:13] nt
	s_add_u32 s12, s12, 0x9000
	s_addc_u32 s13, s13, 0
	global_load_dwordx4 v[96:99], v2, s[12:13] nt
	s_add_u32 s12, s12, 0x9000
	s_addc_u32 s13, s13, 0
	global_load_dwordx4 v[100:103], v2, s[12:13] nt
	s_add_u32 s12, s12, 0x9000
	s_addc_u32 s13, s13, 0
	global_load_dwordx4 v[104:107], v2, s[12:13] nt
	s_add_u32 s12, s12, 0x9000
	s_addc_u32 s13, s13, 0
	global_load_dwordx4 v[108:111], v2, s[12:13] nt
	s_add_u32 s12, s12, 0x9000
	s_addc_u32 s13, s13, 0
	global_load_dwordx4 v[112:115], v2, s[12:13] nt
	s_add_u32 s12, s12, 0x9000
	s_addc_u32 s13, s13, 0
	global_load_dwordx4 v[116:119], v2, s[12:13] nt
	s_add_u32 s12, s12, 0x9000
	s_addc_u32 s13, s13, 0
	global_load_dwordx4 v[120:123], v2, s[12:13] nt
	s_add_u32 s12, s12, 0x9000
	s_addc_u32 s13, s13, 0
	global_load_dwordx4 v[124:127], v2, s[12:13] nt
	s_add_u32 s12, s12, 0x9000
	s_addc_u32 s13, s13, 0
	global_load_dwordx4 v[128:131], v2, s[12:13] nt
	s_add_u32 s12, s12, 0x9000
	s_addc_u32 s13, s13, 0
	global_load_dwordx4 v[132:135], v2, s[12:13] nt
	s_add_u32 s12, s12, 0x9000
	s_addc_u32 s13, s13, 0
	global_load_dwordx4 v[136:139], v2, s[12:13] nt
	s_add_u32 s12, s12, 0x9000
	s_addc_u32 s13, s13, 0
	global_load_dwordx4 v[140:143], v2, s[12:13] nt
	s_add_u32 s12, s12, 0x9000
	s_addc_u32 s13, s13, 0
	global_load_dwordx4 v[144:147], v2, s[12:13] nt
	s_add_u32 s12, s12, 0x9000
	s_addc_u32 s13, s13, 0
	global_load_dwordx4 v[148:151], v2, s[12:13] nt
	s_add_u32 s12, s12, 0x9000
	s_addc_u32 s13, s13, 0
	global_load_dwordx4 v[152:155], v2, s[12:13] nt
	s_add_u32 s12, s12, 0x9000
	s_addc_u32 s13, s13, 0
	global_load_dwordx4 v[156:159], v2, s[12:13] nt
	s_add_u32 s12, s12, 0x9000
	s_addc_u32 s13, s13, 0
	global_load_dwordx4 v[160:163], v2, s[12:13] nt
	s_add_u32 s12, s12, 0x9000
	s_addc_u32 s13, s13, 0
	global_load_dwordx4 v[164:167], v2, s[12:13] nt
	s_add_u32 s12, s12, 0x9000
	s_addc_u32 s13, s13, 0
	global_load_dwordx4 v[168:171], v2, s[12:13] nt
	s_add_u32 s12, s12, 0x9000
	s_addc_u32 s13, s13, 0
	global_load_dwordx4 v[172:175], v2, s[12:13] nt
	s_add_u32 s12, s12, 0x9000
	s_addc_u32 s13, s13, 0
	global_load_dwordx4 v[176:179], v2, s[12:13] nt
	s_add_u32 s12, s12, 0x9000
	s_addc_u32 s13, s13, 0
	global_load_dwordx4 v[180:183], v2, s[12:13] nt
	s_add_u32 s12, s12, 0x9000
	s_addc_u32 s13, s13, 0
	global_load_dwordx4 v[184:187], v2, s[12:13] nt
	s_add_u32 s12, s12, 0x9000
	s_addc_u32 s13, s13, 0
	global_load_dwordx4 v[188:191], v2, s[12:13] nt
	s_add_u32 s12, s12, 0x9000
	s_addc_u32 s13, s13, 0
	global_load_dwordx4 v[192:195], v2, s[12:13] nt
	s_add_u32 s12, s12, 0x9000
	s_addc_u32 s13, s13, 0
	global_load_dwordx4 v[196:199], v2, s[12:13] nt
	s_add_u32 s12, s12, 0x9000
	s_addc_u32 s13, s13, 0
	global_load_dwordx4 v[200:203], v2, s[12:13] nt
	s_add_u32 s12, s12, 0x9000
	s_addc_u32 s13, s13, 0
	s_waitcnt vmcnt(32)
	v_mul_f32_e32 v10, 0xbfb8aa3b, v4
	v_mul_f32_e32 v11, 0xbfb8aa3b, v5
	v_mul_f32_e32 v12, 0xbfb8aa3b, v6
	v_exp_f32_e32 v10, v10
	v_exp_f32_e32 v11, v11
	v_exp_f32_e32 v12, v12
	s_nop 0
	v_add_f32_e32 v10, 1.0, v10
	v_add_f32_e32 v11, 1.0, v11
	v_add_f32_e32 v12, 1.0, v12
	v_rcp_f32_e32 v10, v10
	v_rcp_f32_e32 v11, v11
	v_rcp_f32_e32 v12, v12
	s_nop 0
	v_mul_f32_e32 v7, v4, v10
	v_mul_f32_e32 v8, v5, v11
	v_mul_f32_e32 v9, v6, v12
	s_nop 0
	s_waitcnt vmcnt(31)
	v_readlane_b32 s6, v7, 0
	v_readlane_b32 s7, v8, 0
	v_readlane_b32 s18, v9, 0
	v_fmac_f32_e32 v46, s6, v76
	v_fmac_f32_e32 v47, s6, v77
	v_fmac_f32_e32 v44, s6, v78
	v_fmac_f32_e32 v45, s6, v79
	v_fmac_f32_e32 v54, s7, v76
	v_fmac_f32_e32 v55, s7, v77
	v_fmac_f32_e32 v50, s7, v78
	v_fmac_f32_e32 v51, s7, v79
	v_fmac_f32_e32 v52, s18, v76
	v_fmac_f32_e32 v53, s18, v77
	v_fmac_f32_e32 v48, s18, v78
	v_fmac_f32_e32 v49, s18, v79
	global_load_dwordx4 v[76:79], v2, s[12:13] nt
	s_add_u32 s12, s12, 0x9000
	s_addc_u32 s13, s13, 0
	s_waitcnt vmcnt(31)
	v_readlane_b32 s6, v7, 1
	v_readlane_b32 s7, v8, 1
	v_readlane_b32 s18, v9, 1
	v_fmac_f32_e32 v46, s6, v80
	v_fmac_f32_e32 v47, s6, v81
	v_fmac_f32_e32 v44, s6, v82
	v_fmac_f32_e32 v45, s6, v83
	v_fmac_f32_e32 v54, s7, v80
	v_fmac_f32_e32 v55, s7, v81
	v_fmac_f32_e32 v50, s7, v82
	v_fmac_f32_e32 v51, s7, v83
	v_fmac_f32_e32 v52, s18, v80
	v_fmac_f32_e32 v53, s18, v81
	v_fmac_f32_e32 v48, s18, v82
	v_fmac_f32_e32 v49, s18, v83
	global_load_dwordx4 v[80:83], v2, s[12:13] nt
	s_add_u32 s12, s12, 0x9000
	s_addc_u32 s13, s13, 0
	s_waitcnt vmcnt(31)
	v_readlane_b32 s6, v7, 2
	v_readlane_b32 s7, v8, 2
	v_readlane_b32 s18, v9, 2
	v_fmac_f32_e32 v46, s6, v84
	v_fmac_f32_e32 v47, s6, v85
	v_fmac_f32_e32 v44, s6, v86
	v_fmac_f32_e32 v45, s6, v87
	v_fmac_f32_e32 v54, s7, v84
	v_fmac_f32_e32 v55, s7, v85
	v_fmac_f32_e32 v50, s7, v86
	v_fmac_f32_e32 v51, s7, v87
	v_fmac_f32_e32 v52, s18, v84
	v_fmac_f32_e32 v53, s18, v85
	v_fmac_f32_e32 v48, s18, v86
	v_fmac_f32_e32 v49, s18, v87
	global_load_dwordx4 v[84:87], v2, s[12:13] nt
	s_add_u32 s12, s12, 0x9000
	s_addc_u32 s13, s13, 0
	s_waitcnt vmcnt(31)
; __device__ __forceinline__ void prologue(const kptr_t kp, LAS float* scr, int gw, int NGW, int lane) {
;     ...
;             for (int kk = 0; kk < 64; ++kk) {
;                 const int k = ks * 64 + kk; const float x0 = c[k], x1 = c[1024 + k], x2 = cc[k];
;                 const float s0 = x0 / (1.0f + expf(-x0)), s1 = x1 / (1.0f + expf(-x1)), s2 = x2 / (1.0f + expf(-x2));
;                 const f32x4 w = *(const f32x4*)(wp + (size_t)kk * 9216);
;                 a0 += w * s0; a1 += w * s1; a2 += w * s2;
;             }
	v_readlane_b32 s6, v7, 3
	v_readlane_b32 s7, v8, 3
	v_readlane_b32 s18, v9, 3
	v_fmac_f32_e32 v46, s6, v88
	v_fmac_f32_e32 v47, s6, v89
	v_fmac_f32_e32 v44, s6, v90
	v_fmac_f32_e32 v45, s6, v91
	v_fmac_f32_e32 v54, s7, v88
	v_fmac_f32_e32 v55, s7, v89
	v_fmac_f32_e32 v50, s7, v90
	v_fmac_f32_e32 v51, s7, v91
	v_fmac_f32_e32 v52, s18, v88
	v_fmac_f32_e32 v53, s18, v89
	v_fmac_f32_e32 v48, s18, v90
	v_fmac_f32_e32 v49, s18, v91
	global_load_dwordx4 v[88:91], v2, s[12:13] nt
	s_add_u32 s12, s12, 0x9000
	s_addc_u32 s13, s13, 0
	s_waitcnt vmcnt(31)
	v_readlane_b32 s6, v7, 4
	v_readlane_b32 s7, v8, 4
	v_readlane_b32 s18, v9, 4
	v_fmac_f32_e32 v46, s6, v92
	v_fmac_f32_e32 v47, s6, v93
	v_fmac_f32_e32 v44, s6, v94
	v_fmac_f32_e32 v45, s6, v95
	v_fmac_f32_e32 v54, s7, v92
	v_fmac_f32_e32 v55, s7, v93
	v_fmac_f32_e32 v50, s7, v94
	v_fmac_f32_e32 v51, s7, v95
	v_fmac_f32_e32 v52, s18, v92
	v_fmac_f32_e32 v53, s18, v93
	v_fmac_f32_e32 v48, s18, v94
	v_fmac_f32_e32 v49, s18, v95
	global_load_dwordx4 v[92:95], v2, s[12:13] nt
	s_add_u32 s12, s12, 0x9000
	s_addc_u32 s13, s13, 0
	s_waitcnt vmcnt(31)
	v_readlane_b32 s6, v7, 5
	v_readlane_b32 s7, v8, 5
	v_readlane_b32 s18, v9, 5
	v_fmac_f32_e32 v46, s6, v96
	v_fmac_f32_e32 v47, s6, v97
	v_fmac_f32_e32 v44, s6, v98
	v_fmac_f32_e32 v45, s6, v99
	v_fmac_f32_e32 v54, s7, v96
	v_fmac_f32_e32 v55, s7, v97
	v_fmac_f32_e32 v50, s7, v98
	v_fmac_f32_e32 v51, s7, v99
	v_fmac_f32_e32 v52, s18, v96
	v_fmac_f32_e32 v53, s18, v97
	v_fmac_f32_e32 v48, s18, v98
	v_fmac_f32_e32 v49, s18, v99
	global_load_dwordx4 v[96:99], v2, s[12:13] nt
	s_add_u32 s12, s12, 0x9000
	s_addc_u32 s13, s13, 0
	s_waitcnt vmcnt(31)
	v_readlane_b32 s6, v7, 6
	v_readlane_b32 s7, v8, 6
	v_readlane_b32 s18, v9, 6
	v_fmac_f32_e32 v46, s6, v100
	v_fmac_f32_e32 v47, s6, v101
	v_fmac_f32_e32 v44, s6, v102
	v_fmac_f32_e32 v45, s6, v103
	v_fmac_f32_e32 v54, s7, v100
	v_fmac_f32_e32 v55, s7, v101
	v_fmac_f32_e32 v50, s7, v102
	v_fmac_f32_e32 v51, s7, v103
	v_fmac_f32_e32 v52, s18, v100
	v_fmac_f32_e32 v53, s18, v101
	v_fmac_f32_e32 v48, s18, v102
	v_fmac_f32_e32 v49, s18, v103
	global_load_dwordx4 v[100:103], v2, s[12:13] nt
	s_add_u32 s12, s12, 0x9000
	s_addc_u32 s13, s13, 0
	s_waitcnt vmcnt(31)
	v_readlane_b32 s6, v7, 7
	v_readlane_b32 s7, v8, 7
	v_readlane_b32 s18, v9, 7
	v_fmac_f32_e32 v46, s6, v104
	v_fmac_f32_e32 v47, s6, v105
	v_fmac_f32_e32 v44, s6, v106
	v_fmac_f32_e32 v45, s6, v107
	v_fmac_f32_e32 v54, s7, v104
	v_fmac_f32_e32 v55, s7, v105
	v_fmac_f32_e32 v50, s7, v106
	v_fmac_f32_e32 v51, s7, v107
	v_fmac_f32_e32 v52, s18, v104
	v_fmac_f32_e32 v53, s18, v105
	v_fmac_f32_e32 v48, s18, v106
	v_fmac_f32_e32 v49, s18, v107
	global_load_dwordx4 v[104:107], v2, s[12:13] nt
	s_add_u32 s12, s12, 0x9000
	s_addc_u32 s13, s13, 0
	s_waitcnt vmcnt(31)
	v_readlane_b32 s6, v7, 8
	v_readlane_b32 s7, v8, 8
	v_readlane_b32 s18, v9, 8
	v_fmac_f32_e32 v46, s6, v108
	v_fmac_f32_e32 v47, s6, v109
	v_fmac_f32_e32 v44, s6, v110
	v_fmac_f32_e32 v45, s6, v111
	v_fmac_f32_e32 v54, s7, v108
	v_fmac_f32_e32 v55, s7, v109
	v_fmac_f32_e32 v50, s7, v110
	v_fmac_f32_e32 v51, s7, v111
	v_fmac_f32_e32 v52, s18, v108
	v_fmac_f32_e32 v53, s18, v109
	v_fmac_f32_e32 v48, s18, v110
	v_fmac_f32_e32 v49, s18, v111
	global_load_dwordx4 v[108:111], v2, s[12:13] nt
	s_add_u32 s12, s12, 0x9000
	s_addc_u32 s13, s13, 0
	s_waitcnt vmcnt(31)
	v_readlane_b32 s6, v7, 9
	v_readlane_b32 s7, v8, 9
	v_readlane_b32 s18, v9, 9
	v_fmac_f32_e32 v46, s6, v112
	v_fmac_f32_e32 v47, s6, v113
	v_fmac_f32_e32 v44, s6, v114
	v_fmac_f32_e32 v45, s6, v115
	v_fmac_f32_e32 v54, s7, v112
	v_fmac_f32_e32 v55, s7, v113
	v_fmac_f32_e32 v50, s7, v114
	v_fmac_f32_e32 v51, s7, v115
	v_fmac_f32_e32 v52, s18, v112
	v_fmac_f32_e32 v53, s18, v113
	v_fmac_f32_e32 v48, s18, v114
	v_fmac_f32_e32 v49, s18, v115
	global_load_dwordx4 v[112:115], v2, s[12:13] nt
	s_add_u32 s12, s12, 0x9000
	s_addc_u32 s13, s13, 0
	s_waitcnt vmcnt(31)
	v_readlane_b32 s6, v7, 10
	v_readlane_b32 s7, v8, 10
	v_readlane_b32 s18, v9, 10
	v_fmac_f32_e32 v46, s6, v116
	v_fmac_f32_e32 v47, s6, v117
	v_fmac_f32_e32 v44, s6, v118
	v_fmac_f32_e32 v45, s6, v119
	v_fmac_f32_e32 v54, s7, v116
	v_fmac_f32_e32 v55, s7, v117
	v_fmac_f32_e32 v50, s7, v118
	v_fmac_f32_e32 v51, s7, v119
	v_fmac_f32_e32 v52, s18, v116
	v_fmac_f32_e32 v53, s18, v117
	v_fmac_f32_e32 v48, s18, v118
	v_fmac_f32_e32 v49, s18, v119
	global_load_dwordx4 v[116:119], v2, s[12:13] nt
	s_add_u32 s12, s12, 0x9000
	s_addc_u32 s13, s13, 0
	s_waitcnt vmcnt(31)
	v_readlane_b32 s6, v7, 11
	v_readlane_b32 s7, v8, 11
	v_readlane_b32 s18, v9, 11
	v_fmac_f32_e32 v46, s6, v120
	v_fmac_f32_e32 v47, s6, v121
	v_fmac_f32_e32 v44, s6, v122
	v_fmac_f32_e32 v45, s6, v123
	v_fmac_f32_e32 v54, s7, v120
	v_fmac_f32_e32 v55, s7, v121
	v_fmac_f32_e32 v50, s7, v122
	v_fmac_f32_e32 v51, s7, v123
	v_fmac_f32_e32 v52, s18, v120
	v_fmac_f32_e32 v53, s18, v121
	v_fmac_f32_e32 v48, s18, v122
	v_fmac_f32_e32 v49, s18, v123
	global_load_dwordx4 v[120:123], v2, s[12:13] nt
	s_add_u32 s12, s12, 0x9000
	s_addc_u32 s13, s13, 0
	s_waitcnt vmcnt(31)
	v_readlane_b32 s6, v7, 12
	v_readlane_b32 s7, v8, 12
	v_readlane_b32 s18, v9, 12
	v_fmac_f32_e32 v46, s6, v124
	v_fmac_f32_e32 v47, s6, v125
	v_fmac_f32_e32 v44, s6, v126
	v_fmac_f32_e32 v45, s6, v127
	v_fmac_f32_e32 v54, s7, v124
	v_fmac_f32_e32 v55, s7, v125
	v_fmac_f32_e32 v50, s7, v126
	v_fmac_f32_e32 v51, s7, v127
	v_fmac_f32_e32 v52, s18, v124
	v_fmac_f32_e32 v53, s18, v125
	v_fmac_f32_e32 v48, s18, v126
	v_fmac_f32_e32 v49, s18, v127
	global_load_dwordx4 v[124:127], v2, s[12:13] nt
	s_add_u32 s12, s12, 0x9000
	s_addc_u32 s13, s13, 0
	s_waitcnt vmcnt(31)
; __device__ __forceinline__ void prologue(const kptr_t kp, LAS float* scr, int gw, int NGW, int lane) {
;     ...
;             for (int kk = 0; kk < 64; ++kk) {
;                 const int k = ks * 64 + kk; const float x0 = c[k], x1 = c[1024 + k], x2 = cc[k];
;                 const float s0 = x0 / (1.0f + expf(-x0)), s1 = x1 / (1.0f + expf(-x1)), s2 = x2 / (1.0f + expf(-x2));
;                 const f32x4 w = *(const f32x4*)(wp + (size_t)kk * 9216);
;                 a0 += w * s0; a1 += w * s1; a2 += w * s2;
;             }
	v_readlane_b32 s6, v7, 13
	v_readlane_b32 s7, v8, 13
	v_readlane_b32 s18, v9, 13
	v_fmac_f32_e32 v46, s6, v128
	v_fmac_f32_e32 v47, s6, v129
	v_fmac_f32_e32 v44, s6, v130
	v_fmac_f32_e32 v45, s6, v131
	v_fmac_f32_e32 v54, s7, v128
	v_fmac_f32_e32 v55, s7, v129
	v_fmac_f32_e32 v50, s7, v130
	v_fmac_f32_e32 v51, s7, v131
	v_fmac_f32_e32 v52, s18, v128
	v_fmac_f32_e32 v53, s18, v129
	v_fmac_f32_e32 v48, s18, v130
	v_fmac_f32_e32 v49, s18, v131
	global_load_dwordx4 v[128:131], v2, s[12:13] nt
	s_add_u32 s12, s12, 0x9000
	s_addc_u32 s13, s13, 0
	s_waitcnt vmcnt(31)
	v_readlane_b32 s6, v7, 14
	v_readlane_b32 s7, v8, 14
	v_readlane_b32 s18, v9, 14
	v_fmac_f32_e32 v46, s6, v132
	v_fmac_f32_e32 v47, s6, v133
	v_fmac_f32_e32 v44, s6, v134
	v_fmac_f32_e32 v45, s6, v135
	v_fmac_f32_e32 v54, s7, v132
	v_fmac_f32_e32 v55, s7, v133
	v_fmac_f32_e32 v50, s7, v134
	v_fmac_f32_e32 v51, s7, v135
	v_fmac_f32_e32 v52, s18, v132
	v_fmac_f32_e32 v53, s18, v133
	v_fmac_f32_e32 v48, s18, v134
	v_fmac_f32_e32 v49, s18, v135
	global_load_dwordx4 v[132:135], v2, s[12:13] nt
	s_add_u32 s12, s12, 0x9000
	s_addc_u32 s13, s13, 0
	s_waitcnt vmcnt(31)
	v_readlane_b32 s6, v7, 15
	v_readlane_b32 s7, v8, 15
	v_readlane_b32 s18, v9, 15
	v_fmac_f32_e32 v46, s6, v136
	v_fmac_f32_e32 v47, s6, v137
	v_fmac_f32_e32 v44, s6, v138
	v_fmac_f32_e32 v45, s6, v139
	v_fmac_f32_e32 v54, s7, v136
	v_fmac_f32_e32 v55, s7, v137
	v_fmac_f32_e32 v50, s7, v138
	v_fmac_f32_e32 v51, s7, v139
	v_fmac_f32_e32 v52, s18, v136
	v_fmac_f32_e32 v53, s18, v137
	v_fmac_f32_e32 v48, s18, v138
	v_fmac_f32_e32 v49, s18, v139
	global_load_dwordx4 v[136:139], v2, s[12:13] nt
	s_add_u32 s12, s12, 0x9000
	s_addc_u32 s13, s13, 0
	s_waitcnt vmcnt(31)
	v_readlane_b32 s6, v7, 16
	v_readlane_b32 s7, v8, 16
	v_readlane_b32 s18, v9, 16
	v_fmac_f32_e32 v46, s6, v140
	v_fmac_f32_e32 v47, s6, v141
	v_fmac_f32_e32 v44, s6, v142
	v_fmac_f32_e32 v45, s6, v143
	v_fmac_f32_e32 v54, s7, v140
	v_fmac_f32_e32 v55, s7, v141
	v_fmac_f32_e32 v50, s7, v142
	v_fmac_f32_e32 v51, s7, v143
	v_fmac_f32_e32 v52, s18, v140
	v_fmac_f32_e32 v53, s18, v141
	v_fmac_f32_e32 v48, s18, v142
	v_fmac_f32_e32 v49, s18, v143
	global_load_dwordx4 v[140:143], v2, s[12:13] nt
	s_add_u32 s12, s12, 0x9000
	s_addc_u32 s13, s13, 0
	s_waitcnt vmcnt(31)
	v_readlane_b32 s6, v7, 17
	v_readlane_b32 s7, v8, 17
	v_readlane_b32 s18, v9, 17
	v_fmac_f32_e32 v46, s6, v144
	v_fmac_f32_e32 v47, s6, v145
	v_fmac_f32_e32 v44, s6, v146
	v_fmac_f32_e32 v45, s6, v147
	v_fmac_f32_e32 v54, s7, v144
	v_fmac_f32_e32 v55, s7, v145
	v_fmac_f32_e32 v50, s7, v146
	v_fmac_f32_e32 v51, s7, v147
	v_fmac_f32_e32 v52, s18, v144
	v_fmac_f32_e32 v53, s18, v145
	v_fmac_f32_e32 v48, s18, v146
	v_fmac_f32_e32 v49, s18, v147
	global_load_dwordx4 v[144:147], v2, s[12:13] nt
	s_add_u32 s12, s12, 0x9000
	s_addc_u32 s13, s13, 0
	s_waitcnt vmcnt(31)
	v_readlane_b32 s6, v7, 18
	v_readlane_b32 s7, v8, 18
	v_readlane_b32 s18, v9, 18
	v_fmac_f32_e32 v46, s6, v148
	v_fmac_f32_e32 v47, s6, v149
	v_fmac_f32_e32 v44, s6, v150
	v_fmac_f32_e32 v45, s6, v151
	v_fmac_f32_e32 v54, s7, v148
	v_fmac_f32_e32 v55, s7, v149
	v_fmac_f32_e32 v50, s7, v150
	v_fmac_f32_e32 v51, s7, v151
	v_fmac_f32_e32 v52, s18, v148
	v_fmac_f32_e32 v53, s18, v149
	v_fmac_f32_e32 v48, s18, v150
	v_fmac_f32_e32 v49, s18, v151
	global_load_dwordx4 v[148:151], v2, s[12:13] nt
	s_add_u32 s12, s12, 0x9000
	s_addc_u32 s13, s13, 0
	s_waitcnt vmcnt(31)
	v_readlane_b32 s6, v7, 19
	v_readlane_b32 s7, v8, 19
	v_readlane_b32 s18, v9, 19
	v_fmac_f32_e32 v46, s6, v152
	v_fmac_f32_e32 v47, s6, v153
	v_fmac_f32_e32 v44, s6, v154
	v_fmac_f32_e32 v45, s6, v155
	v_fmac_f32_e32 v54, s7, v152
	v_fmac_f32_e32 v55, s7, v153
	v_fmac_f32_e32 v50, s7, v154
	v_fmac_f32_e32 v51, s7, v155
	v_fmac_f32_e32 v52, s18, v152
	v_fmac_f32_e32 v53, s18, v153
	v_fmac_f32_e32 v48, s18, v154
	v_fmac_f32_e32 v49, s18, v155
	global_load_dwordx4 v[152:155], v2, s[12:13] nt
	s_add_u32 s12, s12, 0x9000
	s_addc_u32 s13, s13, 0
	s_waitcnt vmcnt(31)
	v_readlane_b32 s6, v7, 20
	v_readlane_b32 s7, v8, 20
	v_readlane_b32 s18, v9, 20
	v_fmac_f32_e32 v46, s6, v156
	v_fmac_f32_e32 v47, s6, v157
	v_fmac_f32_e32 v44, s6, v158
	v_fmac_f32_e32 v45, s6, v159
	v_fmac_f32_e32 v54, s7, v156
	v_fmac_f32_e32 v55, s7, v157
	v_fmac_f32_e32 v50, s7, v158
	v_fmac_f32_e32 v51, s7, v159
	v_fmac_f32_e32 v52, s18, v156
	v_fmac_f32_e32 v53, s18, v157
	v_fmac_f32_e32 v48, s18, v158
	v_fmac_f32_e32 v49, s18, v159
	global_load_dwordx4 v[156:159], v2, s[12:13] nt
	s_add_u32 s12, s12, 0x9000
	s_addc_u32 s13, s13, 0
	s_waitcnt vmcnt(31)
	v_readlane_b32 s6, v7, 21
	v_readlane_b32 s7, v8, 21
	v_readlane_b32 s18, v9, 21
	v_fmac_f32_e32 v46, s6, v160
	v_fmac_f32_e32 v47, s6, v161
	v_fmac_f32_e32 v44, s6, v162
	v_fmac_f32_e32 v45, s6, v163
	v_fmac_f32_e32 v54, s7, v160
	v_fmac_f32_e32 v55, s7, v161
	v_fmac_f32_e32 v50, s7, v162
	v_fmac_f32_e32 v51, s7, v163
	v_fmac_f32_e32 v52, s18, v160
	v_fmac_f32_e32 v53, s18, v161
	v_fmac_f32_e32 v48, s18, v162
	v_fmac_f32_e32 v49, s18, v163
	global_load_dwordx4 v[160:163], v2, s[12:13] nt
	s_add_u32 s12, s12, 0x9000
	s_addc_u32 s13, s13, 0
	s_waitcnt vmcnt(31)
	v_readlane_b32 s6, v7, 22
	v_readlane_b32 s7, v8, 22
	v_readlane_b32 s18, v9, 22
	v_fmac_f32_e32 v46, s6, v164
	v_fmac_f32_e32 v47, s6, v165
	v_fmac_f32_e32 v44, s6, v166
	v_fmac_f32_e32 v45, s6, v167
	v_fmac_f32_e32 v54, s7, v164
	v_fmac_f32_e32 v55, s7, v165
	v_fmac_f32_e32 v50, s7, v166
	v_fmac_f32_e32 v51, s7, v167
	v_fmac_f32_e32 v52, s18, v164
	v_fmac_f32_e32 v53, s18, v165
	v_fmac_f32_e32 v48, s18, v166
	v_fmac_f32_e32 v49, s18, v167
	global_load_dwordx4 v[164:167], v2, s[12:13] nt
	s_add_u32 s12, s12, 0x9000
	s_addc_u32 s13, s13, 0
	s_waitcnt vmcnt(31)
; __device__ __forceinline__ void prologue(const kptr_t kp, LAS float* scr, int gw, int NGW, int lane) {
;     ...
;             for (int kk = 0; kk < 64; ++kk) {
;                 const int k = ks * 64 + kk; const float x0 = c[k], x1 = c[1024 + k], x2 = cc[k];
;                 const float s0 = x0 / (1.0f + expf(-x0)), s1 = x1 / (1.0f + expf(-x1)), s2 = x2 / (1.0f + expf(-x2));
;                 const f32x4 w = *(const f32x4*)(wp + (size_t)kk * 9216);
;                 a0 += w * s0; a1 += w * s1; a2 += w * s2;
;             }
	v_readlane_b32 s6, v7, 23
	v_readlane_b32 s7, v8, 23
	v_readlane_b32 s18, v9, 23
	v_fmac_f32_e32 v46, s6, v168
	v_fmac_f32_e32 v47, s6, v169
	v_fmac_f32_e32 v44, s6, v170
	v_fmac_f32_e32 v45, s6, v171
	v_fmac_f32_e32 v54, s7, v168
	v_fmac_f32_e32 v55, s7, v169
	v_fmac_f32_e32 v50, s7, v170
	v_fmac_f32_e32 v51, s7, v171
	v_fmac_f32_e32 v52, s18, v168
	v_fmac_f32_e32 v53, s18, v169
	v_fmac_f32_e32 v48, s18, v170
	v_fmac_f32_e32 v49, s18, v171
	global_load_dwordx4 v[168:171], v2, s[12:13] nt
	s_add_u32 s12, s12, 0x9000
	s_addc_u32 s13, s13, 0
	s_waitcnt vmcnt(31)
	v_readlane_b32 s6, v7, 24
	v_readlane_b32 s7, v8, 24
	v_readlane_b32 s18, v9, 24
	v_fmac_f32_e32 v46, s6, v172
	v_fmac_f32_e32 v47, s6, v173
	v_fmac_f32_e32 v44, s6, v174
	v_fmac_f32_e32 v45, s6, v175
	v_fmac_f32_e32 v54, s7, v172
	v_fmac_f32_e32 v55, s7, v173
	v_fmac_f32_e32 v50, s7, v174
	v_fmac_f32_e32 v51, s7, v175
	v_fmac_f32_e32 v52, s18, v172
	v_fmac_f32_e32 v53, s18, v173
	v_fmac_f32_e32 v48, s18, v174
	v_fmac_f32_e32 v49, s18, v175
	global_load_dwordx4 v[172:175], v2, s[12:13] nt
	s_add_u32 s12, s12, 0x9000
	s_addc_u32 s13, s13, 0
	s_waitcnt vmcnt(31)
	v_readlane_b32 s6, v7, 25
	v_readlane_b32 s7, v8, 25
	v_readlane_b32 s18, v9, 25
	v_fmac_f32_e32 v46, s6, v176
	v_fmac_f32_e32 v47, s6, v177
	v_fmac_f32_e32 v44, s6, v178
	v_fmac_f32_e32 v45, s6, v179
	v_fmac_f32_e32 v54, s7, v176
	v_fmac_f32_e32 v55, s7, v177
	v_fmac_f32_e32 v50, s7, v178
	v_fmac_f32_e32 v51, s7, v179
	v_fmac_f32_e32 v52, s18, v176
	v_fmac_f32_e32 v53, s18, v177
	v_fmac_f32_e32 v48, s18, v178
	v_fmac_f32_e32 v49, s18, v179
	global_load_dwordx4 v[176:179], v2, s[12:13] nt
	s_add_u32 s12, s12, 0x9000
	s_addc_u32 s13, s13, 0
	s_waitcnt vmcnt(31)
	v_readlane_b32 s6, v7, 26
	v_readlane_b32 s7, v8, 26
	v_readlane_b32 s18, v9, 26
	v_fmac_f32_e32 v46, s6, v180
	v_fmac_f32_e32 v47, s6, v181
	v_fmac_f32_e32 v44, s6, v182
	v_fmac_f32_e32 v45, s6, v183
	v_fmac_f32_e32 v54, s7, v180
	v_fmac_f32_e32 v55, s7, v181
	v_fmac_f32_e32 v50, s7, v182
	v_fmac_f32_e32 v51, s7, v183
	v_fmac_f32_e32 v52, s18, v180
	v_fmac_f32_e32 v53, s18, v181
	v_fmac_f32_e32 v48, s18, v182
	v_fmac_f32_e32 v49, s18, v183
	global_load_dwordx4 v[180:183], v2, s[12:13] nt
	s_add_u32 s12, s12, 0x9000
	s_addc_u32 s13, s13, 0
	s_waitcnt vmcnt(31)
	v_readlane_b32 s6, v7, 27
	v_readlane_b32 s7, v8, 27
	v_readlane_b32 s18, v9, 27
	v_fmac_f32_e32 v46, s6, v184
	v_fmac_f32_e32 v47, s6, v185
	v_fmac_f32_e32 v44, s6, v186
	v_fmac_f32_e32 v45, s6, v187
	v_fmac_f32_e32 v54, s7, v184
	v_fmac_f32_e32 v55, s7, v185
	v_fmac_f32_e32 v50, s7, v186
	v_fmac_f32_e32 v51, s7, v187
	v_fmac_f32_e32 v52, s18, v184
	v_fmac_f32_e32 v53, s18, v185
	v_fmac_f32_e32 v48, s18, v186
	v_fmac_f32_e32 v49, s18, v187
	global_load_dwordx4 v[184:187], v2, s[12:13] nt
	s_add_u32 s12, s12, 0x9000
	s_addc_u32 s13, s13, 0
	s_waitcnt vmcnt(31)
	v_readlane_b32 s6, v7, 28
	v_readlane_b32 s7, v8, 28
	v_readlane_b32 s18, v9, 28
	v_fmac_f32_e32 v46, s6, v188
	v_fmac_f32_e32 v47, s6, v189
	v_fmac_f32_e32 v44, s6, v190
	v_fmac_f32_e32 v45, s6, v191
	v_fmac_f32_e32 v54, s7, v188
	v_fmac_f32_e32 v55, s7, v189
	v_fmac_f32_e32 v50, s7, v190
	v_fmac_f32_e32 v51, s7, v191
	v_fmac_f32_e32 v52, s18, v188
	v_fmac_f32_e32 v53, s18, v189
	v_fmac_f32_e32 v48, s18, v190
	v_fmac_f32_e32 v49, s18, v191
	global_load_dwordx4 v[188:191], v2, s[12:13] nt
	s_add_u32 s12, s12, 0x9000
	s_addc_u32 s13, s13, 0
	s_waitcnt vmcnt(31)
	v_readlane_b32 s6, v7, 29
	v_readlane_b32 s7, v8, 29
	v_readlane_b32 s18, v9, 29
	v_fmac_f32_e32 v46, s6, v192
	v_fmac_f32_e32 v47, s6, v193
	v_fmac_f32_e32 v44, s6, v194
	v_fmac_f32_e32 v45, s6, v195
	v_fmac_f32_e32 v54, s7, v192
	v_fmac_f32_e32 v55, s7, v193
	v_fmac_f32_e32 v50, s7, v194
	v_fmac_f32_e32 v51, s7, v195
	v_fmac_f32_e32 v52, s18, v192
	v_fmac_f32_e32 v53, s18, v193
	v_fmac_f32_e32 v48, s18, v194
	v_fmac_f32_e32 v49, s18, v195
	global_load_dwordx4 v[192:195], v2, s[12:13] nt
	s_add_u32 s12, s12, 0x9000
	s_addc_u32 s13, s13, 0
	s_waitcnt vmcnt(31)
	v_readlane_b32 s6, v7, 30
	v_readlane_b32 s7, v8, 30
	v_readlane_b32 s18, v9, 30
	v_fmac_f32_e32 v46, s6, v196
	v_fmac_f32_e32 v47, s6, v197
	v_fmac_f32_e32 v44, s6, v198
	v_fmac_f32_e32 v45, s6, v199
	v_fmac_f32_e32 v54, s7, v196
	v_fmac_f32_e32 v55, s7, v197
	v_fmac_f32_e32 v50, s7, v198
	v_fmac_f32_e32 v51, s7, v199
	v_fmac_f32_e32 v52, s18, v196
	v_fmac_f32_e32 v53, s18, v197
	v_fmac_f32_e32 v48, s18, v198
	v_fmac_f32_e32 v49, s18, v199
	global_load_dwordx4 v[196:199], v2, s[12:13] nt
	s_add_u32 s12, s12, 0x9000
	s_addc_u32 s13, s13, 0
	s_waitcnt vmcnt(31)
	v_readlane_b32 s6, v7, 31
	v_readlane_b32 s7, v8, 31
	v_readlane_b32 s18, v9, 31
	v_fmac_f32_e32 v46, s6, v200
	v_fmac_f32_e32 v47, s6, v201
	v_fmac_f32_e32 v44, s6, v202
	v_fmac_f32_e32 v45, s6, v203
	v_fmac_f32_e32 v54, s7, v200
	v_fmac_f32_e32 v55, s7, v201
	v_fmac_f32_e32 v50, s7, v202
	v_fmac_f32_e32 v51, s7, v203
	v_fmac_f32_e32 v52, s18, v200
	v_fmac_f32_e32 v53, s18, v201
	v_fmac_f32_e32 v48, s18, v202
	v_fmac_f32_e32 v49, s18, v203
	global_load_dwordx4 v[200:203], v2, s[12:13] nt
	s_add_u32 s12, s12, 0x9000
	s_addc_u32 s13, s13, 0
	s_waitcnt vmcnt(31)
	v_readlane_b32 s6, v7, 32
	v_readlane_b32 s7, v8, 32
	v_readlane_b32 s18, v9, 32
	v_fmac_f32_e32 v46, s6, v76
	v_fmac_f32_e32 v47, s6, v77
	v_fmac_f32_e32 v44, s6, v78
	v_fmac_f32_e32 v45, s6, v79
	v_fmac_f32_e32 v54, s7, v76
	v_fmac_f32_e32 v55, s7, v77
	v_fmac_f32_e32 v50, s7, v78
	v_fmac_f32_e32 v51, s7, v79
	v_fmac_f32_e32 v52, s18, v76
	v_fmac_f32_e32 v53, s18, v77
	v_fmac_f32_e32 v48, s18, v78
	v_fmac_f32_e32 v49, s18, v79
	s_waitcnt vmcnt(30)
; __device__ __forceinline__ void prologue(const kptr_t kp, LAS float* scr, int gw, int NGW, int lane) {
;     ...
;             for (int kk = 0; kk < 64; ++kk) {
;                 const int k = ks * 64 + kk; const float x0 = c[k], x1 = c[1024 + k], x2 = cc[k];
;                 const float s0 = x0 / (1.0f + expf(-x0)), s1 = x1 / (1.0f + expf(-x1)), s2 = x2 / (1.0f + expf(-x2));
;                 const f32x4 w = *(const f32x4*)(wp + (size_t)kk * 9216);
;                 a0 += w * s0; a1 += w * s1; a2 += w * s2;
;             }
	v_readlane_b32 s6, v7, 33
	v_readlane_b32 s7, v8, 33
	v_readlane_b32 s18, v9, 33
	v_fmac_f32_e32 v46, s6, v80
	v_fmac_f32_e32 v47, s6, v81
	v_fmac_f32_e32 v44, s6, v82
	v_fmac_f32_e32 v45, s6, v83
	v_fmac_f32_e32 v54, s7, v80
	v_fmac_f32_e32 v55, s7, v81
	v_fmac_f32_e32 v50, s7, v82
	v_fmac_f32_e32 v51, s7, v83
	v_fmac_f32_e32 v52, s18, v80
	v_fmac_f32_e32 v53, s18, v81
	v_fmac_f32_e32 v48, s18, v82
	v_fmac_f32_e32 v49, s18, v83
	s_waitcnt vmcnt(29)
	v_readlane_b32 s6, v7, 34
	v_readlane_b32 s7, v8, 34
	v_readlane_b32 s18, v9, 34
	v_fmac_f32_e32 v46, s6, v84
	v_fmac_f32_e32 v47, s6, v85
	v_fmac_f32_e32 v44, s6, v86
	v_fmac_f32_e32 v45, s6, v87
	v_fmac_f32_e32 v54, s7, v84
	v_fmac_f32_e32 v55, s7, v85
	v_fmac_f32_e32 v50, s7, v86
	v_fmac_f32_e32 v51, s7, v87
	v_fmac_f32_e32 v52, s18, v84
	v_fmac_f32_e32 v53, s18, v85
	v_fmac_f32_e32 v48, s18, v86
	v_fmac_f32_e32 v49, s18, v87
	s_waitcnt vmcnt(28)
	v_readlane_b32 s6, v7, 35
	v_readlane_b32 s7, v8, 35
	v_readlane_b32 s18, v9, 35
	v_fmac_f32_e32 v46, s6, v88
	v_fmac_f32_e32 v47, s6, v89
	v_fmac_f32_e32 v44, s6, v90
	v_fmac_f32_e32 v45, s6, v91
	v_fmac_f32_e32 v54, s7, v88
	v_fmac_f32_e32 v55, s7, v89
	v_fmac_f32_e32 v50, s7, v90
	v_fmac_f32_e32 v51, s7, v91
	v_fmac_f32_e32 v52, s18, v88
	v_fmac_f32_e32 v53, s18, v89
	v_fmac_f32_e32 v48, s18, v90
	v_fmac_f32_e32 v49, s18, v91
	s_waitcnt vmcnt(27)
	v_readlane_b32 s6, v7, 36
	v_readlane_b32 s7, v8, 36
	v_readlane_b32 s18, v9, 36
	v_fmac_f32_e32 v46, s6, v92
	v_fmac_f32_e32 v47, s6, v93
	v_fmac_f32_e32 v44, s6, v94
	v_fmac_f32_e32 v45, s6, v95
	v_fmac_f32_e32 v54, s7, v92
	v_fmac_f32_e32 v55, s7, v93
	v_fmac_f32_e32 v50, s7, v94
	v_fmac_f32_e32 v51, s7, v95
	v_fmac_f32_e32 v52, s18, v92
	v_fmac_f32_e32 v53, s18, v93
	v_fmac_f32_e32 v48, s18, v94
	v_fmac_f32_e32 v49, s18, v95
	s_waitcnt vmcnt(26)
	v_readlane_b32 s6, v7, 37
	v_readlane_b32 s7, v8, 37
	v_readlane_b32 s18, v9, 37
	v_fmac_f32_e32 v46, s6, v96
	v_fmac_f32_e32 v47, s6, v97
	v_fmac_f32_e32 v44, s6, v98
	v_fmac_f32_e32 v45, s6, v99
	v_fmac_f32_e32 v54, s7, v96
	v_fmac_f32_e32 v55, s7, v97
	v_fmac_f32_e32 v50, s7, v98
	v_fmac_f32_e32 v51, s7, v99
	v_fmac_f32_e32 v52, s18, v96
	v_fmac_f32_e32 v53, s18, v97
	v_fmac_f32_e32 v48, s18, v98
	v_fmac_f32_e32 v49, s18, v99
	s_waitcnt vmcnt(25)
	v_readlane_b32 s6, v7, 38
	v_readlane_b32 s7, v8, 38
	v_readlane_b32 s18, v9, 38
	v_fmac_f32_e32 v46, s6, v100
	v_fmac_f32_e32 v47, s6, v101
	v_fmac_f32_e32 v44, s6, v102
	v_fmac_f32_e32 v45, s6, v103
	v_fmac_f32_e32 v54, s7, v100
	v_fmac_f32_e32 v55, s7, v101
	v_fmac_f32_e32 v50, s7, v102
	v_fmac_f32_e32 v51, s7, v103
	v_fmac_f32_e32 v52, s18, v100
	v_fmac_f32_e32 v53, s18, v101
	v_fmac_f32_e32 v48, s18, v102
	v_fmac_f32_e32 v49, s18, v103
	s_waitcnt vmcnt(24)
	v_readlane_b32 s6, v7, 39
	v_readlane_b32 s7, v8, 39
	v_readlane_b32 s18, v9, 39
	v_fmac_f32_e32 v46, s6, v104
	v_fmac_f32_e32 v47, s6, v105
	v_fmac_f32_e32 v44, s6, v106
	v_fmac_f32_e32 v45, s6, v107
	v_fmac_f32_e32 v54, s7, v104
	v_fmac_f32_e32 v55, s7, v105
	v_fmac_f32_e32 v50, s7, v106
	v_fmac_f32_e32 v51, s7, v107
	v_fmac_f32_e32 v52, s18, v104
	v_fmac_f32_e32 v53, s18, v105
	v_fmac_f32_e32 v48, s18, v106
	v_fmac_f32_e32 v49, s18, v107
	s_waitcnt vmcnt(23)
	v_readlane_b32 s6, v7, 40
	v_readlane_b32 s7, v8, 40
	v_readlane_b32 s18, v9, 40
	v_fmac_f32_e32 v46, s6, v108
	v_fmac_f32_e32 v47, s6, v109
	v_fmac_f32_e32 v44, s6, v110
	v_fmac_f32_e32 v45, s6, v111
	v_fmac_f32_e32 v54, s7, v108
	v_fmac_f32_e32 v55, s7, v109
	v_fmac_f32_e32 v50, s7, v110
	v_fmac_f32_e32 v51, s7, v111
	v_fmac_f32_e32 v52, s18, v108
	v_fmac_f32_e32 v53, s18, v109
	v_fmac_f32_e32 v48, s18, v110
	v_fmac_f32_e32 v49, s18, v111
	s_waitcnt vmcnt(22)
	v_readlane_b32 s6, v7, 41
	v_readlane_b32 s7, v8, 41
	v_readlane_b32 s18, v9, 41
	v_fmac_f32_e32 v46, s6, v112
	v_fmac_f32_e32 v47, s6, v113
	v_fmac_f32_e32 v44, s6, v114
	v_fmac_f32_e32 v45, s6, v115
	v_fmac_f32_e32 v54, s7, v112
	v_fmac_f32_e32 v55, s7, v113
	v_fmac_f32_e32 v50, s7, v114
	v_fmac_f32_e32 v51, s7, v115
	v_fmac_f32_e32 v52, s18, v112
	v_fmac_f32_e32 v53, s18, v113
	v_fmac_f32_e32 v48, s18, v114
	v_fmac_f32_e32 v49, s18, v115
	s_waitcnt vmcnt(21)
	v_readlane_b32 s6, v7, 42
	v_readlane_b32 s7, v8, 42
	v_readlane_b32 s18, v9, 42
	v_fmac_f32_e32 v46, s6, v116
	v_fmac_f32_e32 v47, s6, v117
	v_fmac_f32_e32 v44, s6, v118
	v_fmac_f32_e32 v45, s6, v119
	v_fmac_f32_e32 v54, s7, v116
	v_fmac_f32_e32 v55, s7, v117
	v_fmac_f32_e32 v50, s7, v118
	v_fmac_f32_e32 v51, s7, v119
	v_fmac_f32_e32 v52, s18, v116
	v_fmac_f32_e32 v53, s18, v117
	v_fmac_f32_e32 v48, s18, v118
	v_fmac_f32_e32 v49, s18, v119
	s_waitcnt vmcnt(20)
	v_readlane_b32 s6, v7, 43
	v_readlane_b32 s7, v8, 43
	v_readlane_b32 s18, v9, 43
	v_fmac_f32_e32 v46, s6, v120
	v_fmac_f32_e32 v47, s6, v121
	v_fmac_f32_e32 v44, s6, v122
	v_fmac_f32_e32 v45, s6, v123
	v_fmac_f32_e32 v54, s7, v120
	v_fmac_f32_e32 v55, s7, v121
	v_fmac_f32_e32 v50, s7, v122
	v_fmac_f32_e32 v51, s7, v123
	v_fmac_f32_e32 v52, s18, v120
	v_fmac_f32_e32 v53, s18, v121
	v_fmac_f32_e32 v48, s18, v122
	v_fmac_f32_e32 v49, s18, v123
	s_waitcnt vmcnt(19)
	v_readlane_b32 s6, v7, 44
	v_readlane_b32 s7, v8, 44
	v_readlane_b32 s18, v9, 44
	v_fmac_f32_e32 v46, s6, v124
	v_fmac_f32_e32 v47, s6, v125
	v_fmac_f32_e32 v44, s6, v126
	v_fmac_f32_e32 v45, s6, v127
	v_fmac_f32_e32 v54, s7, v124
	v_fmac_f32_e32 v55, s7, v125
	v_fmac_f32_e32 v50, s7, v126
	v_fmac_f32_e32 v51, s7, v127
	v_fmac_f32_e32 v52, s18, v124
	v_fmac_f32_e32 v53, s18, v125
	v_fmac_f32_e32 v48, s18, v126
	v_fmac_f32_e32 v49, s18, v127
	s_waitcnt vmcnt(18)
; __device__ __forceinline__ void prologue(const kptr_t kp, LAS float* scr, int gw, int NGW, int lane) {
;     ...
;             for (int kk = 0; kk < 64; ++kk) {
;                 const int k = ks * 64 + kk; const float x0 = c[k], x1 = c[1024 + k], x2 = cc[k];
;                 const float s0 = x0 / (1.0f + expf(-x0)), s1 = x1 / (1.0f + expf(-x1)), s2 = x2 / (1.0f + expf(-x2));
;                 const f32x4 w = *(const f32x4*)(wp + (size_t)kk * 9216);
;                 a0 += w * s0; a1 += w * s1; a2 += w * s2;
;             }
	v_readlane_b32 s6, v7, 45
	v_readlane_b32 s7, v8, 45
	v_readlane_b32 s18, v9, 45
	v_fmac_f32_e32 v46, s6, v128
	v_fmac_f32_e32 v47, s6, v129
	v_fmac_f32_e32 v44, s6, v130
	v_fmac_f32_e32 v45, s6, v131
	v_fmac_f32_e32 v54, s7, v128
	v_fmac_f32_e32 v55, s7, v129
	v_fmac_f32_e32 v50, s7, v130
	v_fmac_f32_e32 v51, s7, v131
	v_fmac_f32_e32 v52, s18, v128
	v_fmac_f32_e32 v53, s18, v129
	v_fmac_f32_e32 v48, s18, v130
	v_fmac_f32_e32 v49, s18, v131
	s_waitcnt vmcnt(17)
	v_readlane_b32 s6, v7, 46
	v_readlane_b32 s7, v8, 46
	v_readlane_b32 s18, v9, 46
	v_fmac_f32_e32 v46, s6, v132
	v_fmac_f32_e32 v47, s6, v133
	v_fmac_f32_e32 v44, s6, v134
	v_fmac_f32_e32 v45, s6, v135
	v_fmac_f32_e32 v54, s7, v132
	v_fmac_f32_e32 v55, s7, v133
	v_fmac_f32_e32 v50, s7, v134
	v_fmac_f32_e32 v51, s7, v135
	v_fmac_f32_e32 v52, s18, v132
	v_fmac_f32_e32 v53, s18, v133
	v_fmac_f32_e32 v48, s18, v134
	v_fmac_f32_e32 v49, s18, v135
	s_waitcnt vmcnt(16)
	v_readlane_b32 s6, v7, 47
	v_readlane_b32 s7, v8, 47
	v_readlane_b32 s18, v9, 47
	v_fmac_f32_e32 v46, s6, v136
	v_fmac_f32_e32 v47, s6, v137
	v_fmac_f32_e32 v44, s6, v138
	v_fmac_f32_e32 v45, s6, v139
	v_fmac_f32_e32 v54, s7, v136
	v_fmac_f32_e32 v55, s7, v137
	v_fmac_f32_e32 v50, s7, v138
	v_fmac_f32_e32 v51, s7, v139
	v_fmac_f32_e32 v52, s18, v136
	v_fmac_f32_e32 v53, s18, v137
	v_fmac_f32_e32 v48, s18, v138
	v_fmac_f32_e32 v49, s18, v139
	s_waitcnt vmcnt(15)
	v_readlane_b32 s6, v7, 48
	v_readlane_b32 s7, v8, 48
	v_readlane_b32 s18, v9, 48
	v_fmac_f32_e32 v46, s6, v140
	v_fmac_f32_e32 v47, s6, v141
	v_fmac_f32_e32 v44, s6, v142
	v_fmac_f32_e32 v45, s6, v143
	v_fmac_f32_e32 v54, s7, v140
	v_fmac_f32_e32 v55, s7, v141
	v_fmac_f32_e32 v50, s7, v142
	v_fmac_f32_e32 v51, s7, v143
	v_fmac_f32_e32 v52, s18, v140
	v_fmac_f32_e32 v53, s18, v141
	v_fmac_f32_e32 v48, s18, v142
	v_fmac_f32_e32 v49, s18, v143
	s_waitcnt vmcnt(14)
	v_readlane_b32 s6, v7, 49
	v_readlane_b32 s7, v8, 49
	v_readlane_b32 s18, v9, 49
	v_fmac_f32_e32 v46, s6, v144
	v_fmac_f32_e32 v47, s6, v145
	v_fmac_f32_e32 v44, s6, v146
	v_fmac_f32_e32 v45, s6, v147
	v_fmac_f32_e32 v54, s7, v144
	v_fmac_f32_e32 v55, s7, v145
	v_fmac_f32_e32 v50, s7, v146
	v_fmac_f32_e32 v51, s7, v147
	v_fmac_f32_e32 v52, s18, v144
	v_fmac_f32_e32 v53, s18, v145
	v_fmac_f32_e32 v48, s18, v146
	v_fmac_f32_e32 v49, s18, v147
	s_waitcnt vmcnt(13)
	v_readlane_b32 s6, v7, 50
	v_readlane_b32 s7, v8, 50
	v_readlane_b32 s18, v9, 50
	v_fmac_f32_e32 v46, s6, v148
	v_fmac_f32_e32 v47, s6, v149
	v_fmac_f32_e32 v44, s6, v150
	v_fmac_f32_e32 v45, s6, v151
	v_fmac_f32_e32 v54, s7, v148
	v_fmac_f32_e32 v55, s7, v149
	v_fmac_f32_e32 v50, s7, v150
	v_fmac_f32_e32 v51, s7, v151
	v_fmac_f32_e32 v52, s18, v148
	v_fmac_f32_e32 v53, s18, v149
	v_fmac_f32_e32 v48, s18, v150
	v_fmac_f32_e32 v49, s18, v151
	s_waitcnt vmcnt(12)
	v_readlane_b32 s6, v7, 51
	v_readlane_b32 s7, v8, 51
	v_readlane_b32 s18, v9, 51
	v_fmac_f32_e32 v46, s6, v152
	v_fmac_f32_e32 v47, s6, v153
	v_fmac_f32_e32 v44, s6, v154
	v_fmac_f32_e32 v45, s6, v155
	v_fmac_f32_e32 v54, s7, v152
	v_fmac_f32_e32 v55, s7, v153
	v_fmac_f32_e32 v50, s7, v154
	v_fmac_f32_e32 v51, s7, v155
	v_fmac_f32_e32 v52, s18, v152
	v_fmac_f32_e32 v53, s18, v153
	v_fmac_f32_e32 v48, s18, v154
	v_fmac_f32_e32 v49, s18, v155
	s_waitcnt vmcnt(11)
	v_readlane_b32 s6, v7, 52
	v_readlane_b32 s7, v8, 52
	v_readlane_b32 s18, v9, 52
	v_fmac_f32_e32 v46, s6, v156
	v_fmac_f32_e32 v47, s6, v157
	v_fmac_f32_e32 v44, s6, v158
	v_fmac_f32_e32 v45, s6, v159
	v_fmac_f32_e32 v54, s7, v156
	v_fmac_f32_e32 v55, s7, v157
	v_fmac_f32_e32 v50, s7, v158
	v_fmac_f32_e32 v51, s7, v159
	v_fmac_f32_e32 v52, s18, v156
	v_fmac_f32_e32 v53, s18, v157
	v_fmac_f32_e32 v48, s18, v158
	v_fmac_f32_e32 v49, s18, v159
	s_waitcnt vmcnt(10)
	v_readlane_b32 s6, v7, 53
	v_readlane_b32 s7, v8, 53
	v_readlane_b32 s18, v9, 53
	v_fmac_f32_e32 v46, s6, v160
	v_fmac_f32_e32 v47, s6, v161
	v_fmac_f32_e32 v44, s6, v162
	v_fmac_f32_e32 v45, s6, v163
	v_fmac_f32_e32 v54, s7, v160
	v_fmac_f32_e32 v55, s7, v161
	v_fmac_f32_e32 v50, s7, v162
	v_fmac_f32_e32 v51, s7, v163
	v_fmac_f32_e32 v52, s18, v160
	v_fmac_f32_e32 v53, s18, v161
	v_fmac_f32_e32 v48, s18, v162
	v_fmac_f32_e32 v49, s18, v163
	s_waitcnt vmcnt(9)
	v_readlane_b32 s6, v7, 54
	v_readlane_b32 s7, v8, 54
	v_readlane_b32 s18, v9, 54
	v_fmac_f32_e32 v46, s6, v164
	v_fmac_f32_e32 v47, s6, v165
	v_fmac_f32_e32 v44, s6, v166
	v_fmac_f32_e32 v45, s6, v167
	v_fmac_f32_e32 v54, s7, v164
	v_fmac_f32_e32 v55, s7, v165
	v_fmac_f32_e32 v50, s7, v166
	v_fmac_f32_e32 v51, s7, v167
	v_fmac_f32_e32 v52, s18, v164
	v_fmac_f32_e32 v53, s18, v165
	v_fmac_f32_e32 v48, s18, v166
	v_fmac_f32_e32 v49, s18, v167
	s_waitcnt vmcnt(8)
; __device__ __forceinline__ void prologue(const kptr_t kp, LAS float* scr, int gw, int NGW, int lane) {
;     ...
;             for (int kk = 0; kk < 64; ++kk) {
;                 const int k = ks * 64 + kk; const float x0 = c[k], x1 = c[1024 + k], x2 = cc[k];
;                 const float s0 = x0 / (1.0f + expf(-x0)), s1 = x1 / (1.0f + expf(-x1)), s2 = x2 / (1.0f + expf(-x2));
;                 const f32x4 w = *(const f32x4*)(wp + (size_t)kk * 9216);
;                 a0 += w * s0; a1 += w * s1; a2 += w * s2;
;             }
;             if (ks == 0) { const f32x4 b = *(const f32x4*)(KPTR(const float, 5) + l * 9216 + j0); a0 += b; a1 += b; a2 += b; }
	v_readlane_b32 s6, v7, 55
	v_readlane_b32 s7, v8, 55
	v_readlane_b32 s18, v9, 55
	v_fmac_f32_e32 v46, s6, v168
	v_fmac_f32_e32 v47, s6, v169
	v_fmac_f32_e32 v44, s6, v170
	v_fmac_f32_e32 v45, s6, v171
	v_fmac_f32_e32 v54, s7, v168
	v_fmac_f32_e32 v55, s7, v169
	v_fmac_f32_e32 v50, s7, v170
	v_fmac_f32_e32 v51, s7, v171
	v_fmac_f32_e32 v52, s18, v168
	v_fmac_f32_e32 v53, s18, v169
	v_fmac_f32_e32 v48, s18, v170
	v_fmac_f32_e32 v49, s18, v171
	s_waitcnt vmcnt(7)
	v_readlane_b32 s6, v7, 56
	v_readlane_b32 s7, v8, 56
	v_readlane_b32 s18, v9, 56
	v_fmac_f32_e32 v46, s6, v172
	v_fmac_f32_e32 v47, s6, v173
	v_fmac_f32_e32 v44, s6, v174
	v_fmac_f32_e32 v45, s6, v175
	v_fmac_f32_e32 v54, s7, v172
	v_fmac_f32_e32 v55, s7, v173
	v_fmac_f32_e32 v50, s7, v174
	v_fmac_f32_e32 v51, s7, v175
	v_fmac_f32_e32 v52, s18, v172
	v_fmac_f32_e32 v53, s18, v173
	v_fmac_f32_e32 v48, s18, v174
	v_fmac_f32_e32 v49, s18, v175
	s_waitcnt vmcnt(6)
	v_readlane_b32 s6, v7, 57
	v_readlane_b32 s7, v8, 57
	v_readlane_b32 s18, v9, 57
	v_fmac_f32_e32 v46, s6, v176
	v_fmac_f32_e32 v47, s6, v177
	v_fmac_f32_e32 v44, s6, v178
	v_fmac_f32_e32 v45, s6, v179
	v_fmac_f32_e32 v54, s7, v176
	v_fmac_f32_e32 v55, s7, v177
	v_fmac_f32_e32 v50, s7, v178
	v_fmac_f32_e32 v51, s7, v179
	v_fmac_f32_e32 v52, s18, v176
	v_fmac_f32_e32 v53, s18, v177
	v_fmac_f32_e32 v48, s18, v178
	v_fmac_f32_e32 v49, s18, v179
	s_waitcnt vmcnt(5)
	v_readlane_b32 s6, v7, 58
	v_readlane_b32 s7, v8, 58
	v_readlane_b32 s18, v9, 58
	v_fmac_f32_e32 v46, s6, v180
	v_fmac_f32_e32 v47, s6, v181
	v_fmac_f32_e32 v44, s6, v182
	v_fmac_f32_e32 v45, s6, v183
	v_fmac_f32_e32 v54, s7, v180
	v_fmac_f32_e32 v55, s7, v181
	v_fmac_f32_e32 v50, s7, v182
	v_fmac_f32_e32 v51, s7, v183
	v_fmac_f32_e32 v52, s18, v180
	v_fmac_f32_e32 v53, s18, v181
	v_fmac_f32_e32 v48, s18, v182
	v_fmac_f32_e32 v49, s18, v183
	s_waitcnt vmcnt(4)
	v_readlane_b32 s6, v7, 59
	v_readlane_b32 s7, v8, 59
	v_readlane_b32 s18, v9, 59
	v_fmac_f32_e32 v46, s6, v184
	v_fmac_f32_e32 v47, s6, v185
	v_fmac_f32_e32 v44, s6, v186
	v_fmac_f32_e32 v45, s6, v187
	v_fmac_f32_e32 v54, s7, v184
	v_fmac_f32_e32 v55, s7, v185
	v_fmac_f32_e32 v50, s7, v186
	v_fmac_f32_e32 v51, s7, v187
	v_fmac_f32_e32 v52, s18, v184
	v_fmac_f32_e32 v53, s18, v185
	v_fmac_f32_e32 v48, s18, v186
	v_fmac_f32_e32 v49, s18, v187
	s_waitcnt vmcnt(3)
	v_readlane_b32 s6, v7, 60
	v_readlane_b32 s7, v8, 60
	v_readlane_b32 s18, v9, 60
	v_fmac_f32_e32 v46, s6, v188
	v_fmac_f32_e32 v47, s6, v189
	v_fmac_f32_e32 v44, s6, v190
	v_fmac_f32_e32 v45, s6, v191
	v_fmac_f32_e32 v54, s7, v188
	v_fmac_f32_e32 v55, s7, v189
	v_fmac_f32_e32 v50, s7, v190
	v_fmac_f32_e32 v51, s7, v191
	v_fmac_f32_e32 v52, s18, v188
	v_fmac_f32_e32 v53, s18, v189
	v_fmac_f32_e32 v48, s18, v190
	v_fmac_f32_e32 v49, s18, v191
	s_waitcnt vmcnt(2)
	v_readlane_b32 s6, v7, 61
	v_readlane_b32 s7, v8, 61
	v_readlane_b32 s18, v9, 61
	v_fmac_f32_e32 v46, s6, v192
	v_fmac_f32_e32 v47, s6, v193
	v_fmac_f32_e32 v44, s6, v194
	v_fmac_f32_e32 v45, s6, v195
	v_fmac_f32_e32 v54, s7, v192
	v_fmac_f32_e32 v55, s7, v193
	v_fmac_f32_e32 v50, s7, v194
	v_fmac_f32_e32 v51, s7, v195
	v_fmac_f32_e32 v52, s18, v192
	v_fmac_f32_e32 v53, s18, v193
	v_fmac_f32_e32 v48, s18, v194
	v_fmac_f32_e32 v49, s18, v195
	s_waitcnt vmcnt(1)
	v_readlane_b32 s6, v7, 62
	v_readlane_b32 s7, v8, 62
	v_readlane_b32 s18, v9, 62
	v_fmac_f32_e32 v46, s6, v196
	v_fmac_f32_e32 v47, s6, v197
	v_fmac_f32_e32 v44, s6, v198
	v_fmac_f32_e32 v45, s6, v199
	v_fmac_f32_e32 v54, s7, v196
	v_fmac_f32_e32 v55, s7, v197
	v_fmac_f32_e32 v50, s7, v198
	v_fmac_f32_e32 v51, s7, v199
	v_fmac_f32_e32 v52, s18, v196
	v_fmac_f32_e32 v53, s18, v197
	v_fmac_f32_e32 v48, s18, v198
	v_fmac_f32_e32 v49, s18, v199
	s_waitcnt vmcnt(0)
	v_readlane_b32 s6, v7, 63
	v_readlane_b32 s7, v8, 63
	v_readlane_b32 s18, v9, 63
	v_fmac_f32_e32 v46, s6, v200
	v_fmac_f32_e32 v47, s6, v201
	v_fmac_f32_e32 v44, s6, v202
	v_fmac_f32_e32 v45, s6, v203
	v_fmac_f32_e32 v54, s7, v200
	v_fmac_f32_e32 v55, s7, v201
	v_fmac_f32_e32 v50, s7, v202
	v_fmac_f32_e32 v51, s7, v203
	v_fmac_f32_e32 v52, s18, v200
	v_fmac_f32_e32 v53, s18, v201
	v_fmac_f32_e32 v48, s18, v202
	v_fmac_f32_e32 v49, s18, v203
	s_movk_i32 s64, 0x100
	s_mov_b32 s65, 0
	s_and_b32 s4, 0xffff, s82
	s_cmp_eq_u32 s4, 0
	s_cbranch_scc0 .LBB0_7
	s_load_dwordx2 s[4:5], s[36:37], 0x28
	s_mul_i32 s6, s40, 0x2400
	s_ashr_i32 s7, s6, 31
	s_lshl_b64 s[6:7], s[6:7], 2
	s_waitcnt lgkmcnt(0)
	s_add_u32 s4, s4, s6
	s_addc_u32 s5, s5, s7
	v_lshl_add_u64 v[2:3], v[42:43], 2, s[4:5]
	global_load_dwordx4 v[2:5], v[2:3], off
	s_waitcnt vmcnt(0)
	v_pk_add_f32 v[44:45], v[44:45], v[4:5]
	v_pk_add_f32 v[46:47], v[46:47], v[2:3]
	v_pk_add_f32 v[50:51], v[50:51], v[4:5]
	v_pk_add_f32 v[54:55], v[54:55], v[2:3]
	v_pk_add_f32 v[48:49], v[48:49], v[4:5]
	v_pk_add_f32 v[52:53], v[52:53], v[2:3]
	s_branch .LBB0_7
